# trailing s_barrier issued right after the last MFMA, s_setprio 0 moved below it (MFMA wave arrives one slot earlier)
# speedup vs baseline: 1.0120x; 1.0120x over previous
; #define PG8_STAGE(bufoff, gbase, voff) do { _Pragma("unroll") for (int _i = 0; _i < 2; ++_i) \
;         __builtin_amdgcn_global_load_lds((const unsigned*)((const char*)(gbase) + (voff)[_i]), (PG8_LAS unsigned*)(lds + (bufoff) + ldsw + _i * 8192), 16, 0, 0); } while (0)
; #define PG8_LDA(dst, b, h) do { _Pragma("unroll") for (int m = 0; m < 4; ++m) _Pragma("unroll") for (int k = 0; k < 2; ++k) dst[m][k] = *(const PG8_LAS bf16x8*)(lds + PG8_SA(b, h) + aoff + m * 2048 + k * 1024); } while (0)
; #define PG8_MMA(ai, bj, At, Bt) do { __builtin_amdgcn_s_setprio(3); _Pragma("unroll") for (int m = 0; m < 4; ++m) _Pragma("unroll") for (int n = 0; n < 2; ++n) _Pragma("unroll") for (int k = 0; k < 2; ++k) \
;         acc[ai][bj][m][n] = __builtin_amdgcn_mfma_f32_16x16x32_bf16(Bt[n][k], At[m][k], acc[ai][bj][m][n], 0, 0, 0); __builtin_amdgcn_s_setprio(0); } while (0)
; #define PG8_WAIT_V(n) asm volatile("s_waitcnt vmcnt(" #n ")" ::: "memory")
; #define PG8_WAIT_L(n) asm volatile("s_waitcnt lgkmcnt(" #n ")" ::: "memory")
; #define PG8_BAR __builtin_amdgcn_s_barrier()
; #define PG8_SCHED __builtin_amdgcn_sched_barrier(0)
; template <class Epi, class Sched, bool ALIGN_EPI = false, bool SP2 = false>
; __device__ __forceinline__ void gemm_phase(PG8_LAS unsigned char* lds, const Gemm g, const Sched& S, const Epi& E) {
;     ...
;             PG8_WAIT_V(8); PG8_WAIT_L(0); PG8_BAR; PG8_MMA(0, 0, At, B0); PG8_MMA(0, 1, At, B1); PG8_BAR; PG8_SCHED;
;             PG8_LDA(At, 0, 1); PG8_STAGE(PG8_SB(0, 0), b2, voffB); PG8_STAGE(PG8_SB(0, 1), b2 + hstepB, voffB); PG8_STAGE(PG8_SA(0, 0), a2, voffA);
;             PG8_WAIT_V(8); PG8_WAIT_L(0); PG8_BAR; PG8_MMA(1, 0, At, B0); PG8_MMA(1, 1, At, B1); PG8_BAR; PG8_SCHED;
.Lengw1_e:
	s_waitcnt lgkmcnt(0)
	s_barrier
	s_setprio 3
	v_mfma_f32_16x16x32_bf16 v[126:129], v[130:133], v[192:195], v[126:129]
	v_mfma_f32_16x16x32_bf16 v[126:129], v[134:137], v[196:199], v[126:129]
	v_mfma_f32_16x16x32_bf16 v[118:121], v[156:159], v[192:195], v[118:121]
	v_mfma_f32_16x16x32_bf16 v[118:121], v[172:175], v[196:199], v[118:121]
	v_mfma_f32_16x16x32_bf16 v[102:105], v[156:159], v[200:203], v[102:105]
	v_mfma_f32_16x16x32_bf16 v[102:105], v[172:175], v[204:207], v[102:105]
	v_mfma_f32_16x16x32_bf16 v[110:113], v[130:133], v[200:203], v[110:113]
	v_mfma_f32_16x16x32_bf16 v[110:113], v[134:137], v[204:207], v[110:113]
	v_mfma_f32_16x16x32_bf16 v[94:97], v[130:133], v[208:211], v[94:97]
	v_mfma_f32_16x16x32_bf16 v[94:97], v[134:137], v[212:215], v[94:97]
	v_mfma_f32_16x16x32_bf16 v[86:89], v[156:159], v[208:211], v[86:89]
	v_mfma_f32_16x16x32_bf16 v[86:89], v[172:175], v[212:215], v[86:89]
	v_mfma_f32_16x16x32_bf16 v[70:73], v[156:159], v[216:219], v[70:73]
	v_mfma_f32_16x16x32_bf16 v[70:73], v[172:175], v[220:223], v[70:73]
	v_mfma_f32_16x16x32_bf16 v[78:81], v[130:133], v[216:219], v[78:81]
	v_mfma_f32_16x16x32_bf16 v[78:81], v[134:137], v[220:223], v[78:81]
	v_mfma_f32_16x16x32_bf16 v[122:125], v[176:179], v[192:195], v[122:125]
	v_mfma_f32_16x16x32_bf16 v[122:125], v[180:183], v[196:199], v[122:125]
	v_mfma_f32_16x16x32_bf16 v[114:117], v[184:187], v[192:195], v[114:117]
	v_mfma_f32_16x16x32_bf16 v[114:117], v[188:191], v[196:199], v[114:117]
	v_mfma_f32_16x16x32_bf16 v[98:101], v[184:187], v[200:203], v[98:101]
	v_mfma_f32_16x16x32_bf16 v[98:101], v[188:191], v[204:207], v[98:101]
	v_mfma_f32_16x16x32_bf16 v[106:109], v[176:179], v[200:203], v[106:109]
	v_mfma_f32_16x16x32_bf16 v[106:109], v[180:183], v[204:207], v[106:109]
	v_mfma_f32_16x16x32_bf16 v[90:93], v[176:179], v[208:211], v[90:93]
	v_mfma_f32_16x16x32_bf16 v[90:93], v[180:183], v[212:215], v[90:93]
	v_mfma_f32_16x16x32_bf16 v[82:85], v[184:187], v[208:211], v[82:85]
	v_mfma_f32_16x16x32_bf16 v[82:85], v[188:191], v[212:215], v[82:85]
	v_mfma_f32_16x16x32_bf16 v[66:69], v[184:187], v[216:219], v[66:69]
	v_mfma_f32_16x16x32_bf16 v[66:69], v[188:191], v[220:223], v[66:69]
	v_mfma_f32_16x16x32_bf16 v[74:77], v[176:179], v[216:219], v[74:77]
	v_mfma_f32_16x16x32_bf16 v[74:77], v[180:183], v[220:223], v[74:77]
	s_barrier
	s_setprio 0
	s_add_i32 s56, s83, s66
	v_lshl_add_u64 v[160:161], s[8:9], 0, v[140:141]
	s_mov_b32 m0, s56
	ds_read_b128 v[192:195], v169 offset:16384
	ds_read_b128 v[196:199], v169 offset:17408
	ds_read_b128 v[200:203], v169 offset:18432
	ds_read_b128 v[204:207], v169 offset:19456
	ds_read_b128 v[208:211], v169 offset:20480
	ds_read_b128 v[212:215], v169 offset:21504
	ds_read_b128 v[216:219], v169 offset:22528
	ds_read_b128 v[220:223], v169 offset:23552
	global_load_lds_dwordx4 v[160:161], off
	s_add_i32 m0, s56, 0x2000
	s_add_u32 s56, s8, 0x100000
	v_lshl_add_u64 v[224:225], s[8:9], 0, v[144:145]
	s_addc_u32 s57, s9, 0
	s_add_i32 s58, s89, s66
	global_load_lds_dwordx4 v[224:225], off
	v_lshl_add_u64 v[226:227], s[56:57], 0, v[140:141]
	s_mov_b32 m0, s58
	v_lshl_add_u64 v[228:229], s[36:37], 0, v[142:143]
	global_load_lds_dwordx4 v[226:227], off
	v_lshl_add_u64 v[226:227], s[56:57], 0, v[144:145]
	s_add_i32 m0, s58, 0x2000
	s_nop 0
	global_load_lds_dwordx4 v[226:227], off
	v_lshl_add_u64 v[226:227], s[36:37], 0, v[138:139]
	s_mov_b32 m0, s55
	s_nop 0
	global_load_lds_dwordx4 v[226:227], off
	s_mov_b32 m0, s67
	s_nop 0
	global_load_lds_dwordx4 v[228:229], off
	s_cmp_eq_u32 s97, 0
	s_cbranch_scc1 .Lengw2_a
	s_cmp_eq_u32 s97, 2
	s_cbranch_scc1 .Lengw2_b
	s_cmp_eq_u32 s97, 4
	s_cbranch_scc1 .Lengw2_c
	s_waitcnt vmcnt(16)
	s_branch .Lengw2_e

; #define PG8_STAGE(bufoff, gbase, voff) do { _Pragma("unroll") for (int _i = 0; _i < 2; ++_i) \
;         __builtin_amdgcn_global_load_lds((const unsigned*)((const char*)(gbase) + (voff)[_i]), (PG8_LAS unsigned*)(lds + (bufoff) + ldsw + _i * 8192), 16, 0, 0); } while (0)
; #define PG8_LDA(dst, b, h) do { _Pragma("unroll") for (int m = 0; m < 4; ++m) _Pragma("unroll") for (int k = 0; k < 2; ++k) dst[m][k] = *(const PG8_LAS bf16x8*)(lds + PG8_SA(b, h) + aoff + m * 2048 + k * 1024); } while (0)
; #define PG8_LDB(dst, b, h) do { _Pragma("unroll") for (int n = 0; n < 2; ++n) _Pragma("unroll") for (int k = 0; k < 2; ++k) dst[n][k] = *(const PG8_LAS bf16x8*)(lds + PG8_SB(b, h) + boff + n * 2048 + k * 1024); } while (0)
; #define PG8_MMA(ai, bj, At, Bt) do { __builtin_amdgcn_s_setprio(3); _Pragma("unroll") for (int m = 0; m < 4; ++m) _Pragma("unroll") for (int n = 0; n < 2; ++n) _Pragma("unroll") for (int k = 0; k < 2; ++k) \
;         acc[ai][bj][m][n] = __builtin_amdgcn_mfma_f32_16x16x32_bf16(Bt[n][k], At[m][k], acc[ai][bj][m][n], 0, 0, 0); __builtin_amdgcn_s_setprio(0); } while (0)
; #define PG8_WAIT_V(n) asm volatile("s_waitcnt vmcnt(" #n ")" ::: "memory")
; #define PG8_WAIT_L(n) asm volatile("s_waitcnt lgkmcnt(" #n ")" ::: "memory")
; #define PG8_BAR __builtin_amdgcn_s_barrier()
; #define PG8_SCHED __builtin_amdgcn_sched_barrier(0)
; template <class Epi, class Sched, bool ALIGN_EPI = false, bool SP2 = false>
; __device__ __forceinline__ void gemm_phase(PG8_LAS unsigned char* lds, const Gemm g, const Sched& S, const Epi& E) {
;     ...
;             PG8_WAIT_V(8); PG8_WAIT_L(0); PG8_BAR; PG8_MMA(1, 0, At, B0); PG8_MMA(1, 1, At, B1); PG8_BAR; PG8_SCHED;
;             PG8_LDB(B0, 1, 0); PG8_LDB(B1, 1, 1); PG8_SCHED; PG8_LDA(At, 1, 0); PG8_STAGE(PG8_SA(0, 1), a2 + hstepA, voffA);
;             PG8_WAIT_V(8); PG8_WAIT_L(0); PG8_BAR; PG8_MMA(0, 0, At, B0); PG8_MMA(0, 1, At, B1); PG8_BAR; PG8_SCHED;
.Lengw2_e:
	s_waitcnt lgkmcnt(0)
	s_barrier
	s_setprio 3
	v_mfma_f32_16x16x32_bf16 v[62:65], v[130:133], v[192:195], v[62:65]
	v_mfma_f32_16x16x32_bf16 v[62:65], v[134:137], v[196:199], v[62:65]
	v_mfma_f32_16x16x32_bf16 v[54:57], v[156:159], v[192:195], v[54:57]
	v_mfma_f32_16x16x32_bf16 v[54:57], v[172:175], v[196:199], v[54:57]
	v_mfma_f32_16x16x32_bf16 v[38:41], v[156:159], v[200:203], v[38:41]
	v_mfma_f32_16x16x32_bf16 v[38:41], v[172:175], v[204:207], v[38:41]
	v_mfma_f32_16x16x32_bf16 v[46:49], v[130:133], v[200:203], v[46:49]
	v_mfma_f32_16x16x32_bf16 v[46:49], v[134:137], v[204:207], v[46:49]
	v_mfma_f32_16x16x32_bf16 v[30:33], v[130:133], v[208:211], v[30:33]
	v_mfma_f32_16x16x32_bf16 v[30:33], v[134:137], v[212:215], v[30:33]
	v_mfma_f32_16x16x32_bf16 v[22:25], v[156:159], v[208:211], v[22:25]
	v_mfma_f32_16x16x32_bf16 v[22:25], v[172:175], v[212:215], v[22:25]
	v_mfma_f32_16x16x32_bf16 v[6:9], v[156:159], v[216:219], v[6:9]
	v_mfma_f32_16x16x32_bf16 v[6:9], v[172:175], v[220:223], v[6:9]
	v_mfma_f32_16x16x32_bf16 v[14:17], v[130:133], v[216:219], v[14:17]
	v_mfma_f32_16x16x32_bf16 v[14:17], v[134:137], v[220:223], v[14:17]
	v_mfma_f32_16x16x32_bf16 v[58:61], v[176:179], v[192:195], v[58:61]
	v_mfma_f32_16x16x32_bf16 v[58:61], v[180:183], v[196:199], v[58:61]
	v_mfma_f32_16x16x32_bf16 v[50:53], v[184:187], v[192:195], v[50:53]
	v_mfma_f32_16x16x32_bf16 v[50:53], v[188:191], v[196:199], v[50:53]
	v_mfma_f32_16x16x32_bf16 v[34:37], v[184:187], v[200:203], v[34:37]
	v_mfma_f32_16x16x32_bf16 v[34:37], v[188:191], v[204:207], v[34:37]
	v_mfma_f32_16x16x32_bf16 v[42:45], v[176:179], v[200:203], v[42:45]
	v_mfma_f32_16x16x32_bf16 v[42:45], v[180:183], v[204:207], v[42:45]
	v_mfma_f32_16x16x32_bf16 v[26:29], v[176:179], v[208:211], v[26:29]
	v_mfma_f32_16x16x32_bf16 v[26:29], v[180:183], v[212:215], v[26:29]
	v_mfma_f32_16x16x32_bf16 v[18:21], v[184:187], v[208:211], v[18:21]
	v_mfma_f32_16x16x32_bf16 v[18:21], v[188:191], v[212:215], v[18:21]
	v_mfma_f32_16x16x32_bf16 v[2:5], v[184:187], v[216:219], v[2:5]
	v_mfma_f32_16x16x32_bf16 v[2:5], v[188:191], v[220:223], v[2:5]
	v_mfma_f32_16x16x32_bf16 v[10:13], v[176:179], v[216:219], v[10:13]
	v_mfma_f32_16x16x32_bf16 v[10:13], v[180:183], v[220:223], v[10:13]
	s_barrier
	s_setprio 0
	s_add_i32 s56, 0, 0x18000
	v_add_u32_e32 v146, s56, v164
	s_add_i32 s57, 0, 0x1c000
	ds_read_b128 v[130:133], v146
	ds_read_b128 v[134:137], v146 offset:1024
	ds_read_b128 v[156:159], v146 offset:2048
	ds_read_b128 v[172:175], v146 offset:3072
	v_add_u32_e32 v146, s57, v164
	ds_read_b128 v[176:179], v146
	ds_read_b128 v[180:183], v146 offset:1024
	ds_read_b128 v[184:187], v146 offset:2048
	ds_read_b128 v[188:191], v146 offset:3072
	s_add_u32 s36, s36, 0x100000
	s_addc_u32 s37, s37, 0
	s_mov_b32 m0, s72
	v_lshl_add_u64 v[230:231], s[36:37], 0, v[138:139]
	ds_read_b128 v[192:195], v169 offset:32768
	ds_read_b128 v[196:199], v169 offset:33792
	ds_read_b128 v[200:203], v169 offset:34816
	ds_read_b128 v[204:207], v169 offset:35840
	ds_read_b128 v[208:211], v169 offset:36864
	ds_read_b128 v[212:215], v169 offset:37888
	ds_read_b128 v[216:219], v169 offset:38912
	ds_read_b128 v[220:223], v169 offset:39936
	global_load_lds_dwordx4 v[230:231], off
	v_lshl_add_u64 v[230:231], s[36:37], 0, v[142:143]
	s_mov_b32 m0, s73
	s_nop 0
	global_load_lds_dwordx4 v[230:231], off
	s_cmp_eq_u32 s97, 4
	s_cbranch_scc1 .Lengw3_c
	s_cmp_eq_u32 s97, 8
	s_cbranch_scc1 .Lengw3_d
	s_waitcnt vmcnt(8)
	s_branch .Lengw3_e

; #define PG8_STAGE(bufoff, gbase, voff) do { _Pragma("unroll") for (int _i = 0; _i < 2; ++_i) \
;         __builtin_amdgcn_global_load_lds((const unsigned*)((const char*)(gbase) + (voff)[_i]), (PG8_LAS unsigned*)(lds + (bufoff) + ldsw + _i * 8192), 16, 0, 0); } while (0)
; #define PG8_LDA(dst, b, h) do { _Pragma("unroll") for (int m = 0; m < 4; ++m) _Pragma("unroll") for (int k = 0; k < 2; ++k) dst[m][k] = *(const PG8_LAS bf16x8*)(lds + PG8_SA(b, h) + aoff + m * 2048 + k * 1024); } while (0)
; #define PG8_MMA(ai, bj, At, Bt) do { __builtin_amdgcn_s_setprio(3); _Pragma("unroll") for (int m = 0; m < 4; ++m) _Pragma("unroll") for (int n = 0; n < 2; ++n) _Pragma("unroll") for (int k = 0; k < 2; ++k) \
;         acc[ai][bj][m][n] = __builtin_amdgcn_mfma_f32_16x16x32_bf16(Bt[n][k], At[m][k], acc[ai][bj][m][n], 0, 0, 0); __builtin_amdgcn_s_setprio(0); } while (0)
; #define PG8_WAIT_V(n) asm volatile("s_waitcnt vmcnt(" #n ")" ::: "memory")
; #define PG8_WAIT_L(n) asm volatile("s_waitcnt lgkmcnt(" #n ")" ::: "memory")
; #define PG8_BAR __builtin_amdgcn_s_barrier()
; #define PG8_SCHED __builtin_amdgcn_sched_barrier(0)
; template <class Epi, class Sched, bool ALIGN_EPI = false, bool SP2 = false>
; __device__ __forceinline__ void gemm_phase(PG8_LAS unsigned char* lds, const Gemm g, const Sched& S, const Epi& E) {
;     ...
;             PG8_WAIT_V(8); PG8_WAIT_L(0); PG8_BAR; PG8_MMA(0, 0, At, B0); PG8_MMA(0, 1, At, B1); PG8_BAR; PG8_SCHED;
;             PG8_LDA(At, 1, 1); PG8_STAGE(PG8_SB(1, 0), b3, voffB); PG8_STAGE(PG8_SB(1, 1), b3 + hstepB, voffB); PG8_STAGE(PG8_SA(1, 0), a3, voffA);
;             PG8_WAIT_V(8); PG8_WAIT_L(0); PG8_BAR; PG8_MMA(1, 0, At, B0); PG8_MMA(1, 1, At, B1); PG8_BAR; PG8_SCHED;
;     ...
;         if constexpr (ALIGN_EPI) { if (wr == 0) PG8_BAR; }
;         if constexpr (!Epi::AFTER_DRAIN) { E(acc, cur, wr, wc, fr, fq); S.done(cur); }
.Lengw3_e:
	s_waitcnt lgkmcnt(0)
	s_barrier
	s_setprio 3
	v_mfma_f32_16x16x32_bf16 v[126:129], v[130:133], v[192:195], v[126:129]
	v_mfma_f32_16x16x32_bf16 v[126:129], v[134:137], v[196:199], v[126:129]
	v_mfma_f32_16x16x32_bf16 v[118:121], v[156:159], v[192:195], v[118:121]
	v_mfma_f32_16x16x32_bf16 v[118:121], v[172:175], v[196:199], v[118:121]
	v_mfma_f32_16x16x32_bf16 v[102:105], v[156:159], v[200:203], v[102:105]
	v_mfma_f32_16x16x32_bf16 v[102:105], v[172:175], v[204:207], v[102:105]
	v_mfma_f32_16x16x32_bf16 v[110:113], v[130:133], v[200:203], v[110:113]
	v_mfma_f32_16x16x32_bf16 v[110:113], v[134:137], v[204:207], v[110:113]
	v_mfma_f32_16x16x32_bf16 v[94:97], v[130:133], v[208:211], v[94:97]
	v_mfma_f32_16x16x32_bf16 v[94:97], v[134:137], v[212:215], v[94:97]
	v_mfma_f32_16x16x32_bf16 v[86:89], v[156:159], v[208:211], v[86:89]
	v_mfma_f32_16x16x32_bf16 v[86:89], v[172:175], v[212:215], v[86:89]
	v_mfma_f32_16x16x32_bf16 v[70:73], v[156:159], v[216:219], v[70:73]
	v_mfma_f32_16x16x32_bf16 v[70:73], v[172:175], v[220:223], v[70:73]
	v_mfma_f32_16x16x32_bf16 v[78:81], v[130:133], v[216:219], v[78:81]
	v_mfma_f32_16x16x32_bf16 v[78:81], v[134:137], v[220:223], v[78:81]
	v_mfma_f32_16x16x32_bf16 v[122:125], v[176:179], v[192:195], v[122:125]
	v_mfma_f32_16x16x32_bf16 v[122:125], v[180:183], v[196:199], v[122:125]
	v_mfma_f32_16x16x32_bf16 v[114:117], v[184:187], v[192:195], v[114:117]
	v_mfma_f32_16x16x32_bf16 v[114:117], v[188:191], v[196:199], v[114:117]
	v_mfma_f32_16x16x32_bf16 v[98:101], v[184:187], v[200:203], v[98:101]
	v_mfma_f32_16x16x32_bf16 v[98:101], v[188:191], v[204:207], v[98:101]
	v_mfma_f32_16x16x32_bf16 v[106:109], v[176:179], v[200:203], v[106:109]
	v_mfma_f32_16x16x32_bf16 v[106:109], v[180:183], v[204:207], v[106:109]
	v_mfma_f32_16x16x32_bf16 v[90:93], v[176:179], v[208:211], v[90:93]
	v_mfma_f32_16x16x32_bf16 v[90:93], v[180:183], v[212:215], v[90:93]
	v_mfma_f32_16x16x32_bf16 v[82:85], v[184:187], v[208:211], v[82:85]
	v_mfma_f32_16x16x32_bf16 v[82:85], v[188:191], v[212:215], v[82:85]
	v_mfma_f32_16x16x32_bf16 v[66:69], v[184:187], v[216:219], v[66:69]
	v_mfma_f32_16x16x32_bf16 v[66:69], v[188:191], v[220:223], v[66:69]
	v_mfma_f32_16x16x32_bf16 v[74:77], v[176:179], v[216:219], v[74:77]
	v_mfma_f32_16x16x32_bf16 v[74:77], v[180:183], v[220:223], v[74:77]
	s_barrier
	s_setprio 0
	s_add_i32 s36, s56, s66
	v_lshl_add_u64 v[160:161], v[160:161], 0, s[18:19]
	s_mov_b32 m0, s36
	ds_read_b128 v[192:195], v169 offset:49152
	ds_read_b128 v[196:199], v169 offset:50176
	ds_read_b128 v[200:203], v169 offset:51200
	ds_read_b128 v[204:207], v169 offset:52224
	ds_read_b128 v[208:211], v169 offset:53248
	ds_read_b128 v[212:215], v169 offset:54272
	ds_read_b128 v[216:219], v169 offset:55296
	ds_read_b128 v[220:223], v169 offset:56320
	global_load_lds_dwordx4 v[160:161], off
	s_add_i32 m0, s36, 0x2000
	s_add_u32 s8, s8, 0x100080
	v_lshl_add_u64 v[160:161], v[224:225], 0, s[18:19]
	s_addc_u32 s9, s9, 0
	s_add_i32 s36, s57, s66
	global_load_lds_dwordx4 v[160:161], off
	v_lshl_add_u64 v[160:161], s[8:9], 0, v[140:141]
	s_mov_b32 m0, s36
	s_nop 0
	global_load_lds_dwordx4 v[160:161], off
	v_lshl_add_u64 v[160:161], s[8:9], 0, v[144:145]
	s_add_i32 m0, s36, 0x2000
	s_nop 0
	global_load_lds_dwordx4 v[160:161], off
	v_lshl_add_u64 v[160:161], v[226:227], 0, s[18:19]
	s_mov_b32 m0, s75
	s_nop 0
	global_load_lds_dwordx4 v[160:161], off
	v_lshl_add_u64 v[160:161], v[228:229], 0, s[18:19]
	s_mov_b32 m0, s76
	s_nop 0
	global_load_lds_dwordx4 v[160:161], off
	s_waitcnt vmcnt(8)
	s_waitcnt lgkmcnt(0)
	s_barrier
	s_setprio 3
	v_mfma_f32_16x16x32_bf16 v[62:65], v[130:133], v[192:195], v[62:65]
	v_mfma_f32_16x16x32_bf16 v[62:65], v[134:137], v[196:199], v[62:65]
	v_mfma_f32_16x16x32_bf16 v[54:57], v[156:159], v[192:195], v[54:57]
	v_mfma_f32_16x16x32_bf16 v[54:57], v[172:175], v[196:199], v[54:57]
	v_mfma_f32_16x16x32_bf16 v[38:41], v[156:159], v[200:203], v[38:41]
	v_mfma_f32_16x16x32_bf16 v[38:41], v[172:175], v[204:207], v[38:41]
	v_mfma_f32_16x16x32_bf16 v[46:49], v[130:133], v[200:203], v[46:49]
	v_mfma_f32_16x16x32_bf16 v[46:49], v[134:137], v[204:207], v[46:49]
	v_mfma_f32_16x16x32_bf16 v[30:33], v[130:133], v[208:211], v[30:33]
	v_mfma_f32_16x16x32_bf16 v[30:33], v[134:137], v[212:215], v[30:33]
	v_mfma_f32_16x16x32_bf16 v[22:25], v[156:159], v[208:211], v[22:25]
	v_mfma_f32_16x16x32_bf16 v[22:25], v[172:175], v[212:215], v[22:25]
	v_mfma_f32_16x16x32_bf16 v[6:9], v[156:159], v[216:219], v[6:9]
	v_mfma_f32_16x16x32_bf16 v[6:9], v[172:175], v[220:223], v[6:9]
	v_mfma_f32_16x16x32_bf16 v[14:17], v[130:133], v[216:219], v[14:17]
	v_mfma_f32_16x16x32_bf16 v[14:17], v[134:137], v[220:223], v[14:17]
	v_mfma_f32_16x16x32_bf16 v[58:61], v[176:179], v[192:195], v[58:61]
	v_mfma_f32_16x16x32_bf16 v[58:61], v[180:183], v[196:199], v[58:61]
	v_mfma_f32_16x16x32_bf16 v[50:53], v[184:187], v[192:195], v[50:53]
	v_mfma_f32_16x16x32_bf16 v[50:53], v[188:191], v[196:199], v[50:53]
	v_mfma_f32_16x16x32_bf16 v[34:37], v[184:187], v[200:203], v[34:37]
	v_mfma_f32_16x16x32_bf16 v[34:37], v[188:191], v[204:207], v[34:37]
	v_mfma_f32_16x16x32_bf16 v[42:45], v[176:179], v[200:203], v[42:45]
	v_mfma_f32_16x16x32_bf16 v[42:45], v[180:183], v[204:207], v[42:45]
	v_mfma_f32_16x16x32_bf16 v[26:29], v[176:179], v[208:211], v[26:29]
	v_mfma_f32_16x16x32_bf16 v[26:29], v[180:183], v[212:215], v[26:29]
	v_mfma_f32_16x16x32_bf16 v[18:21], v[184:187], v[208:211], v[18:21]
	v_mfma_f32_16x16x32_bf16 v[18:21], v[188:191], v[212:215], v[18:21]
	v_mfma_f32_16x16x32_bf16 v[2:5], v[184:187], v[216:219], v[2:5]
	v_mfma_f32_16x16x32_bf16 v[2:5], v[188:191], v[220:223], v[2:5]
	v_mfma_f32_16x16x32_bf16 v[10:13], v[176:179], v[216:219], v[10:13]
	v_mfma_f32_16x16x32_bf16 v[10:13], v[180:183], v[220:223], v[10:13]
	s_barrier
	s_setprio 0
	s_add_i32 s45, s45, 2
	s_add_u32 s6, s6, 0x100
	s_addc_u32 s7, s7, 0
	s_add_u32 s33, s33, 0x100
	s_addc_u32 s44, s44, 0
	s_cmp_gt_u32 s45, 61
	s_cbranch_scc0 .LBB0_143
	s_and_b64 vcc, exec, s[20:21]
	s_cbranch_vccz .LBB0_148
	s_barrier
	v_lshl_add_u32 v156, s0, 8, v163
	s_cmp_lt_i32 s54, 40
	s_mov_b64 s[0:1], -1
	s_cbranch_scc1 .LBB0_149

; #define PG8_STAGE(bufoff, gbase, voff) do { _Pragma("unroll") for (int _i = 0; _i < 2; ++_i) \
;         __builtin_amdgcn_global_load_lds((const unsigned*)((const char*)(gbase) + (voff)[_i]), (PG8_LAS unsigned*)(lds + (bufoff) + ldsw + _i * 8192), 16, 0, 0); } while (0)
; #define PG8_LDA(dst, b, h) do { _Pragma("unroll") for (int m = 0; m < 4; ++m) _Pragma("unroll") for (int k = 0; k < 2; ++k) dst[m][k] = *(const PG8_LAS bf16x8*)(lds + PG8_SA(b, h) + aoff + m * 2048 + k * 1024); } while (0)
; #define PG8_LDB(dst, b, h) do { _Pragma("unroll") for (int n = 0; n < 2; ++n) _Pragma("unroll") for (int k = 0; k < 2; ++k) dst[n][k] = *(const PG8_LAS bf16x8*)(lds + PG8_SB(b, h) + boff + n * 2048 + k * 1024); } while (0)
; #define PG8_MMA(ai, bj, At, Bt) do { __builtin_amdgcn_s_setprio(3); _Pragma("unroll") for (int m = 0; m < 4; ++m) _Pragma("unroll") for (int n = 0; n < 2; ++n) _Pragma("unroll") for (int k = 0; k < 2; ++k) \
;         acc[ai][bj][m][n] = __builtin_amdgcn_mfma_f32_16x16x32_bf16(Bt[n][k], At[m][k], acc[ai][bj][m][n], 0, 0, 0); __builtin_amdgcn_s_setprio(0); } while (0)
; #define PG8_WAIT_V(n) asm volatile("s_waitcnt vmcnt(" #n ")" ::: "memory")
; #define PG8_WAIT_L(n) asm volatile("s_waitcnt lgkmcnt(" #n ")" ::: "memory")
; #define PG8_BAR __builtin_amdgcn_s_barrier()
; #define PG8_SCHED __builtin_amdgcn_sched_barrier(0)
; template <class Epi, class Sched, bool ALIGN_EPI = false, bool SP2 = false>
; __device__ __forceinline__ void gemm_phase(PG8_LAS unsigned char* lds, const Gemm g, const Sched& S, const Epi& E) {
;     ...
;             const char* a1 = cA + (size_t)(t + 1) * kstep;
;             const char* a2 = last ? nA : cA + (size_t)(t + 2) * kstep; const char* b2 = last ? nB : cB + (size_t)(t + 2) * kstep;
;             const char* a3 = a2 + kstep; const char* b3 = b2 + kstep;
;             if (last && has_next) S.a_ready(nxt);
;             if constexpr (Epi::MIDK) { if (t == E.midk_step(nt)) E.midk(acc, cur, wr, wc, fr, fq); }
;             if constexpr (SP2) {
;             PG8_LDB(B0, 0, 0); PG8_LDB(B1, 0, 1); PG8_SCHED; PG8_LDA(At, 0, 0); PG8_STAGE(PG8_SA(1, 1), a1 + hstepA, voffA);
;             PG8_WAIT_V(8); PG8_WAIT_L(0); PG8_BAR; PG8_MMA(0, 0, At, B0); PG8_MMA(0, 1, At, B1); PG8_BAR; PG8_SCHED;
;             PG8_LDA(At, 0, 1); PG8_STAGE(PG8_SB(0, 0), b2, voffB); PG8_STAGE(PG8_SB(0, 1), b2 + hstepB, voffB); PG8_STAGE(PG8_SA(0, 0), a2, voffA);
.LBB0_478:
	ds_read_b128 v[130:133], v170
	ds_read_b128 v[134:137], v170 offset:1024
	ds_read_b128 v[138:141], v170 offset:2048
	ds_read_b128 v[142:145], v170 offset:3072
	ds_read_b128 v[164:167], v171
	ds_read_b128 v[174:177], v171 offset:1024
	ds_read_b128 v[178:181], v171 offset:2048
	ds_read_b128 v[182:185], v171 offset:3072
	s_add_u32 s36, s6, 0xfff80080
	s_addc_u32 s37, s7, -1
	s_cmp_eq_u32 s79, 4
	s_cselect_b32 s59, s27, s37
	s_cselect_b32 s58, s26, s36
	s_cselect_b32 s37, s23, s78
	s_cselect_b32 s36, s25, s77
	v_lshl_add_u64 v[218:219], s[6:7], 0, v[154:155]
	s_add_i32 m0, s31, 0xc000
	ds_read_b128 v[186:189], v172
	ds_read_b128 v[190:193], v172 offset:1024
	ds_read_b128 v[194:197], v172 offset:2048
	ds_read_b128 v[198:201], v172 offset:3072
	ds_read_b128 v[202:205], v172 offset:4096
	ds_read_b128 v[206:209], v172 offset:5120
	ds_read_b128 v[210:213], v172 offset:6144
	ds_read_b128 v[214:217], v172 offset:7168
	global_load_lds_dwordx4 v[218:219], off
	v_lshl_add_u64 v[218:219], s[6:7], 0, v[156:157]
	s_add_i32 m0, s31, 0xe000
	s_nop 0
	global_load_lds_dwordx4 v[218:219], off
	s_waitcnt vmcnt(8)
	s_waitcnt lgkmcnt(0)
	s_barrier
	s_setprio 3
	v_mfma_f32_16x16x32_bf16 v[126:129], v[130:133], v[186:189], v[126:129]
	v_mfma_f32_16x16x32_bf16 v[126:129], v[134:137], v[190:193], v[126:129]
	v_mfma_f32_16x16x32_bf16 v[122:125], v[138:141], v[186:189], v[122:125]
	v_mfma_f32_16x16x32_bf16 v[122:125], v[142:145], v[190:193], v[122:125]
	v_mfma_f32_16x16x32_bf16 v[114:117], v[138:141], v[194:197], v[114:117]
	v_mfma_f32_16x16x32_bf16 v[114:117], v[142:145], v[198:201], v[114:117]
	v_mfma_f32_16x16x32_bf16 v[118:121], v[130:133], v[194:197], v[118:121]
	v_mfma_f32_16x16x32_bf16 v[118:121], v[134:137], v[198:201], v[118:121]
	v_mfma_f32_16x16x32_bf16 v[110:113], v[130:133], v[202:205], v[110:113]
	v_mfma_f32_16x16x32_bf16 v[110:113], v[134:137], v[206:209], v[110:113]
	v_mfma_f32_16x16x32_bf16 v[102:105], v[138:141], v[202:205], v[102:105]
	v_mfma_f32_16x16x32_bf16 v[102:105], v[142:145], v[206:209], v[102:105]
	v_mfma_f32_16x16x32_bf16 v[74:77], v[138:141], v[210:213], v[74:77]
	v_mfma_f32_16x16x32_bf16 v[74:77], v[142:145], v[214:217], v[74:77]
	v_mfma_f32_16x16x32_bf16 v[78:81], v[130:133], v[210:213], v[78:81]
	v_mfma_f32_16x16x32_bf16 v[78:81], v[134:137], v[214:217], v[78:81]
	v_mfma_f32_16x16x32_bf16 v[106:109], v[164:167], v[186:189], v[106:109]
	v_mfma_f32_16x16x32_bf16 v[106:109], v[174:177], v[190:193], v[106:109]
	v_mfma_f32_16x16x32_bf16 v[98:101], v[178:181], v[186:189], v[98:101]
	v_mfma_f32_16x16x32_bf16 v[98:101], v[182:185], v[190:193], v[98:101]
	v_mfma_f32_16x16x32_bf16 v[90:93], v[178:181], v[194:197], v[90:93]
	v_mfma_f32_16x16x32_bf16 v[90:93], v[182:185], v[198:201], v[90:93]
	v_mfma_f32_16x16x32_bf16 v[94:97], v[164:167], v[194:197], v[94:97]
	v_mfma_f32_16x16x32_bf16 v[94:97], v[174:177], v[198:201], v[94:97]
	v_mfma_f32_16x16x32_bf16 v[86:89], v[164:167], v[202:205], v[86:89]
	v_mfma_f32_16x16x32_bf16 v[86:89], v[174:177], v[206:209], v[86:89]
	v_mfma_f32_16x16x32_bf16 v[82:85], v[178:181], v[202:205], v[82:85]
	v_mfma_f32_16x16x32_bf16 v[82:85], v[182:185], v[206:209], v[82:85]
	v_mfma_f32_16x16x32_bf16 v[66:69], v[178:181], v[210:213], v[66:69]
	v_mfma_f32_16x16x32_bf16 v[66:69], v[182:185], v[214:217], v[66:69]
	v_mfma_f32_16x16x32_bf16 v[70:73], v[164:167], v[210:213], v[70:73]
	v_mfma_f32_16x16x32_bf16 v[70:73], v[174:177], v[214:217], v[70:73]
	s_barrier
	s_setprio 0
	s_add_i32 s83, s72, s44
	v_lshl_add_u64 v[218:219], s[36:37], 0, v[148:149]
	s_mov_b32 m0, s83
	ds_read_b128 v[186:189], v172 offset:16384
	ds_read_b128 v[190:193], v172 offset:17408
	ds_read_b128 v[194:197], v172 offset:18432
	ds_read_b128 v[198:201], v172 offset:19456
	ds_read_b128 v[202:205], v172 offset:20480
	ds_read_b128 v[206:209], v172 offset:21504
	ds_read_b128 v[210:213], v172 offset:22528
	ds_read_b128 v[214:217], v172 offset:23552
	global_load_lds_dwordx4 v[218:219], off
	s_add_i32 m0, s83, 0x2000
	s_add_u32 s84, s36, 0x20000
	v_lshl_add_u64 v[220:221], s[36:37], 0, v[152:153]
	s_addc_u32 s85, s37, 0
	s_add_i32 s83, s73, s44
	global_load_lds_dwordx4 v[220:221], off
	v_lshl_add_u64 v[222:223], s[84:85], 0, v[148:149]
	s_mov_b32 m0, s83
	v_lshl_add_u64 v[224:225], s[58:59], 0, v[150:151]
	global_load_lds_dwordx4 v[222:223], off
	v_lshl_add_u64 v[222:223], s[84:85], 0, v[152:153]
	s_add_i32 m0, s83, 0x2000
	s_nop 0
	global_load_lds_dwordx4 v[222:223], off
	v_lshl_add_u64 v[222:223], s[58:59], 0, v[146:147]
	s_mov_b32 m0, s31
	s_nop 0
	global_load_lds_dwordx4 v[222:223], off
	s_mov_b32 m0, s45
	s_nop 0
	global_load_lds_dwordx4 v[224:225], off
	s_waitcnt vmcnt(8)
	s_waitcnt lgkmcnt(0)
	s_barrier
; #define PG8_STAGE(bufoff, gbase, voff) do { _Pragma("unroll") for (int _i = 0; _i < 2; ++_i) \
;         __builtin_amdgcn_global_load_lds((const unsigned*)((const char*)(gbase) + (voff)[_i]), (PG8_LAS unsigned*)(lds + (bufoff) + ldsw + _i * 8192), 16, 0, 0); } while (0)
; #define PG8_LDA(dst, b, h) do { _Pragma("unroll") for (int m = 0; m < 4; ++m) _Pragma("unroll") for (int k = 0; k < 2; ++k) dst[m][k] = *(const PG8_LAS bf16x8*)(lds + PG8_SA(b, h) + aoff + m * 2048 + k * 1024); } while (0)
; #define PG8_LDB(dst, b, h) do { _Pragma("unroll") for (int n = 0; n < 2; ++n) _Pragma("unroll") for (int k = 0; k < 2; ++k) dst[n][k] = *(const PG8_LAS bf16x8*)(lds + PG8_SB(b, h) + boff + n * 2048 + k * 1024); } while (0)
; #define PG8_MMA(ai, bj, At, Bt) do { __builtin_amdgcn_s_setprio(3); _Pragma("unroll") for (int m = 0; m < 4; ++m) _Pragma("unroll") for (int n = 0; n < 2; ++n) _Pragma("unroll") for (int k = 0; k < 2; ++k) \
;         acc[ai][bj][m][n] = __builtin_amdgcn_mfma_f32_16x16x32_bf16(Bt[n][k], At[m][k], acc[ai][bj][m][n], 0, 0, 0); __builtin_amdgcn_s_setprio(0); } while (0)
; #define PG8_WAIT_V(n) asm volatile("s_waitcnt vmcnt(" #n ")" ::: "memory")
; #define PG8_WAIT_L(n) asm volatile("s_waitcnt lgkmcnt(" #n ")" ::: "memory")
; #define PG8_BAR __builtin_amdgcn_s_barrier()
; #define PG8_SCHED __builtin_amdgcn_sched_barrier(0)
; template <class Epi, class Sched, bool ALIGN_EPI = false, bool SP2 = false>
; __device__ __forceinline__ void gemm_phase(PG8_LAS unsigned char* lds, const Gemm g, const Sched& S, const Epi& E) {
;     ...
;             PG8_WAIT_V(8); PG8_WAIT_L(0); PG8_BAR; PG8_MMA(1, 0, At, B0); PG8_MMA(1, 1, At, B1); PG8_BAR; PG8_SCHED;
;             PG8_LDB(B0, 1, 0); PG8_LDB(B1, 1, 1); PG8_SCHED; PG8_LDA(At, 1, 0); PG8_STAGE(PG8_SA(0, 1), a2 + hstepA, voffA);
;             PG8_WAIT_V(8); PG8_WAIT_L(0); PG8_BAR; PG8_MMA(0, 0, At, B0); PG8_MMA(0, 1, At, B1); PG8_BAR; PG8_SCHED;
	s_setprio 3
	v_mfma_f32_16x16x32_bf16 v[62:65], v[130:133], v[186:189], v[62:65]
	v_mfma_f32_16x16x32_bf16 v[62:65], v[134:137], v[190:193], v[62:65]
	v_mfma_f32_16x16x32_bf16 v[58:61], v[138:141], v[186:189], v[58:61]
	v_mfma_f32_16x16x32_bf16 v[58:61], v[142:145], v[190:193], v[58:61]
	v_mfma_f32_16x16x32_bf16 v[46:49], v[138:141], v[194:197], v[46:49]
	v_mfma_f32_16x16x32_bf16 v[46:49], v[142:145], v[198:201], v[46:49]
	v_mfma_f32_16x16x32_bf16 v[54:57], v[130:133], v[194:197], v[54:57]
	v_mfma_f32_16x16x32_bf16 v[54:57], v[134:137], v[198:201], v[54:57]
	v_mfma_f32_16x16x32_bf16 v[38:41], v[130:133], v[202:205], v[38:41]
	v_mfma_f32_16x16x32_bf16 v[38:41], v[134:137], v[206:209], v[38:41]
	v_mfma_f32_16x16x32_bf16 v[30:33], v[138:141], v[202:205], v[30:33]
	v_mfma_f32_16x16x32_bf16 v[30:33], v[142:145], v[206:209], v[30:33]
	v_mfma_f32_16x16x32_bf16 v[14:17], v[138:141], v[210:213], v[14:17]
	v_mfma_f32_16x16x32_bf16 v[14:17], v[142:145], v[214:217], v[14:17]
	v_mfma_f32_16x16x32_bf16 v[22:25], v[130:133], v[210:213], v[22:25]
	v_mfma_f32_16x16x32_bf16 v[22:25], v[134:137], v[214:217], v[22:25]
	v_mfma_f32_16x16x32_bf16 v[50:53], v[164:167], v[186:189], v[50:53]
	v_mfma_f32_16x16x32_bf16 v[50:53], v[174:177], v[190:193], v[50:53]
	v_mfma_f32_16x16x32_bf16 v[42:45], v[178:181], v[186:189], v[42:45]
	v_mfma_f32_16x16x32_bf16 v[42:45], v[182:185], v[190:193], v[42:45]
	v_mfma_f32_16x16x32_bf16 v[26:29], v[178:181], v[194:197], v[26:29]
	v_mfma_f32_16x16x32_bf16 v[26:29], v[182:185], v[198:201], v[26:29]
	v_mfma_f32_16x16x32_bf16 v[34:37], v[164:167], v[194:197], v[34:37]
	v_mfma_f32_16x16x32_bf16 v[34:37], v[174:177], v[198:201], v[34:37]
	v_mfma_f32_16x16x32_bf16 v[18:21], v[164:167], v[202:205], v[18:21]
	v_mfma_f32_16x16x32_bf16 v[18:21], v[174:177], v[206:209], v[18:21]
	v_mfma_f32_16x16x32_bf16 v[10:13], v[178:181], v[202:205], v[10:13]
	v_mfma_f32_16x16x32_bf16 v[10:13], v[182:185], v[206:209], v[10:13]
	v_mfma_f32_16x16x32_bf16 v[2:5], v[178:181], v[210:213], v[2:5]
	v_mfma_f32_16x16x32_bf16 v[2:5], v[182:185], v[214:217], v[2:5]
	v_mfma_f32_16x16x32_bf16 v[6:9], v[164:167], v[210:213], v[6:9]
	v_mfma_f32_16x16x32_bf16 v[6:9], v[174:177], v[214:217], v[6:9]
	s_barrier
	s_setprio 0
	s_add_i32 s83, 0, 0x18000
	s_add_i32 s84, 0, 0x1c000
	v_add_u32_e32 v142, s83, v168
	v_add_u32_e32 v173, s84, v168
	ds_read_b128 v[130:133], v142
	ds_read_b128 v[134:137], v142 offset:1024
	ds_read_b128 v[138:141], v142 offset:2048
	ds_read_b128 v[142:145], v142 offset:3072
	ds_read_b128 v[164:167], v173
	ds_read_b128 v[174:177], v173 offset:1024
	ds_read_b128 v[178:181], v173 offset:2048
	ds_read_b128 v[182:185], v173 offset:3072
	s_add_u32 s58, s58, 0x80000
	s_addc_u32 s59, s59, 0
	s_mov_b32 m0, s54
	v_lshl_add_u64 v[226:227], s[58:59], 0, v[146:147]
	ds_read_b128 v[186:189], v172 offset:32768
	ds_read_b128 v[190:193], v172 offset:33792
	ds_read_b128 v[194:197], v172 offset:34816
	ds_read_b128 v[198:201], v172 offset:35840
	ds_read_b128 v[202:205], v172 offset:36864
	ds_read_b128 v[206:209], v172 offset:37888
	ds_read_b128 v[210:213], v172 offset:38912
	ds_read_b128 v[214:217], v172 offset:39936
	global_load_lds_dwordx4 v[226:227], off
	v_lshl_add_u64 v[226:227], s[58:59], 0, v[150:151]
	s_mov_b32 m0, s55
	s_nop 0
	global_load_lds_dwordx4 v[226:227], off
	s_waitcnt vmcnt(8)
	s_waitcnt lgkmcnt(0)
	s_barrier
	s_setprio 3
	v_mfma_f32_16x16x32_bf16 v[126:129], v[130:133], v[186:189], v[126:129]
	v_mfma_f32_16x16x32_bf16 v[126:129], v[134:137], v[190:193], v[126:129]
	v_mfma_f32_16x16x32_bf16 v[122:125], v[138:141], v[186:189], v[122:125]
	v_mfma_f32_16x16x32_bf16 v[122:125], v[142:145], v[190:193], v[122:125]
	v_mfma_f32_16x16x32_bf16 v[114:117], v[138:141], v[194:197], v[114:117]
	v_mfma_f32_16x16x32_bf16 v[114:117], v[142:145], v[198:201], v[114:117]
	v_mfma_f32_16x16x32_bf16 v[118:121], v[130:133], v[194:197], v[118:121]
	v_mfma_f32_16x16x32_bf16 v[118:121], v[134:137], v[198:201], v[118:121]
	v_mfma_f32_16x16x32_bf16 v[110:113], v[130:133], v[202:205], v[110:113]
	v_mfma_f32_16x16x32_bf16 v[110:113], v[134:137], v[206:209], v[110:113]
	v_mfma_f32_16x16x32_bf16 v[102:105], v[138:141], v[202:205], v[102:105]
	v_mfma_f32_16x16x32_bf16 v[102:105], v[142:145], v[206:209], v[102:105]
	v_mfma_f32_16x16x32_bf16 v[74:77], v[138:141], v[210:213], v[74:77]
	v_mfma_f32_16x16x32_bf16 v[74:77], v[142:145], v[214:217], v[74:77]
	v_mfma_f32_16x16x32_bf16 v[78:81], v[130:133], v[210:213], v[78:81]
	v_mfma_f32_16x16x32_bf16 v[78:81], v[134:137], v[214:217], v[78:81]
	v_mfma_f32_16x16x32_bf16 v[106:109], v[164:167], v[186:189], v[106:109]
	v_mfma_f32_16x16x32_bf16 v[106:109], v[174:177], v[190:193], v[106:109]
	v_mfma_f32_16x16x32_bf16 v[98:101], v[178:181], v[186:189], v[98:101]
	v_mfma_f32_16x16x32_bf16 v[98:101], v[182:185], v[190:193], v[98:101]
	v_mfma_f32_16x16x32_bf16 v[90:93], v[178:181], v[194:197], v[90:93]
	v_mfma_f32_16x16x32_bf16 v[90:93], v[182:185], v[198:201], v[90:93]
	v_mfma_f32_16x16x32_bf16 v[94:97], v[164:167], v[194:197], v[94:97]
	v_mfma_f32_16x16x32_bf16 v[94:97], v[174:177], v[198:201], v[94:97]
	v_mfma_f32_16x16x32_bf16 v[86:89], v[164:167], v[202:205], v[86:89]
	v_mfma_f32_16x16x32_bf16 v[86:89], v[174:177], v[206:209], v[86:89]
	v_mfma_f32_16x16x32_bf16 v[82:85], v[178:181], v[202:205], v[82:85]
	v_mfma_f32_16x16x32_bf16 v[82:85], v[182:185], v[206:209], v[82:85]
	v_mfma_f32_16x16x32_bf16 v[66:69], v[178:181], v[210:213], v[66:69]
	v_mfma_f32_16x16x32_bf16 v[66:69], v[182:185], v[214:217], v[66:69]
	v_mfma_f32_16x16x32_bf16 v[70:73], v[164:167], v[210:213], v[70:73]
	v_mfma_f32_16x16x32_bf16 v[70:73], v[174:177], v[214:217], v[70:73]
	s_barrier
; #define PG8_STAGE(bufoff, gbase, voff) do { _Pragma("unroll") for (int _i = 0; _i < 2; ++_i) \
;         __builtin_amdgcn_global_load_lds((const unsigned*)((const char*)(gbase) + (voff)[_i]), (PG8_LAS unsigned*)(lds + (bufoff) + ldsw + _i * 8192), 16, 0, 0); } while (0)
; #define PG8_LDA(dst, b, h) do { _Pragma("unroll") for (int m = 0; m < 4; ++m) _Pragma("unroll") for (int k = 0; k < 2; ++k) dst[m][k] = *(const PG8_LAS bf16x8*)(lds + PG8_SA(b, h) + aoff + m * 2048 + k * 1024); } while (0)
; #define PG8_MMA(ai, bj, At, Bt) do { __builtin_amdgcn_s_setprio(3); _Pragma("unroll") for (int m = 0; m < 4; ++m) _Pragma("unroll") for (int n = 0; n < 2; ++n) _Pragma("unroll") for (int k = 0; k < 2; ++k) \
;         acc[ai][bj][m][n] = __builtin_amdgcn_mfma_f32_16x16x32_bf16(Bt[n][k], At[m][k], acc[ai][bj][m][n], 0, 0, 0); __builtin_amdgcn_s_setprio(0); } while (0)
; #define PG8_WAIT_V(n) asm volatile("s_waitcnt vmcnt(" #n ")" ::: "memory")
; #define PG8_WAIT_L(n) asm volatile("s_waitcnt lgkmcnt(" #n ")" ::: "memory")
; #define PG8_BAR __builtin_amdgcn_s_barrier()
; #define PG8_SCHED __builtin_amdgcn_sched_barrier(0)
; template <class Epi, class Sched, bool ALIGN_EPI = false, bool SP2 = false>
; __device__ __forceinline__ void gemm_phase(PG8_LAS unsigned char* lds, const Gemm g, const Sched& S, const Epi& E) {
;     ...
;             PG8_LDA(At, 1, 1); PG8_STAGE(PG8_SB(1, 0), b3, voffB); PG8_STAGE(PG8_SB(1, 1), b3 + hstepB, voffB); PG8_STAGE(PG8_SA(1, 0), a3, voffA);
;             PG8_WAIT_V(8); PG8_WAIT_L(0); PG8_BAR; PG8_MMA(1, 0, At, B0); PG8_MMA(1, 1, At, B1); PG8_BAR; PG8_SCHED;
;     ...
;         if constexpr (ALIGN_EPI) { if (wr == 0) PG8_BAR; }
	s_setprio 0
	s_add_i32 s58, s83, s44
	v_lshl_add_u64 v[218:219], v[218:219], 0, s[18:19]
	s_mov_b32 m0, s58
	ds_read_b128 v[186:189], v172 offset:49152
	ds_read_b128 v[190:193], v172 offset:50176
	ds_read_b128 v[194:197], v172 offset:51200
	ds_read_b128 v[198:201], v172 offset:52224
	ds_read_b128 v[202:205], v172 offset:53248
	ds_read_b128 v[206:209], v172 offset:54272
	ds_read_b128 v[210:213], v172 offset:55296
	ds_read_b128 v[214:217], v172 offset:56320
	global_load_lds_dwordx4 v[218:219], off
	s_add_i32 m0, s58, 0x2000
	s_add_u32 s36, s36, 0x20080
	v_lshl_add_u64 v[218:219], v[220:221], 0, s[18:19]
	s_addc_u32 s37, s37, 0
	s_add_i32 s58, s84, s44
	global_load_lds_dwordx4 v[218:219], off
	v_lshl_add_u64 v[218:219], s[36:37], 0, v[148:149]
	s_mov_b32 m0, s58
	s_nop 0
	global_load_lds_dwordx4 v[218:219], off
	v_lshl_add_u64 v[218:219], s[36:37], 0, v[152:153]
	s_add_i32 m0, s58, 0x2000
	s_nop 0
	global_load_lds_dwordx4 v[218:219], off
	v_lshl_add_u64 v[218:219], v[222:223], 0, s[18:19]
	s_mov_b32 m0, s63
	s_nop 0
	global_load_lds_dwordx4 v[218:219], off
	v_lshl_add_u64 v[218:219], v[224:225], 0, s[18:19]
	s_mov_b32 m0, s66
	s_nop 0
	global_load_lds_dwordx4 v[218:219], off
	s_waitcnt vmcnt(8)
	s_waitcnt lgkmcnt(0)
	s_barrier
	s_setprio 3
	v_mfma_f32_16x16x32_bf16 v[62:65], v[130:133], v[186:189], v[62:65]
	v_mfma_f32_16x16x32_bf16 v[62:65], v[134:137], v[190:193], v[62:65]
	v_mfma_f32_16x16x32_bf16 v[58:61], v[138:141], v[186:189], v[58:61]
	v_mfma_f32_16x16x32_bf16 v[58:61], v[142:145], v[190:193], v[58:61]
	v_mfma_f32_16x16x32_bf16 v[46:49], v[138:141], v[194:197], v[46:49]
	v_mfma_f32_16x16x32_bf16 v[46:49], v[142:145], v[198:201], v[46:49]
	v_mfma_f32_16x16x32_bf16 v[54:57], v[130:133], v[194:197], v[54:57]
	v_mfma_f32_16x16x32_bf16 v[54:57], v[134:137], v[198:201], v[54:57]
	v_mfma_f32_16x16x32_bf16 v[38:41], v[130:133], v[202:205], v[38:41]
	v_mfma_f32_16x16x32_bf16 v[38:41], v[134:137], v[206:209], v[38:41]
	v_mfma_f32_16x16x32_bf16 v[30:33], v[138:141], v[202:205], v[30:33]
	v_mfma_f32_16x16x32_bf16 v[30:33], v[142:145], v[206:209], v[30:33]
	v_mfma_f32_16x16x32_bf16 v[14:17], v[138:141], v[210:213], v[14:17]
	v_mfma_f32_16x16x32_bf16 v[14:17], v[142:145], v[214:217], v[14:17]
	v_mfma_f32_16x16x32_bf16 v[22:25], v[130:133], v[210:213], v[22:25]
	v_mfma_f32_16x16x32_bf16 v[22:25], v[134:137], v[214:217], v[22:25]
	v_mfma_f32_16x16x32_bf16 v[50:53], v[164:167], v[186:189], v[50:53]
	v_mfma_f32_16x16x32_bf16 v[50:53], v[174:177], v[190:193], v[50:53]
	v_mfma_f32_16x16x32_bf16 v[42:45], v[178:181], v[186:189], v[42:45]
	v_mfma_f32_16x16x32_bf16 v[42:45], v[182:185], v[190:193], v[42:45]
	v_mfma_f32_16x16x32_bf16 v[26:29], v[178:181], v[194:197], v[26:29]
	v_mfma_f32_16x16x32_bf16 v[26:29], v[182:185], v[198:201], v[26:29]
	v_mfma_f32_16x16x32_bf16 v[34:37], v[164:167], v[194:197], v[34:37]
	v_mfma_f32_16x16x32_bf16 v[34:37], v[174:177], v[198:201], v[34:37]
	v_mfma_f32_16x16x32_bf16 v[18:21], v[164:167], v[202:205], v[18:21]
	v_mfma_f32_16x16x32_bf16 v[18:21], v[174:177], v[206:209], v[18:21]
	v_mfma_f32_16x16x32_bf16 v[10:13], v[178:181], v[202:205], v[10:13]
	v_mfma_f32_16x16x32_bf16 v[10:13], v[182:185], v[206:209], v[10:13]
	v_mfma_f32_16x16x32_bf16 v[2:5], v[178:181], v[210:213], v[2:5]
	v_mfma_f32_16x16x32_bf16 v[2:5], v[182:185], v[214:217], v[2:5]
	v_mfma_f32_16x16x32_bf16 v[6:9], v[164:167], v[210:213], v[6:9]
	v_mfma_f32_16x16x32_bf16 v[6:9], v[174:177], v[214:217], v[6:9]
	s_barrier
	s_setprio 0
	s_add_i32 s79, s79, 2
	s_add_u32 s6, s6, 0x100
	s_addc_u32 s7, s7, 0
	s_add_u32 s77, s77, 0x100
	s_addc_u32 s78, s78, 0
	s_cmp_gt_u32 s79, 5
	s_cbranch_scc0 .LBB0_478
	s_and_b64 vcc, exec, s[20:21]
	s_cbranch_vccz .LBB0_481
	s_barrier

; #define PG8_STAGE(bufoff, gbase, voff) do { _Pragma("unroll") for (int _i = 0; _i < 2; ++_i) \
;         __builtin_amdgcn_global_load_lds((const unsigned*)((const char*)(gbase) + (voff)[_i]), (PG8_LAS unsigned*)(lds + (bufoff) + ldsw + _i * 8192), 16, 0, 0); } while (0)
; #define PG8_LDA(dst, b, h) do { _Pragma("unroll") for (int m = 0; m < 4; ++m) _Pragma("unroll") for (int k = 0; k < 2; ++k) dst[m][k] = *(const PG8_LAS bf16x8*)(lds + PG8_SA(b, h) + aoff + m * 2048 + k * 1024); } while (0)
; #define PG8_LDB(dst, b, h) do { _Pragma("unroll") for (int n = 0; n < 2; ++n) _Pragma("unroll") for (int k = 0; k < 2; ++k) dst[n][k] = *(const PG8_LAS bf16x8*)(lds + PG8_SB(b, h) + boff + n * 2048 + k * 1024); } while (0)
; #define PG8_MMA(ai, bj, At, Bt) do { __builtin_amdgcn_s_setprio(3); _Pragma("unroll") for (int m = 0; m < 4; ++m) _Pragma("unroll") for (int n = 0; n < 2; ++n) _Pragma("unroll") for (int k = 0; k < 2; ++k) \
;         acc[ai][bj][m][n] = __builtin_amdgcn_mfma_f32_16x16x32_bf16(Bt[n][k], At[m][k], acc[ai][bj][m][n], 0, 0, 0); __builtin_amdgcn_s_setprio(0); } while (0)
; #define PG8_WAIT_V(n) asm volatile("s_waitcnt vmcnt(" #n ")" ::: "memory")
; #define PG8_WAIT_L(n) asm volatile("s_waitcnt lgkmcnt(" #n ")" ::: "memory")
; #define PG8_BAR __builtin_amdgcn_s_barrier()
; #define PG8_SCHED __builtin_amdgcn_sched_barrier(0)
; template <class Epi, class Sched, bool ALIGN_EPI = false, bool SP2 = false>
; __device__ __forceinline__ void gemm_phase(PG8_LAS unsigned char* lds, const Gemm g, const Sched& S, const Epi& E) {
;     ...
;             const char* a1 = cA + (size_t)(t + 1) * kstep;
;             const char* a2 = last ? nA : cA + (size_t)(t + 2) * kstep; const char* b2 = last ? nB : cB + (size_t)(t + 2) * kstep;
;             const char* a3 = a2 + kstep; const char* b3 = b2 + kstep;
;             if (last && has_next) S.a_ready(nxt);
;             if constexpr (Epi::MIDK) { if (t == E.midk_step(nt)) E.midk(acc, cur, wr, wc, fr, fq); }
;             if constexpr (SP2) {
;             PG8_LDB(B0, 0, 0); PG8_LDB(B1, 0, 1); PG8_SCHED; PG8_LDA(At, 0, 0); PG8_STAGE(PG8_SA(1, 1), a1 + hstepA, voffA);
;             PG8_WAIT_V(8); PG8_WAIT_L(0); PG8_BAR; PG8_MMA(0, 0, At, B0); PG8_MMA(0, 1, At, B1); PG8_BAR; PG8_SCHED;
;             PG8_LDA(At, 0, 1); PG8_STAGE(PG8_SB(0, 0), b2, voffB); PG8_STAGE(PG8_SB(0, 1), b2 + hstepB, voffB); PG8_STAGE(PG8_SA(0, 0), a2, voffA);
.LBB0_727:
	v_add_u32_e32 v160, s66, v157
	ds_read_b128 v[130:133], v160
	ds_read_b128 v[164:167], v160 offset:1024
	ds_read_b128 v[168:171], v160 offset:2048
	ds_read_b128 v[172:175], v160 offset:3072
	v_add_u32_e32 v160, s67, v157
	s_add_u32 s0, s28, s30
	ds_read_b128 v[176:179], v160
	ds_read_b128 v[180:183], v160 offset:1024
	ds_read_b128 v[184:187], v160 offset:2048
	ds_read_b128 v[188:191], v160 offset:3072
	s_addc_u32 s1, s29, s31
	s_add_u32 s0, s0, 0x100
	s_addc_u32 s1, s1, 0
	s_add_u32 s84, s79, s30
	s_addc_u32 s85, s81, s31
	s_cmpk_eq_i32 s30, 0x1f00
	s_cselect_b32 s37, s23, s1
	s_cselect_b32 s36, s72, s0
	s_cselect_b32 s1, s75, s85
	s_cselect_b32 s0, s76, s84
	v_lshl_add_u64 v[160:161], v[150:151], 0, s[30:31]
	s_add_i32 m0, s44, 0xc000
	ds_read_b128 v[192:195], v159
	ds_read_b128 v[196:199], v159 offset:1024
	ds_read_b128 v[200:203], v159 offset:2048
	ds_read_b128 v[204:207], v159 offset:3072
	ds_read_b128 v[208:211], v159 offset:4096
	ds_read_b128 v[212:215], v159 offset:5120
	ds_read_b128 v[216:219], v159 offset:6144
	ds_read_b128 v[220:223], v159 offset:7168
	global_load_lds_dwordx4 v[160:161], off
	v_lshl_add_u64 v[160:161], v[152:153], 0, s[30:31]
	s_add_i32 m0, s44, 0xe000
	s_nop 0
	global_load_lds_dwordx4 v[160:161], off
	s_waitcnt vmcnt(8)
	s_waitcnt lgkmcnt(0)
	s_barrier
	s_setprio 3
	v_mfma_f32_16x16x32_bf16 v[126:129], v[130:133], v[192:195], v[126:129]
	v_mfma_f32_16x16x32_bf16 v[126:129], v[164:167], v[196:199], v[126:129]
	v_mfma_f32_16x16x32_bf16 v[122:125], v[168:171], v[192:195], v[122:125]
	v_mfma_f32_16x16x32_bf16 v[122:125], v[172:175], v[196:199], v[122:125]
	v_mfma_f32_16x16x32_bf16 v[106:109], v[168:171], v[200:203], v[106:109]
	v_mfma_f32_16x16x32_bf16 v[106:109], v[172:175], v[204:207], v[106:109]
	v_mfma_f32_16x16x32_bf16 v[110:113], v[130:133], v[200:203], v[110:113]
	v_mfma_f32_16x16x32_bf16 v[110:113], v[164:167], v[204:207], v[110:113]
	v_mfma_f32_16x16x32_bf16 v[94:97], v[130:133], v[208:211], v[94:97]
	v_mfma_f32_16x16x32_bf16 v[94:97], v[164:167], v[212:215], v[94:97]
	v_mfma_f32_16x16x32_bf16 v[90:93], v[168:171], v[208:211], v[90:93]
	v_mfma_f32_16x16x32_bf16 v[90:93], v[172:175], v[212:215], v[90:93]
	v_mfma_f32_16x16x32_bf16 v[74:77], v[168:171], v[216:219], v[74:77]
	v_mfma_f32_16x16x32_bf16 v[74:77], v[172:175], v[220:223], v[74:77]
	v_mfma_f32_16x16x32_bf16 v[78:81], v[130:133], v[216:219], v[78:81]
	v_mfma_f32_16x16x32_bf16 v[78:81], v[164:167], v[220:223], v[78:81]
	v_mfma_f32_16x16x32_bf16 v[118:121], v[176:179], v[192:195], v[118:121]
	v_mfma_f32_16x16x32_bf16 v[118:121], v[180:183], v[196:199], v[118:121]
	v_mfma_f32_16x16x32_bf16 v[114:117], v[184:187], v[192:195], v[114:117]
	v_mfma_f32_16x16x32_bf16 v[114:117], v[188:191], v[196:199], v[114:117]
	v_mfma_f32_16x16x32_bf16 v[98:101], v[184:187], v[200:203], v[98:101]
	v_mfma_f32_16x16x32_bf16 v[98:101], v[188:191], v[204:207], v[98:101]
	v_mfma_f32_16x16x32_bf16 v[102:105], v[176:179], v[200:203], v[102:105]
	v_mfma_f32_16x16x32_bf16 v[102:105], v[180:183], v[204:207], v[102:105]
	v_mfma_f32_16x16x32_bf16 v[86:89], v[176:179], v[208:211], v[86:89]
	v_mfma_f32_16x16x32_bf16 v[86:89], v[180:183], v[212:215], v[86:89]
	v_mfma_f32_16x16x32_bf16 v[82:85], v[184:187], v[208:211], v[82:85]
	v_mfma_f32_16x16x32_bf16 v[82:85], v[188:191], v[212:215], v[82:85]
	v_mfma_f32_16x16x32_bf16 v[66:69], v[184:187], v[216:219], v[66:69]
	v_mfma_f32_16x16x32_bf16 v[66:69], v[188:191], v[220:223], v[66:69]
	v_mfma_f32_16x16x32_bf16 v[70:73], v[176:179], v[216:219], v[70:73]
	v_mfma_f32_16x16x32_bf16 v[70:73], v[180:183], v[220:223], v[70:73]
	s_barrier
	s_setprio 0
	s_add_i32 s84, s66, s33
	v_lshl_add_u64 v[160:161], s[0:1], 0, v[136:137]
	s_mov_b32 m0, s84
	ds_read_b128 v[192:195], v159 offset:16384
	ds_read_b128 v[196:199], v159 offset:17408
	ds_read_b128 v[200:203], v159 offset:18432
	ds_read_b128 v[204:207], v159 offset:19456
	ds_read_b128 v[208:211], v159 offset:20480
	ds_read_b128 v[212:215], v159 offset:21504
	ds_read_b128 v[216:219], v159 offset:22528
	ds_read_b128 v[220:223], v159 offset:23552
	global_load_lds_dwordx4 v[160:161], off
	s_add_i32 m0, s84, 0x2000
	s_add_u32 s84, s0, 0x100000
	v_lshl_add_u64 v[224:225], s[0:1], 0, v[140:141]
	s_addc_u32 s85, s1, 0
	s_add_i32 s86, s67, s33
	global_load_lds_dwordx4 v[224:225], off
	v_lshl_add_u64 v[226:227], s[84:85], 0, v[136:137]
	s_mov_b32 m0, s86
	v_lshl_add_u64 v[228:229], s[36:37], 0, v[138:139]
	global_load_lds_dwordx4 v[226:227], off
	v_lshl_add_u64 v[226:227], s[84:85], 0, v[140:141]
	s_add_i32 m0, s86, 0x2000
	s_nop 0
	global_load_lds_dwordx4 v[226:227], off
	v_lshl_add_u64 v[226:227], s[36:37], 0, v[134:135]
	s_mov_b32 m0, s44
	s_nop 0
	global_load_lds_dwordx4 v[226:227], off
	s_mov_b32 m0, s45
	s_nop 0
	global_load_lds_dwordx4 v[228:229], off
	s_waitcnt vmcnt(8)
	s_waitcnt lgkmcnt(0)
	s_barrier
; #define PG8_STAGE(bufoff, gbase, voff) do { _Pragma("unroll") for (int _i = 0; _i < 2; ++_i) \
;         __builtin_amdgcn_global_load_lds((const unsigned*)((const char*)(gbase) + (voff)[_i]), (PG8_LAS unsigned*)(lds + (bufoff) + ldsw + _i * 8192), 16, 0, 0); } while (0)
; #define PG8_LDA(dst, b, h) do { _Pragma("unroll") for (int m = 0; m < 4; ++m) _Pragma("unroll") for (int k = 0; k < 2; ++k) dst[m][k] = *(const PG8_LAS bf16x8*)(lds + PG8_SA(b, h) + aoff + m * 2048 + k * 1024); } while (0)
; #define PG8_LDB(dst, b, h) do { _Pragma("unroll") for (int n = 0; n < 2; ++n) _Pragma("unroll") for (int k = 0; k < 2; ++k) dst[n][k] = *(const PG8_LAS bf16x8*)(lds + PG8_SB(b, h) + boff + n * 2048 + k * 1024); } while (0)
; #define PG8_MMA(ai, bj, At, Bt) do { __builtin_amdgcn_s_setprio(3); _Pragma("unroll") for (int m = 0; m < 4; ++m) _Pragma("unroll") for (int n = 0; n < 2; ++n) _Pragma("unroll") for (int k = 0; k < 2; ++k) \
;         acc[ai][bj][m][n] = __builtin_amdgcn_mfma_f32_16x16x32_bf16(Bt[n][k], At[m][k], acc[ai][bj][m][n], 0, 0, 0); __builtin_amdgcn_s_setprio(0); } while (0)
; #define PG8_WAIT_V(n) asm volatile("s_waitcnt vmcnt(" #n ")" ::: "memory")
; #define PG8_WAIT_L(n) asm volatile("s_waitcnt lgkmcnt(" #n ")" ::: "memory")
; #define PG8_BAR __builtin_amdgcn_s_barrier()
; #define PG8_SCHED __builtin_amdgcn_sched_barrier(0)
; template <class Epi, class Sched, bool ALIGN_EPI = false, bool SP2 = false>
; __device__ __forceinline__ void gemm_phase(PG8_LAS unsigned char* lds, const Gemm g, const Sched& S, const Epi& E) {
;     ...
;             PG8_WAIT_V(8); PG8_WAIT_L(0); PG8_BAR; PG8_MMA(1, 0, At, B0); PG8_MMA(1, 1, At, B1); PG8_BAR; PG8_SCHED;
;             PG8_LDB(B0, 1, 0); PG8_LDB(B1, 1, 1); PG8_SCHED; PG8_LDA(At, 1, 0); PG8_STAGE(PG8_SA(0, 1), a2 + hstepA, voffA);
;             PG8_WAIT_V(8); PG8_WAIT_L(0); PG8_BAR; PG8_MMA(0, 0, At, B0); PG8_MMA(0, 1, At, B1); PG8_BAR; PG8_SCHED;
	s_setprio 3
	v_mfma_f32_16x16x32_bf16 v[62:65], v[130:133], v[192:195], v[62:65]
	v_mfma_f32_16x16x32_bf16 v[62:65], v[164:167], v[196:199], v[62:65]
	v_mfma_f32_16x16x32_bf16 v[58:61], v[168:171], v[192:195], v[58:61]
	v_mfma_f32_16x16x32_bf16 v[58:61], v[172:175], v[196:199], v[58:61]
	v_mfma_f32_16x16x32_bf16 v[42:45], v[168:171], v[200:203], v[42:45]
	v_mfma_f32_16x16x32_bf16 v[42:45], v[172:175], v[204:207], v[42:45]
	v_mfma_f32_16x16x32_bf16 v[46:49], v[130:133], v[200:203], v[46:49]
	v_mfma_f32_16x16x32_bf16 v[46:49], v[164:167], v[204:207], v[46:49]
	v_mfma_f32_16x16x32_bf16 v[30:33], v[130:133], v[208:211], v[30:33]
	v_mfma_f32_16x16x32_bf16 v[30:33], v[164:167], v[212:215], v[30:33]
	v_mfma_f32_16x16x32_bf16 v[26:29], v[168:171], v[208:211], v[26:29]
	v_mfma_f32_16x16x32_bf16 v[26:29], v[172:175], v[212:215], v[26:29]
	v_mfma_f32_16x16x32_bf16 v[10:13], v[168:171], v[216:219], v[10:13]
	v_mfma_f32_16x16x32_bf16 v[10:13], v[172:175], v[220:223], v[10:13]
	v_mfma_f32_16x16x32_bf16 v[14:17], v[130:133], v[216:219], v[14:17]
	v_mfma_f32_16x16x32_bf16 v[14:17], v[164:167], v[220:223], v[14:17]
	v_mfma_f32_16x16x32_bf16 v[54:57], v[176:179], v[192:195], v[54:57]
	v_mfma_f32_16x16x32_bf16 v[54:57], v[180:183], v[196:199], v[54:57]
	v_mfma_f32_16x16x32_bf16 v[50:53], v[184:187], v[192:195], v[50:53]
	v_mfma_f32_16x16x32_bf16 v[50:53], v[188:191], v[196:199], v[50:53]
	v_mfma_f32_16x16x32_bf16 v[34:37], v[184:187], v[200:203], v[34:37]
	v_mfma_f32_16x16x32_bf16 v[34:37], v[188:191], v[204:207], v[34:37]
	v_mfma_f32_16x16x32_bf16 v[38:41], v[176:179], v[200:203], v[38:41]
	v_mfma_f32_16x16x32_bf16 v[38:41], v[180:183], v[204:207], v[38:41]
	v_mfma_f32_16x16x32_bf16 v[22:25], v[176:179], v[208:211], v[22:25]
	v_mfma_f32_16x16x32_bf16 v[22:25], v[180:183], v[212:215], v[22:25]
	v_mfma_f32_16x16x32_bf16 v[18:21], v[184:187], v[208:211], v[18:21]
	v_mfma_f32_16x16x32_bf16 v[18:21], v[188:191], v[212:215], v[18:21]
	v_mfma_f32_16x16x32_bf16 v[2:5], v[184:187], v[216:219], v[2:5]
	v_mfma_f32_16x16x32_bf16 v[2:5], v[188:191], v[220:223], v[2:5]
	v_mfma_f32_16x16x32_bf16 v[6:9], v[176:179], v[216:219], v[6:9]
	v_mfma_f32_16x16x32_bf16 v[6:9], v[180:183], v[220:223], v[6:9]
	s_barrier
	s_setprio 0
	s_add_i32 s84, 0, 0x18000
	v_add_u32_e32 v163, s84, v157
	s_add_i32 s85, 0, 0x1c000
	ds_read_b128 v[130:133], v163
	ds_read_b128 v[164:167], v163 offset:1024
	ds_read_b128 v[168:171], v163 offset:2048
	ds_read_b128 v[172:175], v163 offset:3072
	v_add_u32_e32 v163, s85, v157
	ds_read_b128 v[176:179], v163
	ds_read_b128 v[180:183], v163 offset:1024
	ds_read_b128 v[184:187], v163 offset:2048
	ds_read_b128 v[188:191], v163 offset:3072
	s_add_u32 s36, s36, 0x100000
	s_addc_u32 s37, s37, 0
	s_mov_b32 m0, s54
	v_lshl_add_u64 v[230:231], s[36:37], 0, v[134:135]
	ds_read_b128 v[192:195], v159 offset:32768
	ds_read_b128 v[196:199], v159 offset:33792
	ds_read_b128 v[200:203], v159 offset:34816
	ds_read_b128 v[204:207], v159 offset:35840
	ds_read_b128 v[208:211], v159 offset:36864
	ds_read_b128 v[212:215], v159 offset:37888
	ds_read_b128 v[216:219], v159 offset:38912
	ds_read_b128 v[220:223], v159 offset:39936
	global_load_lds_dwordx4 v[230:231], off
	v_lshl_add_u64 v[230:231], s[36:37], 0, v[138:139]
	s_mov_b32 m0, s55
	s_nop 0
	global_load_lds_dwordx4 v[230:231], off
	s_waitcnt vmcnt(8)
	s_waitcnt lgkmcnt(0)
	s_barrier
	s_setprio 3
	v_mfma_f32_16x16x32_bf16 v[126:129], v[130:133], v[192:195], v[126:129]
	v_mfma_f32_16x16x32_bf16 v[126:129], v[164:167], v[196:199], v[126:129]
	v_mfma_f32_16x16x32_bf16 v[122:125], v[168:171], v[192:195], v[122:125]
	v_mfma_f32_16x16x32_bf16 v[122:125], v[172:175], v[196:199], v[122:125]
	v_mfma_f32_16x16x32_bf16 v[106:109], v[168:171], v[200:203], v[106:109]
	v_mfma_f32_16x16x32_bf16 v[106:109], v[172:175], v[204:207], v[106:109]
	v_mfma_f32_16x16x32_bf16 v[110:113], v[130:133], v[200:203], v[110:113]
	v_mfma_f32_16x16x32_bf16 v[110:113], v[164:167], v[204:207], v[110:113]
	v_mfma_f32_16x16x32_bf16 v[94:97], v[130:133], v[208:211], v[94:97]
	v_mfma_f32_16x16x32_bf16 v[94:97], v[164:167], v[212:215], v[94:97]
	v_mfma_f32_16x16x32_bf16 v[90:93], v[168:171], v[208:211], v[90:93]
	v_mfma_f32_16x16x32_bf16 v[90:93], v[172:175], v[212:215], v[90:93]
	v_mfma_f32_16x16x32_bf16 v[74:77], v[168:171], v[216:219], v[74:77]
	v_mfma_f32_16x16x32_bf16 v[74:77], v[172:175], v[220:223], v[74:77]
	v_mfma_f32_16x16x32_bf16 v[78:81], v[130:133], v[216:219], v[78:81]
	v_mfma_f32_16x16x32_bf16 v[78:81], v[164:167], v[220:223], v[78:81]
	v_mfma_f32_16x16x32_bf16 v[118:121], v[176:179], v[192:195], v[118:121]
	v_mfma_f32_16x16x32_bf16 v[118:121], v[180:183], v[196:199], v[118:121]
	v_mfma_f32_16x16x32_bf16 v[114:117], v[184:187], v[192:195], v[114:117]
	v_mfma_f32_16x16x32_bf16 v[114:117], v[188:191], v[196:199], v[114:117]
	v_mfma_f32_16x16x32_bf16 v[98:101], v[184:187], v[200:203], v[98:101]
	v_mfma_f32_16x16x32_bf16 v[98:101], v[188:191], v[204:207], v[98:101]
	v_mfma_f32_16x16x32_bf16 v[102:105], v[176:179], v[200:203], v[102:105]
	v_mfma_f32_16x16x32_bf16 v[102:105], v[180:183], v[204:207], v[102:105]
	v_mfma_f32_16x16x32_bf16 v[86:89], v[176:179], v[208:211], v[86:89]
	v_mfma_f32_16x16x32_bf16 v[86:89], v[180:183], v[212:215], v[86:89]
	v_mfma_f32_16x16x32_bf16 v[82:85], v[184:187], v[208:211], v[82:85]
	v_mfma_f32_16x16x32_bf16 v[82:85], v[188:191], v[212:215], v[82:85]
	v_mfma_f32_16x16x32_bf16 v[66:69], v[184:187], v[216:219], v[66:69]
	v_mfma_f32_16x16x32_bf16 v[66:69], v[188:191], v[220:223], v[66:69]
	v_mfma_f32_16x16x32_bf16 v[70:73], v[176:179], v[216:219], v[70:73]
	v_mfma_f32_16x16x32_bf16 v[70:73], v[180:183], v[220:223], v[70:73]
	s_barrier
; #define PG8_STAGE(bufoff, gbase, voff) do { _Pragma("unroll") for (int _i = 0; _i < 2; ++_i) \
;         __builtin_amdgcn_global_load_lds((const unsigned*)((const char*)(gbase) + (voff)[_i]), (PG8_LAS unsigned*)(lds + (bufoff) + ldsw + _i * 8192), 16, 0, 0); } while (0)
; #define PG8_LDA(dst, b, h) do { _Pragma("unroll") for (int m = 0; m < 4; ++m) _Pragma("unroll") for (int k = 0; k < 2; ++k) dst[m][k] = *(const PG8_LAS bf16x8*)(lds + PG8_SA(b, h) + aoff + m * 2048 + k * 1024); } while (0)
; #define PG8_MMA(ai, bj, At, Bt) do { __builtin_amdgcn_s_setprio(3); _Pragma("unroll") for (int m = 0; m < 4; ++m) _Pragma("unroll") for (int n = 0; n < 2; ++n) _Pragma("unroll") for (int k = 0; k < 2; ++k) \
;         acc[ai][bj][m][n] = __builtin_amdgcn_mfma_f32_16x16x32_bf16(Bt[n][k], At[m][k], acc[ai][bj][m][n], 0, 0, 0); __builtin_amdgcn_s_setprio(0); } while (0)
; #define PG8_WAIT_V(n) asm volatile("s_waitcnt vmcnt(" #n ")" ::: "memory")
; #define PG8_WAIT_L(n) asm volatile("s_waitcnt lgkmcnt(" #n ")" ::: "memory")
; #define PG8_BAR __builtin_amdgcn_s_barrier()
; #define PG8_SCHED __builtin_amdgcn_sched_barrier(0)
; template <class Epi, class Sched, bool ALIGN_EPI = false, bool SP2 = false>
; __device__ __forceinline__ void gemm_phase(PG8_LAS unsigned char* lds, const Gemm g, const Sched& S, const Epi& E) {
;     ...
;         for (int t = 0; t < nt; t += 2) {
;     ...
;             PG8_LDA(At, 1, 1); PG8_STAGE(PG8_SB(1, 0), b3, voffB); PG8_STAGE(PG8_SB(1, 1), b3 + hstepB, voffB); PG8_STAGE(PG8_SA(1, 0), a3, voffA);
;             PG8_WAIT_V(8); PG8_WAIT_L(0); PG8_BAR; PG8_MMA(1, 0, At, B0); PG8_MMA(1, 1, At, B1); PG8_BAR; PG8_SCHED;
	s_setprio 0
	s_add_i32 s36, s84, s33
	v_lshl_add_u64 v[160:161], v[160:161], 0, s[10:11]
	s_mov_b32 m0, s36
	ds_read_b128 v[192:195], v159 offset:49152
	ds_read_b128 v[196:199], v159 offset:50176
	ds_read_b128 v[200:203], v159 offset:51200
	ds_read_b128 v[204:207], v159 offset:52224
	ds_read_b128 v[208:211], v159 offset:53248
	ds_read_b128 v[212:215], v159 offset:54272
	ds_read_b128 v[216:219], v159 offset:55296
	ds_read_b128 v[220:223], v159 offset:56320
	global_load_lds_dwordx4 v[160:161], off
	s_add_i32 m0, s36, 0x2000
	s_add_u32 s0, s0, 0x100080
	v_lshl_add_u64 v[160:161], v[224:225], 0, s[10:11]
	s_addc_u32 s1, s1, 0
	s_add_i32 s36, s85, s33
	global_load_lds_dwordx4 v[160:161], off
	v_lshl_add_u64 v[160:161], s[0:1], 0, v[136:137]
	s_mov_b32 m0, s36
	s_nop 0
	global_load_lds_dwordx4 v[160:161], off
	v_lshl_add_u64 v[160:161], s[0:1], 0, v[140:141]
	s_add_i32 m0, s36, 0x2000
	s_nop 0
	global_load_lds_dwordx4 v[160:161], off
	v_lshl_add_u64 v[160:161], v[226:227], 0, s[10:11]
	s_mov_b32 m0, s61
	s_nop 0
	global_load_lds_dwordx4 v[160:161], off
	v_lshl_add_u64 v[160:161], v[228:229], 0, s[10:11]
	s_mov_b32 m0, s62
	s_nop 0
	global_load_lds_dwordx4 v[160:161], off
	s_waitcnt vmcnt(8)
	s_waitcnt lgkmcnt(0)
	s_barrier
	s_setprio 3
	v_mfma_f32_16x16x32_bf16 v[62:65], v[130:133], v[192:195], v[62:65]
	v_mfma_f32_16x16x32_bf16 v[62:65], v[164:167], v[196:199], v[62:65]
	v_mfma_f32_16x16x32_bf16 v[58:61], v[168:171], v[192:195], v[58:61]
	v_mfma_f32_16x16x32_bf16 v[58:61], v[172:175], v[196:199], v[58:61]
	v_mfma_f32_16x16x32_bf16 v[42:45], v[168:171], v[200:203], v[42:45]
	v_mfma_f32_16x16x32_bf16 v[42:45], v[172:175], v[204:207], v[42:45]
	v_mfma_f32_16x16x32_bf16 v[46:49], v[130:133], v[200:203], v[46:49]
	v_mfma_f32_16x16x32_bf16 v[46:49], v[164:167], v[204:207], v[46:49]
	v_mfma_f32_16x16x32_bf16 v[30:33], v[130:133], v[208:211], v[30:33]
	v_mfma_f32_16x16x32_bf16 v[30:33], v[164:167], v[212:215], v[30:33]
	v_mfma_f32_16x16x32_bf16 v[26:29], v[168:171], v[208:211], v[26:29]
	v_mfma_f32_16x16x32_bf16 v[26:29], v[172:175], v[212:215], v[26:29]
	v_mfma_f32_16x16x32_bf16 v[10:13], v[168:171], v[216:219], v[10:13]
	v_mfma_f32_16x16x32_bf16 v[10:13], v[172:175], v[220:223], v[10:13]
	v_mfma_f32_16x16x32_bf16 v[14:17], v[130:133], v[216:219], v[14:17]
	v_mfma_f32_16x16x32_bf16 v[14:17], v[164:167], v[220:223], v[14:17]
	v_mfma_f32_16x16x32_bf16 v[54:57], v[176:179], v[192:195], v[54:57]
	v_mfma_f32_16x16x32_bf16 v[54:57], v[180:183], v[196:199], v[54:57]
	v_mfma_f32_16x16x32_bf16 v[50:53], v[184:187], v[192:195], v[50:53]
	v_mfma_f32_16x16x32_bf16 v[50:53], v[188:191], v[196:199], v[50:53]
	v_mfma_f32_16x16x32_bf16 v[34:37], v[184:187], v[200:203], v[34:37]
	v_mfma_f32_16x16x32_bf16 v[34:37], v[188:191], v[204:207], v[34:37]
	v_mfma_f32_16x16x32_bf16 v[38:41], v[176:179], v[200:203], v[38:41]
	v_mfma_f32_16x16x32_bf16 v[38:41], v[180:183], v[204:207], v[38:41]
	v_mfma_f32_16x16x32_bf16 v[22:25], v[176:179], v[208:211], v[22:25]
	v_mfma_f32_16x16x32_bf16 v[22:25], v[180:183], v[212:215], v[22:25]
	v_mfma_f32_16x16x32_bf16 v[18:21], v[184:187], v[208:211], v[18:21]
	v_mfma_f32_16x16x32_bf16 v[18:21], v[188:191], v[212:215], v[18:21]
	v_mfma_f32_16x16x32_bf16 v[2:5], v[184:187], v[216:219], v[2:5]
	v_mfma_f32_16x16x32_bf16 v[2:5], v[188:191], v[220:223], v[2:5]
	v_mfma_f32_16x16x32_bf16 v[6:9], v[176:179], v[216:219], v[6:9]
	v_mfma_f32_16x16x32_bf16 v[6:9], v[180:183], v[220:223], v[6:9]
	s_barrier
	s_setprio 0
	s_add_i32 s83, s83, 2
	s_add_u32 s30, s30, 0x100
	s_addc_u32 s31, s31, 0
	s_cmp_gt_u32 s83, 61
	s_cbranch_scc1 .LBB0_730

; #define PG8_STAGE(bufoff, gbase, voff) do { _Pragma("unroll") for (int _i = 0; _i < 2; ++_i) \
;         __builtin_amdgcn_global_load_lds((const unsigned*)((const char*)(gbase) + (voff)[_i]), (PG8_LAS unsigned*)(lds + (bufoff) + ldsw + _i * 8192), 16, 0, 0); } while (0)
; #define PG8_LDA(dst, b, h) do { _Pragma("unroll") for (int m = 0; m < 4; ++m) _Pragma("unroll") for (int k = 0; k < 2; ++k) dst[m][k] = *(const PG8_LAS bf16x8*)(lds + PG8_SA(b, h) + aoff + m * 2048 + k * 1024); } while (0)
; #define PG8_LDB(dst, b, h) do { _Pragma("unroll") for (int n = 0; n < 2; ++n) _Pragma("unroll") for (int k = 0; k < 2; ++k) dst[n][k] = *(const PG8_LAS bf16x8*)(lds + PG8_SB(b, h) + boff + n * 2048 + k * 1024); } while (0)
; #define PG8_MMA(ai, bj, At, Bt) do { __builtin_amdgcn_s_setprio(3); _Pragma("unroll") for (int m = 0; m < 4; ++m) _Pragma("unroll") for (int n = 0; n < 2; ++n) _Pragma("unroll") for (int k = 0; k < 2; ++k) \
;         acc[ai][bj][m][n] = __builtin_amdgcn_mfma_f32_16x16x32_bf16(Bt[n][k], At[m][k], acc[ai][bj][m][n], 0, 0, 0); __builtin_amdgcn_s_setprio(0); } while (0)
; #define PG8_WAIT_V(n) asm volatile("s_waitcnt vmcnt(" #n ")" ::: "memory")
; #define PG8_WAIT_L(n) asm volatile("s_waitcnt lgkmcnt(" #n ")" ::: "memory")
; #define PG8_BAR __builtin_amdgcn_s_barrier()
; #define PG8_SCHED __builtin_amdgcn_sched_barrier(0)
; template <class Epi, class Sched, bool ALIGN_EPI = false, bool SP2 = false>
; __device__ __forceinline__ void gemm_phase(PG8_LAS unsigned char* lds, const Gemm g, const Sched& S, const Epi& E) {
;     ...
;             const char* a1 = cA + (size_t)(t + 1) * kstep;
;             const char* a2 = last ? nA : cA + (size_t)(t + 2) * kstep; const char* b2 = last ? nB : cB + (size_t)(t + 2) * kstep;
;             const char* a3 = a2 + kstep; const char* b3 = b2 + kstep;
;             if (last && has_next) S.a_ready(nxt);
;             if constexpr (Epi::MIDK) { if (t == E.midk_step(nt)) E.midk(acc, cur, wr, wc, fr, fq); }
;             if constexpr (SP2) {
;             PG8_LDB(B0, 0, 0); PG8_LDB(B1, 0, 1); PG8_SCHED; PG8_LDA(At, 0, 0); PG8_STAGE(PG8_SA(1, 1), a1 + hstepA, voffA);
;             PG8_WAIT_V(8); PG8_WAIT_L(0); PG8_BAR; PG8_MMA(0, 0, At, B0); PG8_MMA(0, 1, At, B1); PG8_BAR; PG8_SCHED;
;             PG8_LDA(At, 0, 1); PG8_STAGE(PG8_SB(0, 0), b2, voffB); PG8_STAGE(PG8_SB(0, 1), b2 + hstepB, voffB); PG8_STAGE(PG8_SA(0, 0), a2, voffA);
.LBB0_808:
	v_add_u32_e32 v3, s65, v186
	ds_read_b128 v[134:137], v3
	ds_read_b128 v[138:141], v3 offset:1024
	ds_read_b128 v[142:145], v3 offset:2048
	ds_read_b128 v[146:149], v3 offset:3072
	v_add_u32_e32 v3, s66, v186
	s_add_u32 s36, s28, s30
	ds_read_b128 v[150:153], v3
	ds_read_b128 v[154:157], v3 offset:1024
	ds_read_b128 v[158:161], v3 offset:2048
	ds_read_b128 v[190:193], v3 offset:3072
	s_addc_u32 s37, s29, s31
	s_add_u32 s36, s36, 0x100
	s_addc_u32 s37, s37, 0
	s_add_u32 s86, s83, s30
	s_addc_u32 s87, s84, s31
	s_cmpk_eq_i32 s30, 0x1f00
	s_cselect_b32 s41, s23, s37
	s_cselect_b32 s40, s75, s36
	s_cselect_b32 s37, s77, s87
	s_cselect_b32 s36, s78, s86
	v_lshl_add_u64 v[4:5], v[180:181], 0, s[30:31]
	s_add_i32 m0, s42, 0xc000
	ds_read_b128 v[194:197], v188
	ds_read_b128 v[198:201], v188 offset:1024
	ds_read_b128 v[202:205], v188 offset:2048
	ds_read_b128 v[206:209], v188 offset:3072
	ds_read_b128 v[210:213], v188 offset:4096
	ds_read_b128 v[214:217], v188 offset:5120
	ds_read_b128 v[218:221], v188 offset:6144
	ds_read_b128 v[222:225], v188 offset:7168
	global_load_lds_dwordx4 v[4:5], off
	v_lshl_add_u64 v[4:5], v[182:183], 0, s[30:31]
	s_add_i32 m0, s42, 0xe000
	s_nop 0
	global_load_lds_dwordx4 v[4:5], off
	s_waitcnt vmcnt(8)
	s_waitcnt lgkmcnt(0)
	s_barrier
	s_setprio 3
	v_mfma_f32_16x16x32_bf16 v[130:133], v[134:137], v[194:197], v[130:133]
	v_mfma_f32_16x16x32_bf16 v[130:133], v[138:141], v[198:201], v[130:133]
	v_mfma_f32_16x16x32_bf16 v[126:129], v[142:145], v[194:197], v[126:129]
	v_mfma_f32_16x16x32_bf16 v[126:129], v[146:149], v[198:201], v[126:129]
	v_mfma_f32_16x16x32_bf16 v[110:113], v[142:145], v[202:205], v[110:113]
	v_mfma_f32_16x16x32_bf16 v[110:113], v[146:149], v[206:209], v[110:113]
	v_mfma_f32_16x16x32_bf16 v[114:117], v[134:137], v[202:205], v[114:117]
	v_mfma_f32_16x16x32_bf16 v[114:117], v[138:141], v[206:209], v[114:117]
	v_mfma_f32_16x16x32_bf16 v[98:101], v[134:137], v[210:213], v[98:101]
	v_mfma_f32_16x16x32_bf16 v[98:101], v[138:141], v[214:217], v[98:101]
	v_mfma_f32_16x16x32_bf16 v[94:97], v[142:145], v[210:213], v[94:97]
	v_mfma_f32_16x16x32_bf16 v[94:97], v[146:149], v[214:217], v[94:97]
	v_mfma_f32_16x16x32_bf16 v[78:81], v[142:145], v[218:221], v[78:81]
	v_mfma_f32_16x16x32_bf16 v[78:81], v[146:149], v[222:225], v[78:81]
	v_mfma_f32_16x16x32_bf16 v[82:85], v[134:137], v[218:221], v[82:85]
	v_mfma_f32_16x16x32_bf16 v[82:85], v[138:141], v[222:225], v[82:85]
	v_mfma_f32_16x16x32_bf16 v[122:125], v[150:153], v[194:197], v[122:125]
	v_mfma_f32_16x16x32_bf16 v[122:125], v[154:157], v[198:201], v[122:125]
	v_mfma_f32_16x16x32_bf16 v[118:121], v[158:161], v[194:197], v[118:121]
	v_mfma_f32_16x16x32_bf16 v[118:121], v[190:193], v[198:201], v[118:121]
	v_mfma_f32_16x16x32_bf16 v[102:105], v[158:161], v[202:205], v[102:105]
	v_mfma_f32_16x16x32_bf16 v[102:105], v[190:193], v[206:209], v[102:105]
	v_mfma_f32_16x16x32_bf16 v[106:109], v[150:153], v[202:205], v[106:109]
	v_mfma_f32_16x16x32_bf16 v[106:109], v[154:157], v[206:209], v[106:109]
	v_mfma_f32_16x16x32_bf16 v[90:93], v[150:153], v[210:213], v[90:93]
	v_mfma_f32_16x16x32_bf16 v[90:93], v[154:157], v[214:217], v[90:93]
	v_mfma_f32_16x16x32_bf16 v[86:89], v[158:161], v[210:213], v[86:89]
	v_mfma_f32_16x16x32_bf16 v[86:89], v[190:193], v[214:217], v[86:89]
	v_mfma_f32_16x16x32_bf16 v[70:73], v[158:161], v[218:221], v[70:73]
	v_mfma_f32_16x16x32_bf16 v[70:73], v[190:193], v[222:225], v[70:73]
	v_mfma_f32_16x16x32_bf16 v[74:77], v[150:153], v[218:221], v[74:77]
	v_mfma_f32_16x16x32_bf16 v[74:77], v[154:157], v[222:225], v[74:77]
	s_barrier
	s_setprio 0
	s_add_i32 s86, s65, s33
	v_lshl_add_u64 v[226:227], s[36:37], 0, v[166:167]
	s_mov_b32 m0, s86
	ds_read_b128 v[194:197], v188 offset:16384
	ds_read_b128 v[198:201], v188 offset:17408
	ds_read_b128 v[202:205], v188 offset:18432
	ds_read_b128 v[206:209], v188 offset:19456
	ds_read_b128 v[210:213], v188 offset:20480
	ds_read_b128 v[214:217], v188 offset:21504
	ds_read_b128 v[218:221], v188 offset:22528
	ds_read_b128 v[222:225], v188 offset:23552
	global_load_lds_dwordx4 v[226:227], off
	s_add_i32 m0, s86, 0x2000
	s_add_u32 s86, s36, 0x100000
	v_lshl_add_u64 v[228:229], s[36:37], 0, v[170:171]
	s_addc_u32 s87, s37, 0
	s_add_i32 s88, s66, s33
	global_load_lds_dwordx4 v[228:229], off
	v_lshl_add_u64 v[4:5], s[86:87], 0, v[166:167]
	s_mov_b32 m0, s88
	v_lshl_add_u64 v[230:231], s[40:41], 0, v[164:165]
	global_load_lds_dwordx4 v[4:5], off
	v_lshl_add_u64 v[4:5], s[86:87], 0, v[170:171]
	s_add_i32 m0, s88, 0x2000
	v_lshl_add_u64 v[232:233], s[40:41], 0, v[168:169]
	global_load_lds_dwordx4 v[4:5], off
	s_mov_b32 m0, s42
	s_nop 0
	global_load_lds_dwordx4 v[230:231], off
	s_mov_b32 m0, s43
	s_nop 0
	global_load_lds_dwordx4 v[232:233], off
	s_waitcnt vmcnt(8)
	s_waitcnt lgkmcnt(0)
	s_barrier
; #define PG8_STAGE(bufoff, gbase, voff) do { _Pragma("unroll") for (int _i = 0; _i < 2; ++_i) \
;         __builtin_amdgcn_global_load_lds((const unsigned*)((const char*)(gbase) + (voff)[_i]), (PG8_LAS unsigned*)(lds + (bufoff) + ldsw + _i * 8192), 16, 0, 0); } while (0)
; #define PG8_LDA(dst, b, h) do { _Pragma("unroll") for (int m = 0; m < 4; ++m) _Pragma("unroll") for (int k = 0; k < 2; ++k) dst[m][k] = *(const PG8_LAS bf16x8*)(lds + PG8_SA(b, h) + aoff + m * 2048 + k * 1024); } while (0)
; #define PG8_LDB(dst, b, h) do { _Pragma("unroll") for (int n = 0; n < 2; ++n) _Pragma("unroll") for (int k = 0; k < 2; ++k) dst[n][k] = *(const PG8_LAS bf16x8*)(lds + PG8_SB(b, h) + boff + n * 2048 + k * 1024); } while (0)
; #define PG8_MMA(ai, bj, At, Bt) do { __builtin_amdgcn_s_setprio(3); _Pragma("unroll") for (int m = 0; m < 4; ++m) _Pragma("unroll") for (int n = 0; n < 2; ++n) _Pragma("unroll") for (int k = 0; k < 2; ++k) \
;         acc[ai][bj][m][n] = __builtin_amdgcn_mfma_f32_16x16x32_bf16(Bt[n][k], At[m][k], acc[ai][bj][m][n], 0, 0, 0); __builtin_amdgcn_s_setprio(0); } while (0)
; #define PG8_WAIT_V(n) asm volatile("s_waitcnt vmcnt(" #n ")" ::: "memory")
; #define PG8_WAIT_L(n) asm volatile("s_waitcnt lgkmcnt(" #n ")" ::: "memory")
; #define PG8_BAR __builtin_amdgcn_s_barrier()
; #define PG8_SCHED __builtin_amdgcn_sched_barrier(0)
; template <class Epi, class Sched, bool ALIGN_EPI = false, bool SP2 = false>
; __device__ __forceinline__ void gemm_phase(PG8_LAS unsigned char* lds, const Gemm g, const Sched& S, const Epi& E) {
;     ...
;             PG8_WAIT_V(8); PG8_WAIT_L(0); PG8_BAR; PG8_MMA(1, 0, At, B0); PG8_MMA(1, 1, At, B1); PG8_BAR; PG8_SCHED;
;             PG8_LDB(B0, 1, 0); PG8_LDB(B1, 1, 1); PG8_SCHED; PG8_LDA(At, 1, 0); PG8_STAGE(PG8_SA(0, 1), a2 + hstepA, voffA);
;             PG8_WAIT_V(8); PG8_WAIT_L(0); PG8_BAR; PG8_MMA(0, 0, At, B0); PG8_MMA(0, 1, At, B1); PG8_BAR; PG8_SCHED;
	s_setprio 3
	v_mfma_f32_16x16x32_bf16 v[66:69], v[134:137], v[194:197], v[66:69]
	v_mfma_f32_16x16x32_bf16 v[66:69], v[138:141], v[198:201], v[66:69]
	v_mfma_f32_16x16x32_bf16 v[62:65], v[142:145], v[194:197], v[62:65]
	v_mfma_f32_16x16x32_bf16 v[62:65], v[146:149], v[198:201], v[62:65]
	v_mfma_f32_16x16x32_bf16 v[46:49], v[142:145], v[202:205], v[46:49]
	v_mfma_f32_16x16x32_bf16 v[46:49], v[146:149], v[206:209], v[46:49]
	v_mfma_f32_16x16x32_bf16 v[50:53], v[134:137], v[202:205], v[50:53]
	v_mfma_f32_16x16x32_bf16 v[50:53], v[138:141], v[206:209], v[50:53]
	v_mfma_f32_16x16x32_bf16 v[34:37], v[134:137], v[210:213], v[34:37]
	v_mfma_f32_16x16x32_bf16 v[34:37], v[138:141], v[214:217], v[34:37]
	v_mfma_f32_16x16x32_bf16 v[30:33], v[142:145], v[210:213], v[30:33]
	v_mfma_f32_16x16x32_bf16 v[30:33], v[146:149], v[214:217], v[30:33]
	v_mfma_f32_16x16x32_bf16 v[14:17], v[142:145], v[218:221], v[14:17]
	v_mfma_f32_16x16x32_bf16 v[14:17], v[146:149], v[222:225], v[14:17]
	v_mfma_f32_16x16x32_bf16 v[18:21], v[134:137], v[218:221], v[18:21]
	v_mfma_f32_16x16x32_bf16 v[18:21], v[138:141], v[222:225], v[18:21]
	v_mfma_f32_16x16x32_bf16 v[58:61], v[150:153], v[194:197], v[58:61]
	v_mfma_f32_16x16x32_bf16 v[58:61], v[154:157], v[198:201], v[58:61]
	v_mfma_f32_16x16x32_bf16 v[54:57], v[158:161], v[194:197], v[54:57]
	v_mfma_f32_16x16x32_bf16 v[54:57], v[190:193], v[198:201], v[54:57]
	v_mfma_f32_16x16x32_bf16 v[38:41], v[158:161], v[202:205], v[38:41]
	v_mfma_f32_16x16x32_bf16 v[38:41], v[190:193], v[206:209], v[38:41]
	v_mfma_f32_16x16x32_bf16 v[42:45], v[150:153], v[202:205], v[42:45]
	v_mfma_f32_16x16x32_bf16 v[42:45], v[154:157], v[206:209], v[42:45]
	v_mfma_f32_16x16x32_bf16 v[26:29], v[150:153], v[210:213], v[26:29]
	v_mfma_f32_16x16x32_bf16 v[26:29], v[154:157], v[214:217], v[26:29]
	v_mfma_f32_16x16x32_bf16 v[22:25], v[158:161], v[210:213], v[22:25]
	v_mfma_f32_16x16x32_bf16 v[22:25], v[190:193], v[214:217], v[22:25]
	v_mfma_f32_16x16x32_bf16 v[4:7], v[158:161], v[218:221], v[6:9]
	v_mfma_f32_16x16x32_bf16 v[4:7], v[190:193], v[222:225], v[4:7]
	v_mfma_f32_16x16x32_bf16 v[10:13], v[150:153], v[218:221], v[10:13]
	v_mfma_f32_16x16x32_bf16 v[10:13], v[154:157], v[222:225], v[10:13]
	s_barrier
	s_setprio 0
	s_add_i32 s86, 0, 0x18000
	v_add_u32_e32 v3, s86, v186
	s_add_i32 s87, 0, 0x1c000
	ds_read_b128 v[134:137], v3
	ds_read_b128 v[138:141], v3 offset:1024
	ds_read_b128 v[142:145], v3 offset:2048
	ds_read_b128 v[146:149], v3 offset:3072
	v_add_u32_e32 v3, s87, v186
	ds_read_b128 v[150:153], v3
	ds_read_b128 v[154:157], v3 offset:1024
	ds_read_b128 v[158:161], v3 offset:2048
	ds_read_b128 v[190:193], v3 offset:3072
	s_add_u32 s40, s40, 0x100000
	s_addc_u32 s41, s41, 0
	s_mov_b32 m0, s44
	v_lshl_add_u64 v[8:9], s[40:41], 0, v[164:165]
	ds_read_b128 v[194:197], v188 offset:32768
	ds_read_b128 v[198:201], v188 offset:33792
	ds_read_b128 v[202:205], v188 offset:34816
	ds_read_b128 v[206:209], v188 offset:35840
	ds_read_b128 v[210:213], v188 offset:36864
	ds_read_b128 v[214:217], v188 offset:37888
	ds_read_b128 v[218:221], v188 offset:38912
	ds_read_b128 v[222:225], v188 offset:39936
	global_load_lds_dwordx4 v[8:9], off
	v_lshl_add_u64 v[8:9], s[40:41], 0, v[168:169]
	s_mov_b32 m0, s45
	s_nop 0
	global_load_lds_dwordx4 v[8:9], off
	s_waitcnt vmcnt(8)
	s_waitcnt lgkmcnt(0)
	s_barrier
	s_setprio 3
	v_mfma_f32_16x16x32_bf16 v[130:133], v[134:137], v[194:197], v[130:133]
	v_mfma_f32_16x16x32_bf16 v[130:133], v[138:141], v[198:201], v[130:133]
	v_mfma_f32_16x16x32_bf16 v[126:129], v[142:145], v[194:197], v[126:129]
	v_mfma_f32_16x16x32_bf16 v[126:129], v[146:149], v[198:201], v[126:129]
	v_mfma_f32_16x16x32_bf16 v[110:113], v[142:145], v[202:205], v[110:113]
	v_mfma_f32_16x16x32_bf16 v[110:113], v[146:149], v[206:209], v[110:113]
	v_mfma_f32_16x16x32_bf16 v[114:117], v[134:137], v[202:205], v[114:117]
	v_mfma_f32_16x16x32_bf16 v[114:117], v[138:141], v[206:209], v[114:117]
	v_mfma_f32_16x16x32_bf16 v[98:101], v[134:137], v[210:213], v[98:101]
	v_mfma_f32_16x16x32_bf16 v[98:101], v[138:141], v[214:217], v[98:101]
	v_mfma_f32_16x16x32_bf16 v[94:97], v[142:145], v[210:213], v[94:97]
	v_mfma_f32_16x16x32_bf16 v[94:97], v[146:149], v[214:217], v[94:97]
	v_mfma_f32_16x16x32_bf16 v[78:81], v[142:145], v[218:221], v[78:81]
	v_mfma_f32_16x16x32_bf16 v[78:81], v[146:149], v[222:225], v[78:81]
	v_mfma_f32_16x16x32_bf16 v[82:85], v[134:137], v[218:221], v[82:85]
	v_mfma_f32_16x16x32_bf16 v[82:85], v[138:141], v[222:225], v[82:85]
	v_mfma_f32_16x16x32_bf16 v[122:125], v[150:153], v[194:197], v[122:125]
	v_mfma_f32_16x16x32_bf16 v[122:125], v[154:157], v[198:201], v[122:125]
	v_mfma_f32_16x16x32_bf16 v[118:121], v[158:161], v[194:197], v[118:121]
	v_mfma_f32_16x16x32_bf16 v[118:121], v[190:193], v[198:201], v[118:121]
	v_mfma_f32_16x16x32_bf16 v[102:105], v[158:161], v[202:205], v[102:105]
	v_mfma_f32_16x16x32_bf16 v[102:105], v[190:193], v[206:209], v[102:105]
	v_mfma_f32_16x16x32_bf16 v[106:109], v[150:153], v[202:205], v[106:109]
	v_mfma_f32_16x16x32_bf16 v[106:109], v[154:157], v[206:209], v[106:109]
	v_mfma_f32_16x16x32_bf16 v[90:93], v[150:153], v[210:213], v[90:93]
	v_mfma_f32_16x16x32_bf16 v[90:93], v[154:157], v[214:217], v[90:93]
	v_mfma_f32_16x16x32_bf16 v[86:89], v[158:161], v[210:213], v[86:89]
	v_mfma_f32_16x16x32_bf16 v[86:89], v[190:193], v[214:217], v[86:89]
	v_mfma_f32_16x16x32_bf16 v[70:73], v[158:161], v[218:221], v[70:73]
	v_mfma_f32_16x16x32_bf16 v[70:73], v[190:193], v[222:225], v[70:73]
	v_mfma_f32_16x16x32_bf16 v[74:77], v[150:153], v[218:221], v[74:77]
	v_mfma_f32_16x16x32_bf16 v[74:77], v[154:157], v[222:225], v[74:77]
	s_barrier
; #define PG8_STAGE(bufoff, gbase, voff) do { _Pragma("unroll") for (int _i = 0; _i < 2; ++_i) \
;         __builtin_amdgcn_global_load_lds((const unsigned*)((const char*)(gbase) + (voff)[_i]), (PG8_LAS unsigned*)(lds + (bufoff) + ldsw + _i * 8192), 16, 0, 0); } while (0)
; #define PG8_LDA(dst, b, h) do { _Pragma("unroll") for (int m = 0; m < 4; ++m) _Pragma("unroll") for (int k = 0; k < 2; ++k) dst[m][k] = *(const PG8_LAS bf16x8*)(lds + PG8_SA(b, h) + aoff + m * 2048 + k * 1024); } while (0)
; #define PG8_MMA(ai, bj, At, Bt) do { __builtin_amdgcn_s_setprio(3); _Pragma("unroll") for (int m = 0; m < 4; ++m) _Pragma("unroll") for (int n = 0; n < 2; ++n) _Pragma("unroll") for (int k = 0; k < 2; ++k) \
;         acc[ai][bj][m][n] = __builtin_amdgcn_mfma_f32_16x16x32_bf16(Bt[n][k], At[m][k], acc[ai][bj][m][n], 0, 0, 0); __builtin_amdgcn_s_setprio(0); } while (0)
; #define PG8_WAIT_V(n) asm volatile("s_waitcnt vmcnt(" #n ")" ::: "memory")
; #define PG8_WAIT_L(n) asm volatile("s_waitcnt lgkmcnt(" #n ")" ::: "memory")
; #define PG8_BAR __builtin_amdgcn_s_barrier()
; #define PG8_SCHED __builtin_amdgcn_sched_barrier(0)
; template <class Epi, class Sched, bool ALIGN_EPI = false, bool SP2 = false>
; __device__ __forceinline__ void gemm_phase(PG8_LAS unsigned char* lds, const Gemm g, const Sched& S, const Epi& E) {
;     ...
;         for (int t = 0; t < nt; t += 2) {
;     ...
;             PG8_LDA(At, 1, 1); PG8_STAGE(PG8_SB(1, 0), b3, voffB); PG8_STAGE(PG8_SB(1, 1), b3 + hstepB, voffB); PG8_STAGE(PG8_SA(1, 0), a3, voffA);
;             PG8_WAIT_V(8); PG8_WAIT_L(0); PG8_BAR; PG8_MMA(1, 0, At, B0); PG8_MMA(1, 1, At, B1); PG8_BAR; PG8_SCHED;
	s_setprio 0
	s_add_i32 s40, s86, s33
	v_lshl_add_u64 v[8:9], v[226:227], 0, s[10:11]
	s_mov_b32 m0, s40
	ds_read_b128 v[194:197], v188 offset:49152
	ds_read_b128 v[198:201], v188 offset:50176
	ds_read_b128 v[202:205], v188 offset:51200
	ds_read_b128 v[206:209], v188 offset:52224
	ds_read_b128 v[210:213], v188 offset:53248
	ds_read_b128 v[214:217], v188 offset:54272
	ds_read_b128 v[218:221], v188 offset:55296
	ds_read_b128 v[222:225], v188 offset:56320
	global_load_lds_dwordx4 v[8:9], off
	s_add_i32 m0, s40, 0x2000
	s_add_u32 s36, s36, 0x100080
	v_lshl_add_u64 v[8:9], v[228:229], 0, s[10:11]
	s_addc_u32 s37, s37, 0
	s_add_i32 s40, s87, s33
	global_load_lds_dwordx4 v[8:9], off
	v_lshl_add_u64 v[8:9], s[36:37], 0, v[166:167]
	s_mov_b32 m0, s40
	s_nop 0
	global_load_lds_dwordx4 v[8:9], off
	v_lshl_add_u64 v[8:9], s[36:37], 0, v[170:171]
	s_add_i32 m0, s40, 0x2000
	s_nop 0
	global_load_lds_dwordx4 v[8:9], off
	v_lshl_add_u64 v[8:9], v[230:231], 0, s[10:11]
	s_mov_b32 m0, s60
	s_nop 0
	global_load_lds_dwordx4 v[8:9], off
	v_lshl_add_u64 v[8:9], v[232:233], 0, s[10:11]
	s_mov_b32 m0, s61
	s_nop 0
	global_load_lds_dwordx4 v[8:9], off
	s_waitcnt vmcnt(8)
	s_waitcnt lgkmcnt(0)
	s_barrier
	s_setprio 3
	v_mfma_f32_16x16x32_bf16 v[66:69], v[134:137], v[194:197], v[66:69]
	v_mfma_f32_16x16x32_bf16 v[66:69], v[138:141], v[198:201], v[66:69]
	v_mfma_f32_16x16x32_bf16 v[62:65], v[142:145], v[194:197], v[62:65]
	v_mfma_f32_16x16x32_bf16 v[62:65], v[146:149], v[198:201], v[62:65]
	v_mfma_f32_16x16x32_bf16 v[46:49], v[142:145], v[202:205], v[46:49]
	v_mfma_f32_16x16x32_bf16 v[46:49], v[146:149], v[206:209], v[46:49]
	v_mfma_f32_16x16x32_bf16 v[50:53], v[134:137], v[202:205], v[50:53]
	v_mfma_f32_16x16x32_bf16 v[50:53], v[138:141], v[206:209], v[50:53]
	v_mfma_f32_16x16x32_bf16 v[34:37], v[134:137], v[210:213], v[34:37]
	v_mfma_f32_16x16x32_bf16 v[34:37], v[138:141], v[214:217], v[34:37]
	v_mfma_f32_16x16x32_bf16 v[30:33], v[142:145], v[210:213], v[30:33]
	v_mfma_f32_16x16x32_bf16 v[30:33], v[146:149], v[214:217], v[30:33]
	v_mfma_f32_16x16x32_bf16 v[14:17], v[142:145], v[218:221], v[14:17]
	v_mfma_f32_16x16x32_bf16 v[14:17], v[146:149], v[222:225], v[14:17]
	v_mfma_f32_16x16x32_bf16 v[18:21], v[134:137], v[218:221], v[18:21]
	v_mfma_f32_16x16x32_bf16 v[18:21], v[138:141], v[222:225], v[18:21]
	v_mfma_f32_16x16x32_bf16 v[58:61], v[150:153], v[194:197], v[58:61]
	v_mfma_f32_16x16x32_bf16 v[54:57], v[158:161], v[194:197], v[54:57]
	v_mfma_f32_16x16x32_bf16 v[42:45], v[150:153], v[202:205], v[42:45]
	v_mfma_f32_16x16x32_bf16 v[38:41], v[158:161], v[202:205], v[38:41]
	v_mfma_f32_16x16x32_bf16 v[26:29], v[150:153], v[210:213], v[26:29]
	v_mfma_f32_16x16x32_bf16 v[22:25], v[158:161], v[210:213], v[22:25]
	v_mfma_f32_16x16x32_bf16 v[8:11], v[150:153], v[218:221], v[10:13]
	v_mfma_f32_16x16x32_bf16 v[4:7], v[158:161], v[218:221], v[4:7]
	v_mfma_f32_16x16x32_bf16 v[58:61], v[154:157], v[198:201], v[58:61]
	v_mfma_f32_16x16x32_bf16 v[54:57], v[190:193], v[198:201], v[54:57]
	v_mfma_f32_16x16x32_bf16 v[42:45], v[154:157], v[206:209], v[42:45]
	v_mfma_f32_16x16x32_bf16 v[38:41], v[190:193], v[206:209], v[38:41]
	v_mfma_f32_16x16x32_bf16 v[26:29], v[154:157], v[214:217], v[26:29]
	v_mfma_f32_16x16x32_bf16 v[22:25], v[190:193], v[214:217], v[22:25]
	v_mfma_f32_16x16x32_bf16 v[10:13], v[154:157], v[222:225], v[8:11]
	v_mfma_f32_16x16x32_bf16 v[6:9], v[190:193], v[222:225], v[4:7]
	s_barrier
	s_setprio 0
	s_add_i32 s85, s85, 2
	s_add_u32 s30, s30, 0x100
	s_addc_u32 s31, s31, 0
	s_cmp_gt_u32 s85, 61
	s_cbranch_scc1 .LBB0_811

; #define PG8_STAGE(bufoff, gbase, voff) do { _Pragma("unroll") for (int _i = 0; _i < 2; ++_i) \
;         __builtin_amdgcn_global_load_lds((const unsigned*)((const char*)(gbase) + (voff)[_i]), (PG8_LAS unsigned*)(lds + (bufoff) + ldsw + _i * 8192), 16, 0, 0); } while (0)
; #define PG8_LDA(dst, b, h) do { _Pragma("unroll") for (int m = 0; m < 4; ++m) _Pragma("unroll") for (int k = 0; k < 2; ++k) dst[m][k] = *(const PG8_LAS bf16x8*)(lds + PG8_SA(b, h) + aoff + m * 2048 + k * 1024); } while (0)
; #define PG8_LDB(dst, b, h) do { _Pragma("unroll") for (int n = 0; n < 2; ++n) _Pragma("unroll") for (int k = 0; k < 2; ++k) dst[n][k] = *(const PG8_LAS bf16x8*)(lds + PG8_SB(b, h) + boff + n * 2048 + k * 1024); } while (0)
; #define PG8_MMA(ai, bj, At, Bt) do { __builtin_amdgcn_s_setprio(3); _Pragma("unroll") for (int m = 0; m < 4; ++m) _Pragma("unroll") for (int n = 0; n < 2; ++n) _Pragma("unroll") for (int k = 0; k < 2; ++k) \
;         acc[ai][bj][m][n] = __builtin_amdgcn_mfma_f32_16x16x32_bf16(Bt[n][k], At[m][k], acc[ai][bj][m][n], 0, 0, 0); __builtin_amdgcn_s_setprio(0); } while (0)
; #define PG8_WAIT_V(n) asm volatile("s_waitcnt vmcnt(" #n ")" ::: "memory")
; #define PG8_WAIT_L(n) asm volatile("s_waitcnt lgkmcnt(" #n ")" ::: "memory")
; #define PG8_BAR __builtin_amdgcn_s_barrier()
; #define PG8_SCHED __builtin_amdgcn_sched_barrier(0)
; template <class Epi, class Sched, bool ALIGN_EPI = false, bool SP2 = false>
; __device__ __forceinline__ void gemm_phase(PG8_LAS unsigned char* lds, const Gemm g, const Sched& S, const Epi& E) {
;     ...
;             const char* a1 = cA + (size_t)(t + 1) * kstep;
;             const char* a2 = last ? nA : cA + (size_t)(t + 2) * kstep; const char* b2 = last ? nB : cB + (size_t)(t + 2) * kstep;
;             const char* a3 = a2 + kstep; const char* b3 = b2 + kstep;
;             if (last && has_next) S.a_ready(nxt);
;             if constexpr (Epi::MIDK) { if (t == E.midk_step(nt)) E.midk(acc, cur, wr, wc, fr, fq); }
;             if constexpr (SP2) {
;             PG8_LDB(B0, 0, 0); PG8_LDB(B1, 0, 1); PG8_SCHED; PG8_LDA(At, 0, 0); PG8_STAGE(PG8_SA(1, 1), a1 + hstepA, voffA);
;             PG8_WAIT_V(8); PG8_WAIT_L(0); PG8_BAR; PG8_MMA(0, 0, At, B0); PG8_MMA(0, 1, At, B1); PG8_BAR; PG8_SCHED;
;             PG8_LDA(At, 0, 1); PG8_STAGE(PG8_SB(0, 0), b2, voffB); PG8_STAGE(PG8_SB(0, 1), b2 + hstepB, voffB); PG8_STAGE(PG8_SA(0, 0), a2, voffA);
.LBB0_908:
	ds_read_b128 v[158:161], v155
	ds_read_b128 v[164:167], v155 offset:1024
	ds_read_b128 v[168:171], v155 offset:2048
	ds_read_b128 v[172:175], v155 offset:3072
	ds_read_b128 v[176:179], v156
	ds_read_b128 v[180:183], v156 offset:1024
	ds_read_b128 v[184:187], v156 offset:2048
	ds_read_b128 v[188:191], v156 offset:3072
	s_add_u32 s26, s24, 0xfff00080
	s_addc_u32 s27, s25, -1
	s_cmp_eq_u32 s55, 60
	s_cselect_b32 s29, s17, s27
	s_cselect_b32 s28, s47, s26
	s_cselect_b32 s27, s15, s54
	s_cselect_b32 s26, s52, s53
	v_lshl_add_u64 v[146:147], s[24:25], 0, v[138:139]
	s_add_i32 m0, s23, 0xc000
	ds_read_b128 v[192:195], v157
	ds_read_b128 v[196:199], v157 offset:1024
	ds_read_b128 v[200:203], v157 offset:2048
	ds_read_b128 v[204:207], v157 offset:3072
	ds_read_b128 v[208:211], v157 offset:4096
	ds_read_b128 v[212:215], v157 offset:5120
	ds_read_b128 v[216:219], v157 offset:6144
	ds_read_b128 v[220:223], v157 offset:7168
	global_load_lds_dwordx4 v[146:147], off
	v_lshl_add_u64 v[146:147], s[24:25], 0, v[140:141]
	s_add_i32 m0, s23, 0xe000
	s_nop 0
	global_load_lds_dwordx4 v[146:147], off
	s_waitcnt vmcnt(8)
	s_waitcnt lgkmcnt(0)
	s_barrier
	s_setprio 3
	v_mfma_f32_16x16x32_bf16 v[126:129], v[158:161], v[192:195], v[126:129]
	v_mfma_f32_16x16x32_bf16 v[126:129], v[164:167], v[196:199], v[126:129]
	v_mfma_f32_16x16x32_bf16 v[122:125], v[168:171], v[192:195], v[122:125]
	v_mfma_f32_16x16x32_bf16 v[122:125], v[172:175], v[196:199], v[122:125]
	v_mfma_f32_16x16x32_bf16 v[106:109], v[168:171], v[200:203], v[106:109]
	v_mfma_f32_16x16x32_bf16 v[106:109], v[172:175], v[204:207], v[106:109]
	v_mfma_f32_16x16x32_bf16 v[114:117], v[158:161], v[200:203], v[114:117]
	v_mfma_f32_16x16x32_bf16 v[114:117], v[164:167], v[204:207], v[114:117]
	v_mfma_f32_16x16x32_bf16 v[98:101], v[158:161], v[208:211], v[98:101]
	v_mfma_f32_16x16x32_bf16 v[98:101], v[164:167], v[212:215], v[98:101]
	v_mfma_f32_16x16x32_bf16 v[90:93], v[168:171], v[208:211], v[90:93]
	v_mfma_f32_16x16x32_bf16 v[90:93], v[172:175], v[212:215], v[90:93]
	v_mfma_f32_16x16x32_bf16 v[74:77], v[168:171], v[216:219], v[74:77]
	v_mfma_f32_16x16x32_bf16 v[74:77], v[172:175], v[220:223], v[74:77]
	v_mfma_f32_16x16x32_bf16 v[82:85], v[158:161], v[216:219], v[82:85]
	v_mfma_f32_16x16x32_bf16 v[82:85], v[164:167], v[220:223], v[82:85]
	v_mfma_f32_16x16x32_bf16 v[118:121], v[176:179], v[192:195], v[118:121]
	v_mfma_f32_16x16x32_bf16 v[118:121], v[180:183], v[196:199], v[118:121]
	v_mfma_f32_16x16x32_bf16 v[110:113], v[184:187], v[192:195], v[110:113]
	v_mfma_f32_16x16x32_bf16 v[110:113], v[188:191], v[196:199], v[110:113]
	v_mfma_f32_16x16x32_bf16 v[94:97], v[184:187], v[200:203], v[94:97]
	v_mfma_f32_16x16x32_bf16 v[94:97], v[188:191], v[204:207], v[94:97]
	v_mfma_f32_16x16x32_bf16 v[102:105], v[176:179], v[200:203], v[102:105]
	v_mfma_f32_16x16x32_bf16 v[102:105], v[180:183], v[204:207], v[102:105]
	v_mfma_f32_16x16x32_bf16 v[86:89], v[176:179], v[208:211], v[86:89]
	v_mfma_f32_16x16x32_bf16 v[86:89], v[180:183], v[212:215], v[86:89]
	v_mfma_f32_16x16x32_bf16 v[78:81], v[184:187], v[208:211], v[78:81]
	v_mfma_f32_16x16x32_bf16 v[78:81], v[188:191], v[212:215], v[78:81]
	v_mfma_f32_16x16x32_bf16 v[66:69], v[184:187], v[216:219], v[66:69]
	v_mfma_f32_16x16x32_bf16 v[66:69], v[188:191], v[220:223], v[66:69]
	v_mfma_f32_16x16x32_bf16 v[70:73], v[176:179], v[216:219], v[70:73]
	v_mfma_f32_16x16x32_bf16 v[70:73], v[180:183], v[220:223], v[70:73]
	s_barrier
	s_setprio 0
	s_add_i32 s56, s42, s30
	v_lshl_add_u64 v[146:147], s[26:27], 0, v[134:135]
	s_mov_b32 m0, s56
	ds_read_b128 v[192:195], v157 offset:16384
	ds_read_b128 v[196:199], v157 offset:17408
	ds_read_b128 v[200:203], v157 offset:18432
	ds_read_b128 v[204:207], v157 offset:19456
	ds_read_b128 v[208:211], v157 offset:20480
	ds_read_b128 v[212:215], v157 offset:21504
	ds_read_b128 v[216:219], v157 offset:22528
	ds_read_b128 v[220:223], v157 offset:23552
	global_load_lds_dwordx4 v[146:147], off
	s_add_i32 m0, s56, 0x2000
	s_add_u32 s56, s26, 0x100000
	v_lshl_add_u64 v[224:225], s[26:27], 0, v[130:131]
	s_addc_u32 s57, s27, 0
	s_add_i32 s58, s43, s30
	global_load_lds_dwordx4 v[224:225], off
	v_lshl_add_u64 v[226:227], s[56:57], 0, v[134:135]
	s_mov_b32 m0, s58
	v_lshl_add_u64 v[228:229], s[28:29], 0, v[132:133]
	global_load_lds_dwordx4 v[226:227], off
	v_lshl_add_u64 v[226:227], s[56:57], 0, v[130:131]
	s_add_i32 m0, s58, 0x2000
	s_nop 0
	global_load_lds_dwordx4 v[226:227], off
	v_lshl_add_u64 v[226:227], s[28:29], 0, v[136:137]
	s_mov_b32 m0, s23
	s_nop 0
	global_load_lds_dwordx4 v[226:227], off
	s_mov_b32 m0, s33
	s_nop 0
	global_load_lds_dwordx4 v[228:229], off
	s_waitcnt vmcnt(8)
	s_waitcnt lgkmcnt(0)
	s_barrier
; #define PG8_STAGE(bufoff, gbase, voff) do { _Pragma("unroll") for (int _i = 0; _i < 2; ++_i) \
;         __builtin_amdgcn_global_load_lds((const unsigned*)((const char*)(gbase) + (voff)[_i]), (PG8_LAS unsigned*)(lds + (bufoff) + ldsw + _i * 8192), 16, 0, 0); } while (0)
; #define PG8_LDA(dst, b, h) do { _Pragma("unroll") for (int m = 0; m < 4; ++m) _Pragma("unroll") for (int k = 0; k < 2; ++k) dst[m][k] = *(const PG8_LAS bf16x8*)(lds + PG8_SA(b, h) + aoff + m * 2048 + k * 1024); } while (0)
; #define PG8_LDB(dst, b, h) do { _Pragma("unroll") for (int n = 0; n < 2; ++n) _Pragma("unroll") for (int k = 0; k < 2; ++k) dst[n][k] = *(const PG8_LAS bf16x8*)(lds + PG8_SB(b, h) + boff + n * 2048 + k * 1024); } while (0)
; #define PG8_MMA(ai, bj, At, Bt) do { __builtin_amdgcn_s_setprio(3); _Pragma("unroll") for (int m = 0; m < 4; ++m) _Pragma("unroll") for (int n = 0; n < 2; ++n) _Pragma("unroll") for (int k = 0; k < 2; ++k) \
;         acc[ai][bj][m][n] = __builtin_amdgcn_mfma_f32_16x16x32_bf16(Bt[n][k], At[m][k], acc[ai][bj][m][n], 0, 0, 0); __builtin_amdgcn_s_setprio(0); } while (0)
; #define PG8_WAIT_V(n) asm volatile("s_waitcnt vmcnt(" #n ")" ::: "memory")
; #define PG8_WAIT_L(n) asm volatile("s_waitcnt lgkmcnt(" #n ")" ::: "memory")
; #define PG8_BAR __builtin_amdgcn_s_barrier()
; #define PG8_SCHED __builtin_amdgcn_sched_barrier(0)
; template <class Epi, class Sched, bool ALIGN_EPI = false, bool SP2 = false>
; __device__ __forceinline__ void gemm_phase(PG8_LAS unsigned char* lds, const Gemm g, const Sched& S, const Epi& E) {
;     ...
;             PG8_WAIT_V(8); PG8_WAIT_L(0); PG8_BAR; PG8_MMA(1, 0, At, B0); PG8_MMA(1, 1, At, B1); PG8_BAR; PG8_SCHED;
;             PG8_LDB(B0, 1, 0); PG8_LDB(B1, 1, 1); PG8_SCHED; PG8_LDA(At, 1, 0); PG8_STAGE(PG8_SA(0, 1), a2 + hstepA, voffA);
;             PG8_WAIT_V(8); PG8_WAIT_L(0); PG8_BAR; PG8_MMA(0, 0, At, B0); PG8_MMA(0, 1, At, B1); PG8_BAR; PG8_SCHED;
	s_setprio 3
	v_mfma_f32_16x16x32_bf16 v[62:65], v[158:161], v[192:195], v[62:65]
	v_mfma_f32_16x16x32_bf16 v[62:65], v[164:167], v[196:199], v[62:65]
	v_mfma_f32_16x16x32_bf16 v[58:61], v[168:171], v[192:195], v[58:61]
	v_mfma_f32_16x16x32_bf16 v[58:61], v[172:175], v[196:199], v[58:61]
	v_mfma_f32_16x16x32_bf16 v[42:45], v[168:171], v[200:203], v[42:45]
	v_mfma_f32_16x16x32_bf16 v[42:45], v[172:175], v[204:207], v[42:45]
	v_mfma_f32_16x16x32_bf16 v[50:53], v[158:161], v[200:203], v[50:53]
	v_mfma_f32_16x16x32_bf16 v[50:53], v[164:167], v[204:207], v[50:53]
	v_mfma_f32_16x16x32_bf16 v[34:37], v[158:161], v[208:211], v[34:37]
	v_mfma_f32_16x16x32_bf16 v[34:37], v[164:167], v[212:215], v[34:37]
	v_mfma_f32_16x16x32_bf16 v[26:29], v[168:171], v[208:211], v[26:29]
	v_mfma_f32_16x16x32_bf16 v[26:29], v[172:175], v[212:215], v[26:29]
	v_mfma_f32_16x16x32_bf16 v[10:13], v[168:171], v[216:219], v[10:13]
	v_mfma_f32_16x16x32_bf16 v[10:13], v[172:175], v[220:223], v[10:13]
	v_mfma_f32_16x16x32_bf16 v[14:17], v[158:161], v[216:219], v[14:17]
	v_mfma_f32_16x16x32_bf16 v[14:17], v[164:167], v[220:223], v[14:17]
	v_mfma_f32_16x16x32_bf16 v[54:57], v[176:179], v[192:195], v[54:57]
	v_mfma_f32_16x16x32_bf16 v[54:57], v[180:183], v[196:199], v[54:57]
	v_mfma_f32_16x16x32_bf16 v[46:49], v[184:187], v[192:195], v[46:49]
	v_mfma_f32_16x16x32_bf16 v[46:49], v[188:191], v[196:199], v[46:49]
	v_mfma_f32_16x16x32_bf16 v[30:33], v[184:187], v[200:203], v[30:33]
	v_mfma_f32_16x16x32_bf16 v[30:33], v[188:191], v[204:207], v[30:33]
	v_mfma_f32_16x16x32_bf16 v[38:41], v[176:179], v[200:203], v[38:41]
	v_mfma_f32_16x16x32_bf16 v[38:41], v[180:183], v[204:207], v[38:41]
	v_mfma_f32_16x16x32_bf16 v[22:25], v[176:179], v[208:211], v[22:25]
	v_mfma_f32_16x16x32_bf16 v[22:25], v[180:183], v[212:215], v[22:25]
	v_mfma_f32_16x16x32_bf16 v[18:21], v[184:187], v[208:211], v[18:21]
	v_mfma_f32_16x16x32_bf16 v[18:21], v[188:191], v[212:215], v[18:21]
	v_mfma_f32_16x16x32_bf16 v[2:5], v[184:187], v[216:219], v[2:5]
	v_mfma_f32_16x16x32_bf16 v[2:5], v[188:191], v[220:223], v[2:5]
	v_mfma_f32_16x16x32_bf16 v[6:9], v[176:179], v[216:219], v[6:9]
	v_mfma_f32_16x16x32_bf16 v[6:9], v[180:183], v[220:223], v[6:9]
	s_barrier
	s_setprio 0
	s_add_i32 s56, 0, 0x18000
	v_add_u32_e32 v148, s56, v151
	s_add_i32 s57, 0, 0x1c000
	ds_read_b128 v[158:161], v148
	ds_read_b128 v[164:167], v148 offset:1024
	ds_read_b128 v[168:171], v148 offset:2048
	ds_read_b128 v[172:175], v148 offset:3072
	v_add_u32_e32 v148, s57, v151
	ds_read_b128 v[176:179], v148
	ds_read_b128 v[180:183], v148 offset:1024
	ds_read_b128 v[184:187], v148 offset:2048
	ds_read_b128 v[188:191], v148 offset:3072
	s_add_u32 s28, s28, 0x100000
	s_addc_u32 s29, s29, 0
	s_mov_b32 m0, s36
	v_lshl_add_u64 v[230:231], s[28:29], 0, v[136:137]
	ds_read_b128 v[192:195], v157 offset:32768
	ds_read_b128 v[196:199], v157 offset:33792
	ds_read_b128 v[200:203], v157 offset:34816
	ds_read_b128 v[204:207], v157 offset:35840
	ds_read_b128 v[208:211], v157 offset:36864
	ds_read_b128 v[212:215], v157 offset:37888
	ds_read_b128 v[216:219], v157 offset:38912
	ds_read_b128 v[220:223], v157 offset:39936
	global_load_lds_dwordx4 v[230:231], off
	v_lshl_add_u64 v[230:231], s[28:29], 0, v[132:133]
	s_mov_b32 m0, s37
	s_nop 0
	global_load_lds_dwordx4 v[230:231], off
	s_waitcnt vmcnt(8)
	s_waitcnt lgkmcnt(0)
	s_barrier
	s_setprio 3
	v_mfma_f32_16x16x32_bf16 v[126:129], v[158:161], v[192:195], v[126:129]
	v_mfma_f32_16x16x32_bf16 v[126:129], v[164:167], v[196:199], v[126:129]
	v_mfma_f32_16x16x32_bf16 v[122:125], v[168:171], v[192:195], v[122:125]
	v_mfma_f32_16x16x32_bf16 v[122:125], v[172:175], v[196:199], v[122:125]
	v_mfma_f32_16x16x32_bf16 v[106:109], v[168:171], v[200:203], v[106:109]
	v_mfma_f32_16x16x32_bf16 v[106:109], v[172:175], v[204:207], v[106:109]
	v_mfma_f32_16x16x32_bf16 v[114:117], v[158:161], v[200:203], v[114:117]
	v_mfma_f32_16x16x32_bf16 v[114:117], v[164:167], v[204:207], v[114:117]
	v_mfma_f32_16x16x32_bf16 v[98:101], v[158:161], v[208:211], v[98:101]
	v_mfma_f32_16x16x32_bf16 v[98:101], v[164:167], v[212:215], v[98:101]
	v_mfma_f32_16x16x32_bf16 v[90:93], v[168:171], v[208:211], v[90:93]
	v_mfma_f32_16x16x32_bf16 v[90:93], v[172:175], v[212:215], v[90:93]
	v_mfma_f32_16x16x32_bf16 v[74:77], v[168:171], v[216:219], v[74:77]
	v_mfma_f32_16x16x32_bf16 v[74:77], v[172:175], v[220:223], v[74:77]
	v_mfma_f32_16x16x32_bf16 v[82:85], v[158:161], v[216:219], v[82:85]
	v_mfma_f32_16x16x32_bf16 v[82:85], v[164:167], v[220:223], v[82:85]
	v_mfma_f32_16x16x32_bf16 v[118:121], v[176:179], v[192:195], v[118:121]
	v_mfma_f32_16x16x32_bf16 v[118:121], v[180:183], v[196:199], v[118:121]
	v_mfma_f32_16x16x32_bf16 v[110:113], v[184:187], v[192:195], v[110:113]
	v_mfma_f32_16x16x32_bf16 v[110:113], v[188:191], v[196:199], v[110:113]
	v_mfma_f32_16x16x32_bf16 v[94:97], v[184:187], v[200:203], v[94:97]
	v_mfma_f32_16x16x32_bf16 v[94:97], v[188:191], v[204:207], v[94:97]
	v_mfma_f32_16x16x32_bf16 v[102:105], v[176:179], v[200:203], v[102:105]
	v_mfma_f32_16x16x32_bf16 v[102:105], v[180:183], v[204:207], v[102:105]
	v_mfma_f32_16x16x32_bf16 v[86:89], v[176:179], v[208:211], v[86:89]
	v_mfma_f32_16x16x32_bf16 v[86:89], v[180:183], v[212:215], v[86:89]
	v_mfma_f32_16x16x32_bf16 v[78:81], v[184:187], v[208:211], v[78:81]
	v_mfma_f32_16x16x32_bf16 v[78:81], v[188:191], v[212:215], v[78:81]
	v_mfma_f32_16x16x32_bf16 v[66:69], v[184:187], v[216:219], v[66:69]
	v_mfma_f32_16x16x32_bf16 v[66:69], v[188:191], v[220:223], v[66:69]
	v_mfma_f32_16x16x32_bf16 v[70:73], v[176:179], v[216:219], v[70:73]
	v_mfma_f32_16x16x32_bf16 v[70:73], v[180:183], v[220:223], v[70:73]
	s_barrier
; #define PG8_STAGE(bufoff, gbase, voff) do { _Pragma("unroll") for (int _i = 0; _i < 2; ++_i) \
;         __builtin_amdgcn_global_load_lds((const unsigned*)((const char*)(gbase) + (voff)[_i]), (PG8_LAS unsigned*)(lds + (bufoff) + ldsw + _i * 8192), 16, 0, 0); } while (0)
; #define PG8_LDA(dst, b, h) do { _Pragma("unroll") for (int m = 0; m < 4; ++m) _Pragma("unroll") for (int k = 0; k < 2; ++k) dst[m][k] = *(const PG8_LAS bf16x8*)(lds + PG8_SA(b, h) + aoff + m * 2048 + k * 1024); } while (0)
; #define PG8_MMA(ai, bj, At, Bt) do { __builtin_amdgcn_s_setprio(3); _Pragma("unroll") for (int m = 0; m < 4; ++m) _Pragma("unroll") for (int n = 0; n < 2; ++n) _Pragma("unroll") for (int k = 0; k < 2; ++k) \
;         acc[ai][bj][m][n] = __builtin_amdgcn_mfma_f32_16x16x32_bf16(Bt[n][k], At[m][k], acc[ai][bj][m][n], 0, 0, 0); __builtin_amdgcn_s_setprio(0); } while (0)
; #define PG8_WAIT_V(n) asm volatile("s_waitcnt vmcnt(" #n ")" ::: "memory")
; #define PG8_WAIT_L(n) asm volatile("s_waitcnt lgkmcnt(" #n ")" ::: "memory")
; #define PG8_BAR __builtin_amdgcn_s_barrier()
; #define PG8_SCHED __builtin_amdgcn_sched_barrier(0)
; template <class Epi, class Sched, bool ALIGN_EPI = false, bool SP2 = false>
; __device__ __forceinline__ void gemm_phase(PG8_LAS unsigned char* lds, const Gemm g, const Sched& S, const Epi& E) {
;     ...
;             PG8_LDA(At, 1, 1); PG8_STAGE(PG8_SB(1, 0), b3, voffB); PG8_STAGE(PG8_SB(1, 1), b3 + hstepB, voffB); PG8_STAGE(PG8_SA(1, 0), a3, voffA);
;             PG8_WAIT_V(8); PG8_WAIT_L(0); PG8_BAR; PG8_MMA(1, 0, At, B0); PG8_MMA(1, 1, At, B1); PG8_BAR; PG8_SCHED;
;     ...
;         if constexpr (ALIGN_EPI) { if (wr == 0) PG8_BAR; }
	s_setprio 0
	s_add_i32 s28, s56, s30
	v_lshl_add_u64 v[146:147], v[146:147], 0, s[12:13]
	s_mov_b32 m0, s28
	ds_read_b128 v[192:195], v157 offset:49152
	ds_read_b128 v[196:199], v157 offset:50176
	ds_read_b128 v[200:203], v157 offset:51200
	ds_read_b128 v[204:207], v157 offset:52224
	ds_read_b128 v[208:211], v157 offset:53248
	ds_read_b128 v[212:215], v157 offset:54272
	ds_read_b128 v[216:219], v157 offset:55296
	ds_read_b128 v[220:223], v157 offset:56320
	global_load_lds_dwordx4 v[146:147], off
	s_add_i32 m0, s28, 0x2000
	s_add_u32 s26, s26, 0x100080
	v_lshl_add_u64 v[146:147], v[224:225], 0, s[12:13]
	s_addc_u32 s27, s27, 0
	s_add_i32 s28, s57, s30
	global_load_lds_dwordx4 v[146:147], off
	v_lshl_add_u64 v[146:147], s[26:27], 0, v[134:135]
	s_mov_b32 m0, s28
	s_nop 0
	global_load_lds_dwordx4 v[146:147], off
	v_lshl_add_u64 v[146:147], s[26:27], 0, v[130:131]
	s_add_i32 m0, s28, 0x2000
	s_nop 0
	global_load_lds_dwordx4 v[146:147], off
	v_lshl_add_u64 v[146:147], v[226:227], 0, s[12:13]
	s_mov_b32 m0, s39
	s_nop 0
	global_load_lds_dwordx4 v[146:147], off
	v_lshl_add_u64 v[146:147], v[228:229], 0, s[12:13]
	s_mov_b32 m0, s40
	s_nop 0
	global_load_lds_dwordx4 v[146:147], off
	s_waitcnt vmcnt(8)
	s_waitcnt lgkmcnt(0)
	s_barrier
	s_setprio 3
	v_mfma_f32_16x16x32_bf16 v[62:65], v[158:161], v[192:195], v[62:65]
	v_mfma_f32_16x16x32_bf16 v[62:65], v[164:167], v[196:199], v[62:65]
	v_mfma_f32_16x16x32_bf16 v[58:61], v[168:171], v[192:195], v[58:61]
	v_mfma_f32_16x16x32_bf16 v[58:61], v[172:175], v[196:199], v[58:61]
	v_mfma_f32_16x16x32_bf16 v[42:45], v[168:171], v[200:203], v[42:45]
	v_mfma_f32_16x16x32_bf16 v[42:45], v[172:175], v[204:207], v[42:45]
	v_mfma_f32_16x16x32_bf16 v[50:53], v[158:161], v[200:203], v[50:53]
	v_mfma_f32_16x16x32_bf16 v[50:53], v[164:167], v[204:207], v[50:53]
	v_mfma_f32_16x16x32_bf16 v[34:37], v[158:161], v[208:211], v[34:37]
	v_mfma_f32_16x16x32_bf16 v[34:37], v[164:167], v[212:215], v[34:37]
	v_mfma_f32_16x16x32_bf16 v[26:29], v[168:171], v[208:211], v[26:29]
	v_mfma_f32_16x16x32_bf16 v[26:29], v[172:175], v[212:215], v[26:29]
	v_mfma_f32_16x16x32_bf16 v[10:13], v[168:171], v[216:219], v[10:13]
	v_mfma_f32_16x16x32_bf16 v[10:13], v[172:175], v[220:223], v[10:13]
	v_mfma_f32_16x16x32_bf16 v[14:17], v[158:161], v[216:219], v[14:17]
	v_mfma_f32_16x16x32_bf16 v[14:17], v[164:167], v[220:223], v[14:17]
	v_mfma_f32_16x16x32_bf16 v[54:57], v[176:179], v[192:195], v[54:57]
	v_mfma_f32_16x16x32_bf16 v[54:57], v[180:183], v[196:199], v[54:57]
	v_mfma_f32_16x16x32_bf16 v[46:49], v[184:187], v[192:195], v[46:49]
	v_mfma_f32_16x16x32_bf16 v[46:49], v[188:191], v[196:199], v[46:49]
	v_mfma_f32_16x16x32_bf16 v[30:33], v[184:187], v[200:203], v[30:33]
	v_mfma_f32_16x16x32_bf16 v[30:33], v[188:191], v[204:207], v[30:33]
	v_mfma_f32_16x16x32_bf16 v[38:41], v[176:179], v[200:203], v[38:41]
	v_mfma_f32_16x16x32_bf16 v[38:41], v[180:183], v[204:207], v[38:41]
	v_mfma_f32_16x16x32_bf16 v[22:25], v[176:179], v[208:211], v[22:25]
	v_mfma_f32_16x16x32_bf16 v[22:25], v[180:183], v[212:215], v[22:25]
	v_mfma_f32_16x16x32_bf16 v[18:21], v[184:187], v[208:211], v[18:21]
	v_mfma_f32_16x16x32_bf16 v[18:21], v[188:191], v[212:215], v[18:21]
	v_mfma_f32_16x16x32_bf16 v[2:5], v[184:187], v[216:219], v[2:5]
	v_mfma_f32_16x16x32_bf16 v[2:5], v[188:191], v[220:223], v[2:5]
	v_mfma_f32_16x16x32_bf16 v[6:9], v[176:179], v[216:219], v[6:9]
	v_mfma_f32_16x16x32_bf16 v[6:9], v[180:183], v[220:223], v[6:9]
	s_barrier
	s_setprio 0
	s_add_i32 s55, s55, 2
	s_add_u32 s24, s24, 0x100
	s_addc_u32 s25, s25, 0
	s_add_u32 s53, s53, 0x100
	s_addc_u32 s54, s54, 0
	s_cmp_gt_u32 s55, 61
	s_cbranch_scc0 .LBB0_908
	s_and_b64 vcc, exec, s[0:1]
	s_cbranch_vccz .LBB0_911
	s_barrier

; #define PG8_STAGE(bufoff, gbase, voff) do { _Pragma("unroll") for (int _i = 0; _i < 2; ++_i) \
;         __builtin_amdgcn_global_load_lds((const unsigned*)((const char*)(gbase) + (voff)[_i]), (PG8_LAS unsigned*)(lds + (bufoff) + ldsw + _i * 8192), 16, 0, 0); } while (0)
; #define PG8_LDA(dst, b, h) do { _Pragma("unroll") for (int m = 0; m < 4; ++m) _Pragma("unroll") for (int k = 0; k < 2; ++k) dst[m][k] = *(const PG8_LAS bf16x8*)(lds + PG8_SA(b, h) + aoff + m * 2048 + k * 1024); } while (0)
; #define PG8_LDB(dst, b, h) do { _Pragma("unroll") for (int n = 0; n < 2; ++n) _Pragma("unroll") for (int k = 0; k < 2; ++k) dst[n][k] = *(const PG8_LAS bf16x8*)(lds + PG8_SB(b, h) + boff + n * 2048 + k * 1024); } while (0)
; #define PG8_MMA(ai, bj, At, Bt) do { __builtin_amdgcn_s_setprio(3); _Pragma("unroll") for (int m = 0; m < 4; ++m) _Pragma("unroll") for (int n = 0; n < 2; ++n) _Pragma("unroll") for (int k = 0; k < 2; ++k) \
;         acc[ai][bj][m][n] = __builtin_amdgcn_mfma_f32_16x16x32_bf16(Bt[n][k], At[m][k], acc[ai][bj][m][n], 0, 0, 0); __builtin_amdgcn_s_setprio(0); } while (0)
; #define PG8_WAIT_V(n) asm volatile("s_waitcnt vmcnt(" #n ")" ::: "memory")
; #define PG8_WAIT_L(n) asm volatile("s_waitcnt lgkmcnt(" #n ")" ::: "memory")
; #define PG8_BAR __builtin_amdgcn_s_barrier()
; #define PG8_SCHED __builtin_amdgcn_sched_barrier(0)
; template <class Epi, class Sched, bool ALIGN_EPI = false, bool SP2 = false>
; __device__ __forceinline__ void gemm_phase(PG8_LAS unsigned char* lds, const Gemm g, const Sched& S, const Epi& E) {
;     ...
;             const char* a1 = cA + (size_t)(t + 1) * kstep;
;             const char* a2 = last ? nA : cA + (size_t)(t + 2) * kstep; const char* b2 = last ? nB : cB + (size_t)(t + 2) * kstep;
;             const char* a3 = a2 + kstep; const char* b3 = b2 + kstep;
;             if (last && has_next) S.a_ready(nxt);
;             if constexpr (Epi::MIDK) { if (t == E.midk_step(nt)) E.midk(acc, cur, wr, wc, fr, fq); }
;             if constexpr (SP2) {
;             PG8_LDB(B0, 0, 0); PG8_LDB(B1, 0, 1); PG8_SCHED; PG8_LDA(At, 0, 0); PG8_STAGE(PG8_SA(1, 1), a1 + hstepA, voffA);
;             PG8_WAIT_V(8); PG8_WAIT_L(0); PG8_BAR; PG8_MMA(0, 0, At, B0); PG8_MMA(0, 1, At, B1); PG8_BAR; PG8_SCHED;
;             PG8_LDA(At, 0, 1); PG8_STAGE(PG8_SB(0, 0), b2, voffB); PG8_STAGE(PG8_SB(0, 1), b2 + hstepB, voffB); PG8_STAGE(PG8_SA(0, 0), a2, voffA);
.LBB0_975:
	v_add_u32_e32 v144, s46, v206
	v_add_u32_e32 v160, s47, v206
	s_add_u32 s28, s2, s12
	ds_read_b128 v[132:135], v144
	ds_read_b128 v[136:139], v144 offset:1024
	ds_read_b128 v[140:143], v144 offset:2048
	ds_read_b128 v[144:147], v144 offset:3072
	ds_read_b128 v[148:151], v160
	ds_read_b128 v[152:155], v160 offset:1024
	ds_read_b128 v[156:159], v160 offset:2048
	ds_read_b128 v[160:163], v160 offset:3072
	s_addc_u32 s29, s3, s13
	s_add_u32 s28, s28, 0x21500100
	s_addc_u32 s29, s29, 0
	s_add_u32 s81, s44, s12
	s_addc_u32 s82, s45, s13
	s_cmpk_eq_i32 s12, 0x5500
	s_cselect_b32 s31, s1, s29
	s_cselect_b32 s30, s0, s28
	s_cselect_b32 s29, s11, s82
	s_cselect_b32 s28, s10, s81
	s_mov_b32 m0, s71
	v_lshl_add_u64 v[234:235], v[2:3], 0, s[12:13]
	ds_read_b128 v[164:167], v207
	ds_read_b128 v[168:171], v207 offset:1024
	ds_read_b128 v[210:213], v207 offset:2048
	ds_read_b128 v[214:217], v207 offset:3072
	ds_read_b128 v[218:221], v207 offset:4096
	ds_read_b128 v[222:225], v207 offset:5120
	ds_read_b128 v[226:229], v207 offset:6144
	ds_read_b128 v[230:233], v207 offset:7168
	global_load_lds_dwordx4 v[234:235], off
	v_lshl_add_u64 v[234:235], v[200:201], 0, s[12:13]
	s_mov_b32 m0, s72
	s_nop 0
	global_load_lds_dwordx4 v[234:235], off
	s_waitcnt vmcnt(8)
	s_waitcnt lgkmcnt(0)
	s_barrier
	s_setprio 3
	v_mfma_f32_16x16x32_bf16 v[128:131], v[132:135], v[164:167], v[128:131]
	v_mfma_f32_16x16x32_bf16 v[128:131], v[136:139], v[168:171], v[128:131]
	v_mfma_f32_16x16x32_bf16 v[124:127], v[140:143], v[164:167], v[124:127]
	v_mfma_f32_16x16x32_bf16 v[124:127], v[144:147], v[168:171], v[124:127]
	v_mfma_f32_16x16x32_bf16 v[96:99], v[140:143], v[210:213], v[96:99]
	v_mfma_f32_16x16x32_bf16 v[96:99], v[144:147], v[214:217], v[96:99]
	v_mfma_f32_16x16x32_bf16 v[100:103], v[132:135], v[210:213], v[100:103]
	v_mfma_f32_16x16x32_bf16 v[100:103], v[136:139], v[214:217], v[100:103]
	v_mfma_f32_16x16x32_bf16 v[112:115], v[132:135], v[218:221], v[112:115]
	v_mfma_f32_16x16x32_bf16 v[112:115], v[136:139], v[222:225], v[112:115]
	v_mfma_f32_16x16x32_bf16 v[108:111], v[140:143], v[218:221], v[108:111]
	v_mfma_f32_16x16x32_bf16 v[108:111], v[144:147], v[222:225], v[108:111]
	v_mfma_f32_16x16x32_bf16 v[76:79], v[140:143], v[226:229], v[76:79]
	v_mfma_f32_16x16x32_bf16 v[76:79], v[144:147], v[230:233], v[76:79]
	v_mfma_f32_16x16x32_bf16 v[80:83], v[132:135], v[226:229], v[80:83]
	v_mfma_f32_16x16x32_bf16 v[80:83], v[136:139], v[230:233], v[80:83]
	v_mfma_f32_16x16x32_bf16 v[120:123], v[148:151], v[164:167], v[120:123]
	v_mfma_f32_16x16x32_bf16 v[120:123], v[152:155], v[168:171], v[120:123]
	v_mfma_f32_16x16x32_bf16 v[116:119], v[156:159], v[164:167], v[116:119]
	v_mfma_f32_16x16x32_bf16 v[116:119], v[160:163], v[168:171], v[116:119]
	v_mfma_f32_16x16x32_bf16 v[88:91], v[156:159], v[210:213], v[88:91]
	v_mfma_f32_16x16x32_bf16 v[88:91], v[160:163], v[214:217], v[88:91]
	v_mfma_f32_16x16x32_bf16 v[92:95], v[148:151], v[210:213], v[92:95]
	v_mfma_f32_16x16x32_bf16 v[92:95], v[152:155], v[214:217], v[92:95]
	v_mfma_f32_16x16x32_bf16 v[104:107], v[148:151], v[218:221], v[104:107]
	v_mfma_f32_16x16x32_bf16 v[104:107], v[152:155], v[222:225], v[104:107]
	v_mfma_f32_16x16x32_bf16 v[84:87], v[156:159], v[218:221], v[84:87]
	v_mfma_f32_16x16x32_bf16 v[84:87], v[160:163], v[222:225], v[84:87]
	v_mfma_f32_16x16x32_bf16 v[68:71], v[156:159], v[226:229], v[68:71]
	v_mfma_f32_16x16x32_bf16 v[68:71], v[160:163], v[230:233], v[68:71]
	v_mfma_f32_16x16x32_bf16 v[72:75], v[148:151], v[226:229], v[72:75]
	v_mfma_f32_16x16x32_bf16 v[72:75], v[152:155], v[230:233], v[72:75]
	s_barrier
	s_setprio 0
	s_mov_b32 m0, s73
	v_lshl_add_u64 v[234:235], s[28:29], 0, v[174:175]
	s_add_u32 s82, s28, 0x2b0000
	ds_read_b128 v[164:167], v207 offset:16384
	ds_read_b128 v[168:171], v207 offset:17408
	ds_read_b128 v[210:213], v207 offset:18432
	ds_read_b128 v[214:217], v207 offset:19456
	ds_read_b128 v[218:221], v207 offset:20480
	ds_read_b128 v[222:225], v207 offset:21504
	ds_read_b128 v[226:229], v207 offset:22528
	ds_read_b128 v[230:233], v207 offset:23552
	global_load_lds_dwordx4 v[234:235], off
	v_lshl_add_u64 v[236:237], s[28:29], 0, v[178:179]
	s_mov_b32 m0, s74
	s_addc_u32 s83, s29, 0
	global_load_lds_dwordx4 v[236:237], off
	v_lshl_add_u64 v[238:239], s[82:83], 0, v[174:175]
	s_mov_b32 m0, s75
	v_lshl_add_u64 v[240:241], s[30:31], 0, v[176:177]
	global_load_lds_dwordx4 v[238:239], off
	v_lshl_add_u64 v[238:239], s[82:83], 0, v[178:179]
	s_mov_b32 m0, s76
	s_nop 0
	global_load_lds_dwordx4 v[238:239], off
	v_lshl_add_u64 v[238:239], s[30:31], 0, v[172:173]
	s_mov_b32 m0, s42
	s_nop 0
	global_load_lds_dwordx4 v[238:239], off
	s_mov_b32 m0, s54
	s_nop 0
	global_load_lds_dwordx4 v[240:241], off
	s_waitcnt vmcnt(8)
	s_waitcnt lgkmcnt(0)
	s_barrier
; #define PG8_STAGE(bufoff, gbase, voff) do { _Pragma("unroll") for (int _i = 0; _i < 2; ++_i) \
;         __builtin_amdgcn_global_load_lds((const unsigned*)((const char*)(gbase) + (voff)[_i]), (PG8_LAS unsigned*)(lds + (bufoff) + ldsw + _i * 8192), 16, 0, 0); } while (0)
; #define PG8_LDA(dst, b, h) do { _Pragma("unroll") for (int m = 0; m < 4; ++m) _Pragma("unroll") for (int k = 0; k < 2; ++k) dst[m][k] = *(const PG8_LAS bf16x8*)(lds + PG8_SA(b, h) + aoff + m * 2048 + k * 1024); } while (0)
; #define PG8_LDB(dst, b, h) do { _Pragma("unroll") for (int n = 0; n < 2; ++n) _Pragma("unroll") for (int k = 0; k < 2; ++k) dst[n][k] = *(const PG8_LAS bf16x8*)(lds + PG8_SB(b, h) + boff + n * 2048 + k * 1024); } while (0)
; #define PG8_MMA(ai, bj, At, Bt) do { __builtin_amdgcn_s_setprio(3); _Pragma("unroll") for (int m = 0; m < 4; ++m) _Pragma("unroll") for (int n = 0; n < 2; ++n) _Pragma("unroll") for (int k = 0; k < 2; ++k) \
;         acc[ai][bj][m][n] = __builtin_amdgcn_mfma_f32_16x16x32_bf16(Bt[n][k], At[m][k], acc[ai][bj][m][n], 0, 0, 0); __builtin_amdgcn_s_setprio(0); } while (0)
; #define PG8_WAIT_V(n) asm volatile("s_waitcnt vmcnt(" #n ")" ::: "memory")
; #define PG8_WAIT_L(n) asm volatile("s_waitcnt lgkmcnt(" #n ")" ::: "memory")
; #define PG8_BAR __builtin_amdgcn_s_barrier()
; #define PG8_SCHED __builtin_amdgcn_sched_barrier(0)
; template <class Epi, class Sched, bool ALIGN_EPI = false, bool SP2 = false>
; __device__ __forceinline__ void gemm_phase(PG8_LAS unsigned char* lds, const Gemm g, const Sched& S, const Epi& E) {
;     ...
;             PG8_WAIT_V(8); PG8_WAIT_L(0); PG8_BAR; PG8_MMA(1, 0, At, B0); PG8_MMA(1, 1, At, B1); PG8_BAR; PG8_SCHED;
;             PG8_LDB(B0, 1, 0); PG8_LDB(B1, 1, 1); PG8_SCHED; PG8_LDA(At, 1, 0); PG8_STAGE(PG8_SA(0, 1), a2 + hstepA, voffA);
;             PG8_WAIT_V(8); PG8_WAIT_L(0); PG8_BAR; PG8_MMA(0, 0, At, B0); PG8_MMA(0, 1, At, B1); PG8_BAR; PG8_SCHED;
	s_setprio 3
	v_mfma_f32_16x16x32_bf16 v[64:67], v[132:135], v[164:167], v[64:67]
	v_mfma_f32_16x16x32_bf16 v[64:67], v[136:139], v[168:171], v[64:67]
	v_mfma_f32_16x16x32_bf16 v[60:63], v[140:143], v[164:167], v[60:63]
	v_mfma_f32_16x16x32_bf16 v[60:63], v[144:147], v[168:171], v[60:63]
	v_mfma_f32_16x16x32_bf16 v[44:47], v[140:143], v[210:213], v[44:47]
	v_mfma_f32_16x16x32_bf16 v[44:47], v[144:147], v[214:217], v[44:47]
	v_mfma_f32_16x16x32_bf16 v[48:51], v[132:135], v[210:213], v[48:51]
	v_mfma_f32_16x16x32_bf16 v[48:51], v[136:139], v[214:217], v[48:51]
	v_mfma_f32_16x16x32_bf16 v[32:35], v[132:135], v[218:221], v[32:35]
	v_mfma_f32_16x16x32_bf16 v[32:35], v[136:139], v[222:225], v[32:35]
	v_mfma_f32_16x16x32_bf16 v[28:31], v[140:143], v[218:221], v[28:31]
	v_mfma_f32_16x16x32_bf16 v[28:31], v[144:147], v[222:225], v[28:31]
	v_mfma_f32_16x16x32_bf16 v[12:15], v[140:143], v[226:229], v[12:15]
	v_mfma_f32_16x16x32_bf16 v[12:15], v[144:147], v[230:233], v[12:15]
	v_mfma_f32_16x16x32_bf16 v[16:19], v[132:135], v[226:229], v[16:19]
	v_mfma_f32_16x16x32_bf16 v[16:19], v[136:139], v[230:233], v[16:19]
	v_mfma_f32_16x16x32_bf16 v[56:59], v[148:151], v[164:167], v[56:59]
	v_mfma_f32_16x16x32_bf16 v[56:59], v[152:155], v[168:171], v[56:59]
	v_mfma_f32_16x16x32_bf16 v[52:55], v[156:159], v[164:167], v[52:55]
	v_mfma_f32_16x16x32_bf16 v[52:55], v[160:163], v[168:171], v[52:55]
	v_mfma_f32_16x16x32_bf16 v[36:39], v[156:159], v[210:213], v[36:39]
	v_mfma_f32_16x16x32_bf16 v[36:39], v[160:163], v[214:217], v[36:39]
	v_mfma_f32_16x16x32_bf16 v[40:43], v[148:151], v[210:213], v[40:43]
	v_mfma_f32_16x16x32_bf16 v[40:43], v[152:155], v[214:217], v[40:43]
	v_mfma_f32_16x16x32_bf16 v[24:27], v[148:151], v[218:221], v[24:27]
	v_mfma_f32_16x16x32_bf16 v[24:27], v[152:155], v[222:225], v[24:27]
	v_mfma_f32_16x16x32_bf16 v[20:23], v[156:159], v[218:221], v[20:23]
	v_mfma_f32_16x16x32_bf16 v[20:23], v[160:163], v[222:225], v[20:23]
	v_mfma_f32_16x16x32_bf16 v[4:7], v[156:159], v[226:229], v[4:7]
	v_mfma_f32_16x16x32_bf16 v[4:7], v[160:163], v[230:233], v[4:7]
	v_mfma_f32_16x16x32_bf16 v[8:11], v[148:151], v[226:229], v[8:11]
	v_mfma_f32_16x16x32_bf16 v[8:11], v[152:155], v[230:233], v[8:11]
	s_barrier
	s_setprio 0
	v_add_u32_e32 v144, s52, v206
	v_add_u32_e32 v160, s53, v206
	ds_read_b128 v[132:135], v144
	ds_read_b128 v[136:139], v144 offset:1024
	ds_read_b128 v[140:143], v144 offset:2048
	ds_read_b128 v[144:147], v144 offset:3072
	ds_read_b128 v[148:151], v160
	ds_read_b128 v[152:155], v160 offset:1024
	ds_read_b128 v[156:159], v160 offset:2048
	ds_read_b128 v[160:163], v160 offset:3072
	s_add_u32 s30, s30, 0x2b0000
	s_addc_u32 s31, s31, 0
	s_mov_b32 m0, s55
	v_lshl_add_u64 v[242:243], s[30:31], 0, v[172:173]
	ds_read_b128 v[164:167], v207 offset:32768
	ds_read_b128 v[168:171], v207 offset:33792
	ds_read_b128 v[210:213], v207 offset:34816
	ds_read_b128 v[214:217], v207 offset:35840
	ds_read_b128 v[218:221], v207 offset:36864
	ds_read_b128 v[222:225], v207 offset:37888
	ds_read_b128 v[226:229], v207 offset:38912
	ds_read_b128 v[230:233], v207 offset:39936
	global_load_lds_dwordx4 v[242:243], off
	v_lshl_add_u64 v[242:243], s[30:31], 0, v[176:177]
	s_mov_b32 m0, s56
	s_nop 0
	global_load_lds_dwordx4 v[242:243], off
	s_waitcnt vmcnt(8)
	s_waitcnt lgkmcnt(0)
	s_barrier
	s_setprio 3
	v_mfma_f32_16x16x32_bf16 v[128:131], v[132:135], v[164:167], v[128:131]
	v_mfma_f32_16x16x32_bf16 v[128:131], v[136:139], v[168:171], v[128:131]
	v_mfma_f32_16x16x32_bf16 v[124:127], v[140:143], v[164:167], v[124:127]
	v_mfma_f32_16x16x32_bf16 v[124:127], v[144:147], v[168:171], v[124:127]
	v_mfma_f32_16x16x32_bf16 v[96:99], v[140:143], v[210:213], v[96:99]
	v_mfma_f32_16x16x32_bf16 v[96:99], v[144:147], v[214:217], v[96:99]
	v_mfma_f32_16x16x32_bf16 v[100:103], v[132:135], v[210:213], v[100:103]
	v_mfma_f32_16x16x32_bf16 v[100:103], v[136:139], v[214:217], v[100:103]
	v_mfma_f32_16x16x32_bf16 v[112:115], v[132:135], v[218:221], v[112:115]
	v_mfma_f32_16x16x32_bf16 v[112:115], v[136:139], v[222:225], v[112:115]
	v_mfma_f32_16x16x32_bf16 v[108:111], v[140:143], v[218:221], v[108:111]
	v_mfma_f32_16x16x32_bf16 v[108:111], v[144:147], v[222:225], v[108:111]
	v_mfma_f32_16x16x32_bf16 v[76:79], v[140:143], v[226:229], v[76:79]
	v_mfma_f32_16x16x32_bf16 v[76:79], v[144:147], v[230:233], v[76:79]
	v_mfma_f32_16x16x32_bf16 v[80:83], v[132:135], v[226:229], v[80:83]
	v_mfma_f32_16x16x32_bf16 v[80:83], v[136:139], v[230:233], v[80:83]
	v_mfma_f32_16x16x32_bf16 v[120:123], v[148:151], v[164:167], v[120:123]
	v_mfma_f32_16x16x32_bf16 v[120:123], v[152:155], v[168:171], v[120:123]
	v_mfma_f32_16x16x32_bf16 v[116:119], v[156:159], v[164:167], v[116:119]
	v_mfma_f32_16x16x32_bf16 v[116:119], v[160:163], v[168:171], v[116:119]
	v_mfma_f32_16x16x32_bf16 v[88:91], v[156:159], v[210:213], v[88:91]
	v_mfma_f32_16x16x32_bf16 v[88:91], v[160:163], v[214:217], v[88:91]
	v_mfma_f32_16x16x32_bf16 v[92:95], v[148:151], v[210:213], v[92:95]
	v_mfma_f32_16x16x32_bf16 v[92:95], v[152:155], v[214:217], v[92:95]
	v_mfma_f32_16x16x32_bf16 v[104:107], v[148:151], v[218:221], v[104:107]
	v_mfma_f32_16x16x32_bf16 v[104:107], v[152:155], v[222:225], v[104:107]
	v_mfma_f32_16x16x32_bf16 v[84:87], v[156:159], v[218:221], v[84:87]
	v_mfma_f32_16x16x32_bf16 v[84:87], v[160:163], v[222:225], v[84:87]
	v_mfma_f32_16x16x32_bf16 v[68:71], v[156:159], v[226:229], v[68:71]
	v_mfma_f32_16x16x32_bf16 v[68:71], v[160:163], v[230:233], v[68:71]
	v_mfma_f32_16x16x32_bf16 v[72:75], v[148:151], v[226:229], v[72:75]
	v_mfma_f32_16x16x32_bf16 v[72:75], v[152:155], v[230:233], v[72:75]
	s_barrier
; #define PG8_STAGE(bufoff, gbase, voff) do { _Pragma("unroll") for (int _i = 0; _i < 2; ++_i) \
;         __builtin_amdgcn_global_load_lds((const unsigned*)((const char*)(gbase) + (voff)[_i]), (PG8_LAS unsigned*)(lds + (bufoff) + ldsw + _i * 8192), 16, 0, 0); } while (0)
; #define PG8_LDA(dst, b, h) do { _Pragma("unroll") for (int m = 0; m < 4; ++m) _Pragma("unroll") for (int k = 0; k < 2; ++k) dst[m][k] = *(const PG8_LAS bf16x8*)(lds + PG8_SA(b, h) + aoff + m * 2048 + k * 1024); } while (0)
; #define PG8_MMA(ai, bj, At, Bt) do { __builtin_amdgcn_s_setprio(3); _Pragma("unroll") for (int m = 0; m < 4; ++m) _Pragma("unroll") for (int n = 0; n < 2; ++n) _Pragma("unroll") for (int k = 0; k < 2; ++k) \
;         acc[ai][bj][m][n] = __builtin_amdgcn_mfma_f32_16x16x32_bf16(Bt[n][k], At[m][k], acc[ai][bj][m][n], 0, 0, 0); __builtin_amdgcn_s_setprio(0); } while (0)
; #define PG8_WAIT_V(n) asm volatile("s_waitcnt vmcnt(" #n ")" ::: "memory")
; #define PG8_WAIT_L(n) asm volatile("s_waitcnt lgkmcnt(" #n ")" ::: "memory")
; #define PG8_BAR __builtin_amdgcn_s_barrier()
; #define PG8_SCHED __builtin_amdgcn_sched_barrier(0)
; template <class Epi, class Sched, bool ALIGN_EPI = false, bool SP2 = false>
; __device__ __forceinline__ void gemm_phase(PG8_LAS unsigned char* lds, const Gemm g, const Sched& S, const Epi& E) {
;     ...
;         for (int t = 0; t < nt; t += 2) {
;     ...
;             PG8_LDA(At, 1, 1); PG8_STAGE(PG8_SB(1, 0), b3, voffB); PG8_STAGE(PG8_SB(1, 1), b3 + hstepB, voffB); PG8_STAGE(PG8_SA(1, 0), a3, voffA);
;             PG8_WAIT_V(8); PG8_WAIT_L(0); PG8_BAR; PG8_MMA(1, 0, At, B0); PG8_MMA(1, 1, At, B1); PG8_BAR; PG8_SCHED;
	s_setprio 0
	s_mov_b32 m0, s77
	v_lshl_add_u64 v[234:235], v[234:235], 0, s[4:5]
	s_add_u32 s28, s28, 0x2b0080
	ds_read_b128 v[164:167], v207 offset:49152
	ds_read_b128 v[168:171], v207 offset:50176
	ds_read_b128 v[210:213], v207 offset:51200
	ds_read_b128 v[214:217], v207 offset:52224
	ds_read_b128 v[218:221], v207 offset:53248
	ds_read_b128 v[222:225], v207 offset:54272
	ds_read_b128 v[226:229], v207 offset:55296
	ds_read_b128 v[230:233], v207 offset:56320
	global_load_lds_dwordx4 v[234:235], off
	v_lshl_add_u64 v[234:235], v[236:237], 0, s[4:5]
	s_mov_b32 m0, s78
	s_addc_u32 s29, s29, 0
	global_load_lds_dwordx4 v[234:235], off
	v_lshl_add_u64 v[234:235], s[28:29], 0, v[174:175]
	s_mov_b32 m0, s79
	s_nop 0
	global_load_lds_dwordx4 v[234:235], off
	v_lshl_add_u64 v[234:235], s[28:29], 0, v[178:179]
	s_mov_b32 m0, s80
	s_nop 0
	global_load_lds_dwordx4 v[234:235], off
	v_lshl_add_u64 v[234:235], v[238:239], 0, s[4:5]
	s_mov_b32 m0, s57
	s_nop 0
	global_load_lds_dwordx4 v[234:235], off
	v_lshl_add_u64 v[234:235], v[240:241], 0, s[4:5]
	s_mov_b32 m0, s58
	s_nop 0
	global_load_lds_dwordx4 v[234:235], off
	s_waitcnt vmcnt(8)
	s_waitcnt lgkmcnt(0)
	s_barrier
	s_setprio 3
	v_mfma_f32_16x16x32_bf16 v[64:67], v[132:135], v[164:167], v[64:67]
	v_mfma_f32_16x16x32_bf16 v[64:67], v[136:139], v[168:171], v[64:67]
	v_mfma_f32_16x16x32_bf16 v[60:63], v[140:143], v[164:167], v[60:63]
	v_mfma_f32_16x16x32_bf16 v[60:63], v[144:147], v[168:171], v[60:63]
	v_mfma_f32_16x16x32_bf16 v[44:47], v[140:143], v[210:213], v[44:47]
	v_mfma_f32_16x16x32_bf16 v[44:47], v[144:147], v[214:217], v[44:47]
	v_mfma_f32_16x16x32_bf16 v[48:51], v[132:135], v[210:213], v[48:51]
	v_mfma_f32_16x16x32_bf16 v[48:51], v[136:139], v[214:217], v[48:51]
	v_mfma_f32_16x16x32_bf16 v[32:35], v[132:135], v[218:221], v[32:35]
	v_mfma_f32_16x16x32_bf16 v[32:35], v[136:139], v[222:225], v[32:35]
	v_mfma_f32_16x16x32_bf16 v[28:31], v[140:143], v[218:221], v[28:31]
	v_mfma_f32_16x16x32_bf16 v[28:31], v[144:147], v[222:225], v[28:31]
	v_mfma_f32_16x16x32_bf16 v[12:15], v[140:143], v[226:229], v[12:15]
	v_mfma_f32_16x16x32_bf16 v[12:15], v[144:147], v[230:233], v[12:15]
	v_mfma_f32_16x16x32_bf16 v[16:19], v[132:135], v[226:229], v[16:19]
	v_mfma_f32_16x16x32_bf16 v[16:19], v[136:139], v[230:233], v[16:19]
	v_mfma_f32_16x16x32_bf16 v[56:59], v[148:151], v[164:167], v[56:59]
	v_mfma_f32_16x16x32_bf16 v[56:59], v[152:155], v[168:171], v[56:59]
	v_mfma_f32_16x16x32_bf16 v[52:55], v[156:159], v[164:167], v[52:55]
	v_mfma_f32_16x16x32_bf16 v[52:55], v[160:163], v[168:171], v[52:55]
	v_mfma_f32_16x16x32_bf16 v[36:39], v[156:159], v[210:213], v[36:39]
	v_mfma_f32_16x16x32_bf16 v[36:39], v[160:163], v[214:217], v[36:39]
	v_mfma_f32_16x16x32_bf16 v[40:43], v[148:151], v[210:213], v[40:43]
	v_mfma_f32_16x16x32_bf16 v[40:43], v[152:155], v[214:217], v[40:43]
	v_mfma_f32_16x16x32_bf16 v[24:27], v[148:151], v[218:221], v[24:27]
	v_mfma_f32_16x16x32_bf16 v[24:27], v[152:155], v[222:225], v[24:27]
	v_mfma_f32_16x16x32_bf16 v[20:23], v[156:159], v[218:221], v[20:23]
	v_mfma_f32_16x16x32_bf16 v[20:23], v[160:163], v[222:225], v[20:23]
	v_mfma_f32_16x16x32_bf16 v[4:7], v[156:159], v[226:229], v[4:7]
	v_mfma_f32_16x16x32_bf16 v[4:7], v[160:163], v[230:233], v[4:7]
	v_mfma_f32_16x16x32_bf16 v[8:11], v[148:151], v[226:229], v[8:11]
	v_mfma_f32_16x16x32_bf16 v[8:11], v[152:155], v[230:233], v[8:11]
	s_barrier
	s_setprio 0
	s_add_i32 s61, s61, 2
	s_add_u32 s12, s12, 0x100
	s_addc_u32 s13, s13, 0
	s_cmpk_gt_u32 s61, 0xa9
	s_cbranch_scc1 .LBB0_978

; #define PG8_STAGE(bufoff, gbase, voff) do { _Pragma("unroll") for (int _i = 0; _i < 2; ++_i) \
;         __builtin_amdgcn_global_load_lds((const unsigned*)((const char*)(gbase) + (voff)[_i]), (PG8_LAS unsigned*)(lds + (bufoff) + ldsw + _i * 8192), 16, 0, 0); } while (0)
; #define PG8_LDA(dst, b, h) do { _Pragma("unroll") for (int m = 0; m < 4; ++m) _Pragma("unroll") for (int k = 0; k < 2; ++k) dst[m][k] = *(const PG8_LAS bf16x8*)(lds + PG8_SA(b, h) + aoff + m * 2048 + k * 1024); } while (0)
; #define PG8_LDB(dst, b, h) do { _Pragma("unroll") for (int n = 0; n < 2; ++n) _Pragma("unroll") for (int k = 0; k < 2; ++k) dst[n][k] = *(const PG8_LAS bf16x8*)(lds + PG8_SB(b, h) + boff + n * 2048 + k * 1024); } while (0)
; #define PG8_MMA(ai, bj, At, Bt) do { __builtin_amdgcn_s_setprio(3); _Pragma("unroll") for (int m = 0; m < 4; ++m) _Pragma("unroll") for (int n = 0; n < 2; ++n) _Pragma("unroll") for (int k = 0; k < 2; ++k) \
;         acc[ai][bj][m][n] = __builtin_amdgcn_mfma_f32_16x16x32_bf16(Bt[n][k], At[m][k], acc[ai][bj][m][n], 0, 0, 0); __builtin_amdgcn_s_setprio(0); } while (0)
; #define PG8_WAIT_V(n) asm volatile("s_waitcnt vmcnt(" #n ")" ::: "memory")
; #define PG8_WAIT_L(n) asm volatile("s_waitcnt lgkmcnt(" #n ")" ::: "memory")
; #define PG8_BAR __builtin_amdgcn_s_barrier()
; #define PG8_SCHED __builtin_amdgcn_sched_barrier(0)
; template <class Epi, class Sched, bool ALIGN_EPI = false, bool SP2 = false>
; __device__ __forceinline__ void gemm_phase(PG8_LAS unsigned char* lds, const Gemm g, const Sched& S, const Epi& E) {
;     ...
;             const char* a1 = cA + (size_t)(t + 1) * kstep;
;             const char* a2 = last ? nA : cA + (size_t)(t + 2) * kstep; const char* b2 = last ? nB : cB + (size_t)(t + 2) * kstep;
;             const char* a3 = a2 + kstep; const char* b3 = b2 + kstep;
;             if (last && has_next) S.a_ready(nxt);
;             if constexpr (Epi::MIDK) { if (t == E.midk_step(nt)) E.midk(acc, cur, wr, wc, fr, fq); }
;             if constexpr (SP2) {
;             PG8_LDB(B0, 0, 0); PG8_LDB(B1, 0, 1); PG8_SCHED; PG8_LDA(At, 0, 0); PG8_STAGE(PG8_SA(1, 1), a1 + hstepA, voffA);
;             PG8_WAIT_V(8); PG8_WAIT_L(0); PG8_BAR; PG8_MMA(0, 0, At, B0); PG8_MMA(0, 1, At, B1); PG8_BAR; PG8_SCHED;
;             PG8_LDA(At, 0, 1); PG8_STAGE(PG8_SB(0, 0), b2, voffB); PG8_STAGE(PG8_SB(0, 1), b2 + hstepB, voffB); PG8_STAGE(PG8_SA(0, 0), a2, voffA);
.LBB0_1018:
	v_add_u32_e32 v142, s46, v189
	v_add_u32_e32 v158, s47, v189
	s_add_u32 s40, s20, s22
	ds_read_b128 v[130:133], v142
	ds_read_b128 v[134:137], v142 offset:1024
	ds_read_b128 v[138:141], v142 offset:2048
	ds_read_b128 v[142:145], v142 offset:3072
	ds_read_b128 v[146:149], v158
	ds_read_b128 v[150:153], v158 offset:1024
	ds_read_b128 v[154:157], v158 offset:2048
	ds_read_b128 v[158:161], v158 offset:3072
	s_addc_u32 s41, s21, s23
	s_add_u32 s40, s40, 0x21500100
	s_addc_u32 s41, s41, 0
	s_add_u32 s87, s44, s22
	s_addc_u32 s88, s45, s23
	s_cmpk_eq_i32 s22, 0x5500
	s_cselect_b32 s43, s17, s41
	s_cselect_b32 s42, s16, s40
	s_cselect_b32 s41, s11, s88
	s_cselect_b32 s40, s10, s87
	s_mov_b32 m0, s77
	v_lshl_add_u64 v[186:187], v[0:1], 0, s[22:23]
	ds_read_b128 v[162:165], v180
	ds_read_b128 v[166:169], v180 offset:1024
	ds_read_b128 v[182:185], v180 offset:2048
	ds_read_b128 v[190:193], v180 offset:3072
	ds_read_b128 v[194:197], v180 offset:4096
	ds_read_b128 v[208:211], v180 offset:5120
	ds_read_b128 v[212:215], v180 offset:6144
	ds_read_b128 v[216:219], v180 offset:7168
	global_load_lds_dwordx4 v[186:187], off
	v_lshl_add_u64 v[186:187], v[170:171], 0, s[22:23]
	s_mov_b32 m0, s78
	s_nop 0
	global_load_lds_dwordx4 v[186:187], off
	s_waitcnt vmcnt(8)
	s_waitcnt lgkmcnt(0)
	s_barrier
	s_setprio 3
	v_mfma_f32_16x16x32_bf16 v[126:129], v[130:133], v[162:165], v[126:129]
	v_mfma_f32_16x16x32_bf16 v[126:129], v[134:137], v[166:169], v[126:129]
	v_mfma_f32_16x16x32_bf16 v[122:125], v[138:141], v[162:165], v[122:125]
	v_mfma_f32_16x16x32_bf16 v[122:125], v[142:145], v[166:169], v[122:125]
	v_mfma_f32_16x16x32_bf16 v[94:97], v[138:141], v[182:185], v[94:97]
	v_mfma_f32_16x16x32_bf16 v[94:97], v[142:145], v[190:193], v[94:97]
	v_mfma_f32_16x16x32_bf16 v[98:101], v[130:133], v[182:185], v[98:101]
	v_mfma_f32_16x16x32_bf16 v[98:101], v[134:137], v[190:193], v[98:101]
	v_mfma_f32_16x16x32_bf16 v[110:113], v[130:133], v[194:197], v[110:113]
	v_mfma_f32_16x16x32_bf16 v[110:113], v[134:137], v[208:211], v[110:113]
	v_mfma_f32_16x16x32_bf16 v[106:109], v[138:141], v[194:197], v[106:109]
	v_mfma_f32_16x16x32_bf16 v[106:109], v[142:145], v[208:211], v[106:109]
	v_mfma_f32_16x16x32_bf16 v[74:77], v[138:141], v[212:215], v[74:77]
	v_mfma_f32_16x16x32_bf16 v[74:77], v[142:145], v[216:219], v[74:77]
	v_mfma_f32_16x16x32_bf16 v[78:81], v[130:133], v[212:215], v[78:81]
	v_mfma_f32_16x16x32_bf16 v[78:81], v[134:137], v[216:219], v[78:81]
	v_mfma_f32_16x16x32_bf16 v[118:121], v[146:149], v[162:165], v[118:121]
	v_mfma_f32_16x16x32_bf16 v[118:121], v[150:153], v[166:169], v[118:121]
	v_mfma_f32_16x16x32_bf16 v[114:117], v[154:157], v[162:165], v[114:117]
	v_mfma_f32_16x16x32_bf16 v[114:117], v[158:161], v[166:169], v[114:117]
	v_mfma_f32_16x16x32_bf16 v[86:89], v[154:157], v[182:185], v[86:89]
	v_mfma_f32_16x16x32_bf16 v[86:89], v[158:161], v[190:193], v[86:89]
	v_mfma_f32_16x16x32_bf16 v[90:93], v[146:149], v[182:185], v[90:93]
	v_mfma_f32_16x16x32_bf16 v[90:93], v[150:153], v[190:193], v[90:93]
	v_mfma_f32_16x16x32_bf16 v[102:105], v[146:149], v[194:197], v[102:105]
	v_mfma_f32_16x16x32_bf16 v[102:105], v[150:153], v[208:211], v[102:105]
	v_mfma_f32_16x16x32_bf16 v[82:85], v[154:157], v[194:197], v[82:85]
	v_mfma_f32_16x16x32_bf16 v[82:85], v[158:161], v[208:211], v[82:85]
	v_mfma_f32_16x16x32_bf16 v[66:69], v[154:157], v[212:215], v[66:69]
	v_mfma_f32_16x16x32_bf16 v[66:69], v[158:161], v[216:219], v[66:69]
	v_mfma_f32_16x16x32_bf16 v[70:73], v[146:149], v[212:215], v[70:73]
	v_mfma_f32_16x16x32_bf16 v[70:73], v[150:153], v[216:219], v[70:73]
	s_barrier
	s_setprio 0
	s_mov_b32 m0, s79
	v_lshl_add_u64 v[186:187], s[40:41], 0, v[174:175]
	s_add_u32 s88, s40, 0x2b0000
	ds_read_b128 v[162:165], v180 offset:16384
	ds_read_b128 v[166:169], v180 offset:17408
	ds_read_b128 v[182:185], v180 offset:18432
	ds_read_b128 v[190:193], v180 offset:19456
	ds_read_b128 v[194:197], v180 offset:20480
	ds_read_b128 v[208:211], v180 offset:21504
	ds_read_b128 v[212:215], v180 offset:22528
	ds_read_b128 v[216:219], v180 offset:23552
	global_load_lds_dwordx4 v[186:187], off
	v_lshl_add_u64 v[198:199], s[40:41], 0, v[178:179]
	s_mov_b32 m0, s80
	s_addc_u32 s89, s41, 0
	global_load_lds_dwordx4 v[198:199], off
	v_lshl_add_u64 v[204:205], s[88:89], 0, v[174:175]
	s_mov_b32 m0, s81
	v_lshl_add_u64 v[220:221], s[42:43], 0, v[176:177]
	global_load_lds_dwordx4 v[204:205], off
	v_lshl_add_u64 v[204:205], s[88:89], 0, v[178:179]
	s_mov_b32 m0, s82
	s_nop 0
	global_load_lds_dwordx4 v[204:205], off
	v_lshl_add_u64 v[204:205], s[42:43], 0, v[172:173]
	s_mov_b32 m0, s58
	s_nop 0
	global_load_lds_dwordx4 v[204:205], off
	s_mov_b32 m0, s60
	s_nop 0
	global_load_lds_dwordx4 v[220:221], off
	s_waitcnt vmcnt(8)
	s_waitcnt lgkmcnt(0)
	s_barrier
; #define PG8_STAGE(bufoff, gbase, voff) do { _Pragma("unroll") for (int _i = 0; _i < 2; ++_i) \
;         __builtin_amdgcn_global_load_lds((const unsigned*)((const char*)(gbase) + (voff)[_i]), (PG8_LAS unsigned*)(lds + (bufoff) + ldsw + _i * 8192), 16, 0, 0); } while (0)
; #define PG8_LDA(dst, b, h) do { _Pragma("unroll") for (int m = 0; m < 4; ++m) _Pragma("unroll") for (int k = 0; k < 2; ++k) dst[m][k] = *(const PG8_LAS bf16x8*)(lds + PG8_SA(b, h) + aoff + m * 2048 + k * 1024); } while (0)
; #define PG8_LDB(dst, b, h) do { _Pragma("unroll") for (int n = 0; n < 2; ++n) _Pragma("unroll") for (int k = 0; k < 2; ++k) dst[n][k] = *(const PG8_LAS bf16x8*)(lds + PG8_SB(b, h) + boff + n * 2048 + k * 1024); } while (0)
; #define PG8_MMA(ai, bj, At, Bt) do { __builtin_amdgcn_s_setprio(3); _Pragma("unroll") for (int m = 0; m < 4; ++m) _Pragma("unroll") for (int n = 0; n < 2; ++n) _Pragma("unroll") for (int k = 0; k < 2; ++k) \
;         acc[ai][bj][m][n] = __builtin_amdgcn_mfma_f32_16x16x32_bf16(Bt[n][k], At[m][k], acc[ai][bj][m][n], 0, 0, 0); __builtin_amdgcn_s_setprio(0); } while (0)
; #define PG8_WAIT_V(n) asm volatile("s_waitcnt vmcnt(" #n ")" ::: "memory")
; #define PG8_WAIT_L(n) asm volatile("s_waitcnt lgkmcnt(" #n ")" ::: "memory")
; #define PG8_BAR __builtin_amdgcn_s_barrier()
; #define PG8_SCHED __builtin_amdgcn_sched_barrier(0)
; template <class Epi, class Sched, bool ALIGN_EPI = false, bool SP2 = false>
; __device__ __forceinline__ void gemm_phase(PG8_LAS unsigned char* lds, const Gemm g, const Sched& S, const Epi& E) {
;     ...
;             PG8_WAIT_V(8); PG8_WAIT_L(0); PG8_BAR; PG8_MMA(1, 0, At, B0); PG8_MMA(1, 1, At, B1); PG8_BAR; PG8_SCHED;
;             PG8_LDB(B0, 1, 0); PG8_LDB(B1, 1, 1); PG8_SCHED; PG8_LDA(At, 1, 0); PG8_STAGE(PG8_SA(0, 1), a2 + hstepA, voffA);
;             PG8_WAIT_V(8); PG8_WAIT_L(0); PG8_BAR; PG8_MMA(0, 0, At, B0); PG8_MMA(0, 1, At, B1); PG8_BAR; PG8_SCHED;
	s_setprio 3
	v_mfma_f32_16x16x32_bf16 v[62:65], v[130:133], v[162:165], v[62:65]
	v_mfma_f32_16x16x32_bf16 v[62:65], v[134:137], v[166:169], v[62:65]
	v_mfma_f32_16x16x32_bf16 v[58:61], v[138:141], v[162:165], v[58:61]
	v_mfma_f32_16x16x32_bf16 v[58:61], v[142:145], v[166:169], v[58:61]
	v_mfma_f32_16x16x32_bf16 v[42:45], v[138:141], v[182:185], v[42:45]
	v_mfma_f32_16x16x32_bf16 v[42:45], v[142:145], v[190:193], v[42:45]
	v_mfma_f32_16x16x32_bf16 v[46:49], v[130:133], v[182:185], v[46:49]
	v_mfma_f32_16x16x32_bf16 v[46:49], v[134:137], v[190:193], v[46:49]
	v_mfma_f32_16x16x32_bf16 v[30:33], v[130:133], v[194:197], v[30:33]
	v_mfma_f32_16x16x32_bf16 v[30:33], v[134:137], v[208:211], v[30:33]
	v_mfma_f32_16x16x32_bf16 v[26:29], v[138:141], v[194:197], v[26:29]
	v_mfma_f32_16x16x32_bf16 v[26:29], v[142:145], v[208:211], v[26:29]
	v_mfma_f32_16x16x32_bf16 v[10:13], v[138:141], v[212:215], v[10:13]
	v_mfma_f32_16x16x32_bf16 v[10:13], v[142:145], v[216:219], v[10:13]
	v_mfma_f32_16x16x32_bf16 v[14:17], v[130:133], v[212:215], v[14:17]
	v_mfma_f32_16x16x32_bf16 v[14:17], v[134:137], v[216:219], v[14:17]
	v_mfma_f32_16x16x32_bf16 v[54:57], v[146:149], v[162:165], v[54:57]
	v_mfma_f32_16x16x32_bf16 v[54:57], v[150:153], v[166:169], v[54:57]
	v_mfma_f32_16x16x32_bf16 v[50:53], v[154:157], v[162:165], v[50:53]
	v_mfma_f32_16x16x32_bf16 v[50:53], v[158:161], v[166:169], v[50:53]
	v_mfma_f32_16x16x32_bf16 v[34:37], v[154:157], v[182:185], v[34:37]
	v_mfma_f32_16x16x32_bf16 v[34:37], v[158:161], v[190:193], v[34:37]
	v_mfma_f32_16x16x32_bf16 v[38:41], v[146:149], v[182:185], v[38:41]
	v_mfma_f32_16x16x32_bf16 v[38:41], v[150:153], v[190:193], v[38:41]
	v_mfma_f32_16x16x32_bf16 v[22:25], v[146:149], v[194:197], v[22:25]
	v_mfma_f32_16x16x32_bf16 v[22:25], v[150:153], v[208:211], v[22:25]
	v_mfma_f32_16x16x32_bf16 v[18:21], v[154:157], v[194:197], v[18:21]
	v_mfma_f32_16x16x32_bf16 v[18:21], v[158:161], v[208:211], v[18:21]
	v_mfma_f32_16x16x32_bf16 v[2:5], v[154:157], v[212:215], v[2:5]
	v_mfma_f32_16x16x32_bf16 v[2:5], v[158:161], v[216:219], v[2:5]
	v_mfma_f32_16x16x32_bf16 v[6:9], v[146:149], v[212:215], v[6:9]
	v_mfma_f32_16x16x32_bf16 v[6:9], v[150:153], v[216:219], v[6:9]
	s_barrier
	s_setprio 0
	v_add_u32_e32 v142, s52, v189
	v_add_u32_e32 v158, s53, v189
	ds_read_b128 v[130:133], v142
	ds_read_b128 v[134:137], v142 offset:1024
	ds_read_b128 v[138:141], v142 offset:2048
	ds_read_b128 v[142:145], v142 offset:3072
	ds_read_b128 v[146:149], v158
	ds_read_b128 v[150:153], v158 offset:1024
	ds_read_b128 v[154:157], v158 offset:2048
	ds_read_b128 v[158:161], v158 offset:3072
	s_add_u32 s42, s42, 0x2b0000
	s_addc_u32 s43, s43, 0
	s_mov_b32 m0, s61
	v_lshl_add_u64 v[222:223], s[42:43], 0, v[172:173]
	ds_read_b128 v[162:165], v180 offset:32768
	ds_read_b128 v[166:169], v180 offset:33792
	ds_read_b128 v[182:185], v180 offset:34816
	ds_read_b128 v[190:193], v180 offset:35840
	ds_read_b128 v[194:197], v180 offset:36864
	ds_read_b128 v[208:211], v180 offset:37888
	ds_read_b128 v[212:215], v180 offset:38912
	ds_read_b128 v[216:219], v180 offset:39936
	global_load_lds_dwordx4 v[222:223], off
	v_lshl_add_u64 v[222:223], s[42:43], 0, v[176:177]
	s_mov_b32 m0, s62
	s_nop 0
	global_load_lds_dwordx4 v[222:223], off
	s_waitcnt vmcnt(8)
	s_waitcnt lgkmcnt(0)
	s_barrier
	s_setprio 3
	v_mfma_f32_16x16x32_bf16 v[126:129], v[130:133], v[162:165], v[126:129]
	v_mfma_f32_16x16x32_bf16 v[126:129], v[134:137], v[166:169], v[126:129]
	v_mfma_f32_16x16x32_bf16 v[122:125], v[138:141], v[162:165], v[122:125]
	v_mfma_f32_16x16x32_bf16 v[122:125], v[142:145], v[166:169], v[122:125]
	v_mfma_f32_16x16x32_bf16 v[94:97], v[138:141], v[182:185], v[94:97]
	v_mfma_f32_16x16x32_bf16 v[94:97], v[142:145], v[190:193], v[94:97]
	v_mfma_f32_16x16x32_bf16 v[98:101], v[130:133], v[182:185], v[98:101]
	v_mfma_f32_16x16x32_bf16 v[98:101], v[134:137], v[190:193], v[98:101]
	v_mfma_f32_16x16x32_bf16 v[110:113], v[130:133], v[194:197], v[110:113]
	v_mfma_f32_16x16x32_bf16 v[110:113], v[134:137], v[208:211], v[110:113]
	v_mfma_f32_16x16x32_bf16 v[106:109], v[138:141], v[194:197], v[106:109]
	v_mfma_f32_16x16x32_bf16 v[106:109], v[142:145], v[208:211], v[106:109]
	v_mfma_f32_16x16x32_bf16 v[74:77], v[138:141], v[212:215], v[74:77]
	v_mfma_f32_16x16x32_bf16 v[74:77], v[142:145], v[216:219], v[74:77]
	v_mfma_f32_16x16x32_bf16 v[78:81], v[130:133], v[212:215], v[78:81]
	v_mfma_f32_16x16x32_bf16 v[78:81], v[134:137], v[216:219], v[78:81]
	v_mfma_f32_16x16x32_bf16 v[118:121], v[146:149], v[162:165], v[118:121]
	v_mfma_f32_16x16x32_bf16 v[118:121], v[150:153], v[166:169], v[118:121]
	v_mfma_f32_16x16x32_bf16 v[114:117], v[154:157], v[162:165], v[114:117]
	v_mfma_f32_16x16x32_bf16 v[114:117], v[158:161], v[166:169], v[114:117]
	v_mfma_f32_16x16x32_bf16 v[86:89], v[154:157], v[182:185], v[86:89]
	v_mfma_f32_16x16x32_bf16 v[86:89], v[158:161], v[190:193], v[86:89]
	v_mfma_f32_16x16x32_bf16 v[90:93], v[146:149], v[182:185], v[90:93]
	v_mfma_f32_16x16x32_bf16 v[90:93], v[150:153], v[190:193], v[90:93]
	v_mfma_f32_16x16x32_bf16 v[102:105], v[146:149], v[194:197], v[102:105]
	v_mfma_f32_16x16x32_bf16 v[102:105], v[150:153], v[208:211], v[102:105]
	v_mfma_f32_16x16x32_bf16 v[82:85], v[154:157], v[194:197], v[82:85]
	v_mfma_f32_16x16x32_bf16 v[82:85], v[158:161], v[208:211], v[82:85]
	v_mfma_f32_16x16x32_bf16 v[66:69], v[154:157], v[212:215], v[66:69]
	v_mfma_f32_16x16x32_bf16 v[66:69], v[158:161], v[216:219], v[66:69]
	v_mfma_f32_16x16x32_bf16 v[70:73], v[146:149], v[212:215], v[70:73]
	v_mfma_f32_16x16x32_bf16 v[70:73], v[150:153], v[216:219], v[70:73]
	s_barrier
; #define PG8_STAGE(bufoff, gbase, voff) do { _Pragma("unroll") for (int _i = 0; _i < 2; ++_i) \
;         __builtin_amdgcn_global_load_lds((const unsigned*)((const char*)(gbase) + (voff)[_i]), (PG8_LAS unsigned*)(lds + (bufoff) + ldsw + _i * 8192), 16, 0, 0); } while (0)
; #define PG8_LDA(dst, b, h) do { _Pragma("unroll") for (int m = 0; m < 4; ++m) _Pragma("unroll") for (int k = 0; k < 2; ++k) dst[m][k] = *(const PG8_LAS bf16x8*)(lds + PG8_SA(b, h) + aoff + m * 2048 + k * 1024); } while (0)
; #define PG8_MMA(ai, bj, At, Bt) do { __builtin_amdgcn_s_setprio(3); _Pragma("unroll") for (int m = 0; m < 4; ++m) _Pragma("unroll") for (int n = 0; n < 2; ++n) _Pragma("unroll") for (int k = 0; k < 2; ++k) \
;         acc[ai][bj][m][n] = __builtin_amdgcn_mfma_f32_16x16x32_bf16(Bt[n][k], At[m][k], acc[ai][bj][m][n], 0, 0, 0); __builtin_amdgcn_s_setprio(0); } while (0)
; #define PG8_WAIT_V(n) asm volatile("s_waitcnt vmcnt(" #n ")" ::: "memory")
; #define PG8_WAIT_L(n) asm volatile("s_waitcnt lgkmcnt(" #n ")" ::: "memory")
; #define PG8_BAR __builtin_amdgcn_s_barrier()
; #define PG8_SCHED __builtin_amdgcn_sched_barrier(0)
; template <class Epi, class Sched, bool ALIGN_EPI = false, bool SP2 = false>
; __device__ __forceinline__ void gemm_phase(PG8_LAS unsigned char* lds, const Gemm g, const Sched& S, const Epi& E) {
;     ...
;         for (int t = 0; t < nt; t += 2) {
;     ...
;             PG8_LDA(At, 1, 1); PG8_STAGE(PG8_SB(1, 0), b3, voffB); PG8_STAGE(PG8_SB(1, 1), b3 + hstepB, voffB); PG8_STAGE(PG8_SA(1, 0), a3, voffA);
;             PG8_WAIT_V(8); PG8_WAIT_L(0); PG8_BAR; PG8_MMA(1, 0, At, B0); PG8_MMA(1, 1, At, B1); PG8_BAR; PG8_SCHED;
	s_setprio 0
	s_mov_b32 m0, s83
	v_lshl_add_u64 v[186:187], v[186:187], 0, s[18:19]
	s_add_u32 s40, s40, 0x2b0080
	ds_read_b128 v[162:165], v180 offset:49152
	ds_read_b128 v[166:169], v180 offset:50176
	ds_read_b128 v[182:185], v180 offset:51200
	ds_read_b128 v[190:193], v180 offset:52224
	ds_read_b128 v[194:197], v180 offset:53248
	ds_read_b128 v[208:211], v180 offset:54272
	ds_read_b128 v[212:215], v180 offset:55296
	ds_read_b128 v[216:219], v180 offset:56320
	global_load_lds_dwordx4 v[186:187], off
	v_lshl_add_u64 v[186:187], v[198:199], 0, s[18:19]
	s_mov_b32 m0, s84
	s_addc_u32 s41, s41, 0
	global_load_lds_dwordx4 v[186:187], off
	v_lshl_add_u64 v[186:187], s[40:41], 0, v[174:175]
	s_mov_b32 m0, s85
	s_nop 0
	global_load_lds_dwordx4 v[186:187], off
	v_lshl_add_u64 v[186:187], s[40:41], 0, v[178:179]
	s_mov_b32 m0, s86
	s_nop 0
	global_load_lds_dwordx4 v[186:187], off
	v_lshl_add_u64 v[186:187], v[204:205], 0, s[18:19]
	s_mov_b32 m0, s63
	s_nop 0
	global_load_lds_dwordx4 v[186:187], off
	v_lshl_add_u64 v[186:187], v[220:221], 0, s[18:19]
	s_mov_b32 m0, s64
	s_nop 0
	global_load_lds_dwordx4 v[186:187], off
	s_waitcnt vmcnt(8)
	s_waitcnt lgkmcnt(0)
	s_barrier
	s_setprio 3
	v_mfma_f32_16x16x32_bf16 v[62:65], v[130:133], v[162:165], v[62:65]
	v_mfma_f32_16x16x32_bf16 v[62:65], v[134:137], v[166:169], v[62:65]
	v_mfma_f32_16x16x32_bf16 v[58:61], v[138:141], v[162:165], v[58:61]
	v_mfma_f32_16x16x32_bf16 v[58:61], v[142:145], v[166:169], v[58:61]
	v_mfma_f32_16x16x32_bf16 v[42:45], v[138:141], v[182:185], v[42:45]
	v_mfma_f32_16x16x32_bf16 v[42:45], v[142:145], v[190:193], v[42:45]
	v_mfma_f32_16x16x32_bf16 v[46:49], v[130:133], v[182:185], v[46:49]
	v_mfma_f32_16x16x32_bf16 v[46:49], v[134:137], v[190:193], v[46:49]
	v_mfma_f32_16x16x32_bf16 v[30:33], v[130:133], v[194:197], v[30:33]
	v_mfma_f32_16x16x32_bf16 v[30:33], v[134:137], v[208:211], v[30:33]
	v_mfma_f32_16x16x32_bf16 v[26:29], v[138:141], v[194:197], v[26:29]
	v_mfma_f32_16x16x32_bf16 v[26:29], v[142:145], v[208:211], v[26:29]
	v_mfma_f32_16x16x32_bf16 v[10:13], v[138:141], v[212:215], v[10:13]
	v_mfma_f32_16x16x32_bf16 v[10:13], v[142:145], v[216:219], v[10:13]
	v_mfma_f32_16x16x32_bf16 v[14:17], v[130:133], v[212:215], v[14:17]
	v_mfma_f32_16x16x32_bf16 v[14:17], v[134:137], v[216:219], v[14:17]
	v_mfma_f32_16x16x32_bf16 v[54:57], v[146:149], v[162:165], v[54:57]
	v_mfma_f32_16x16x32_bf16 v[54:57], v[150:153], v[166:169], v[54:57]
	v_mfma_f32_16x16x32_bf16 v[50:53], v[154:157], v[162:165], v[50:53]
	v_mfma_f32_16x16x32_bf16 v[50:53], v[158:161], v[166:169], v[50:53]
	v_mfma_f32_16x16x32_bf16 v[34:37], v[154:157], v[182:185], v[34:37]
	v_mfma_f32_16x16x32_bf16 v[34:37], v[158:161], v[190:193], v[34:37]
	v_mfma_f32_16x16x32_bf16 v[38:41], v[146:149], v[182:185], v[38:41]
	v_mfma_f32_16x16x32_bf16 v[38:41], v[150:153], v[190:193], v[38:41]
	v_mfma_f32_16x16x32_bf16 v[22:25], v[146:149], v[194:197], v[22:25]
	v_mfma_f32_16x16x32_bf16 v[22:25], v[150:153], v[208:211], v[22:25]
	v_mfma_f32_16x16x32_bf16 v[18:21], v[154:157], v[194:197], v[18:21]
	v_mfma_f32_16x16x32_bf16 v[18:21], v[158:161], v[208:211], v[18:21]
	v_mfma_f32_16x16x32_bf16 v[2:5], v[154:157], v[212:215], v[2:5]
	v_mfma_f32_16x16x32_bf16 v[2:5], v[158:161], v[216:219], v[2:5]
	v_mfma_f32_16x16x32_bf16 v[6:9], v[146:149], v[212:215], v[6:9]
	v_mfma_f32_16x16x32_bf16 v[6:9], v[150:153], v[216:219], v[6:9]
	s_barrier
	s_setprio 0
	s_add_i32 s67, s67, 2
	s_add_u32 s22, s22, 0x100
	s_addc_u32 s23, s23, 0
	s_cmpk_gt_u32 s67, 0xa9
	s_cbranch_scc1 .LBB0_1021
